# speedup vs baseline: 1.0383x; 1.0142x over previous
; __device__ __forceinline__ int crow(int r, int hi) { return (r & 3) + 8 * (r >> 2) + 4 * hi; }
; __device__ __forceinline__ void attn_fused(const Params& p, int layer, float lam, float lam_init, int q0, int tok0, int h, int seq, char* lds) {
;     ...
;   if (hi == 0) { li0[r32] = l0; li1[r32] = l1; } asm volatile("s_waitcnt lgkmcnt(0)" ::: "memory");
;   float ss[16];
; #pragma unroll
;   for (int r = 0; r < 16; ++r) { const float ra = __builtin_amdgcn_rcpf(li0[crow(r, hi)]), rb = lam * __builtin_amdgcn_rcpf(li1[crow(r, hi)]); float s = 0.f;
; #pragma unroll
;     for (int d = 0; d < 4; ++d) { const float v = oa[d][r] * ra - ob[d][r] * rb; oa[d][r] = v; s = fmaf(v, v, s); }
;     ss[r] = s; }
.LBB0_115:
	s_or_b64 exec, exec, s[48:49]
	s_waitcnt lgkmcnt(0)
	v_lshl_add_u32 v134, v205, 4, s34
	ds_read_b128 v[136:139], v134 offset:128
	ds_read_b128 v[128:131], v134 offset:160
	ds_read_b128 v[140:143], v134 offset:256
	v_mov_b32_e32 v146, v96
	v_mov_b32_e32 v147, v64
	s_waitcnt lgkmcnt(2)
	v_rcp_f32_e32 v144, v136
	v_rcp_f32_e32 v136, v137
	s_waitcnt lgkmcnt(0)
	v_rcp_f32_e32 v132, v140
	v_mov_b32_e32 v64, v97
	s_mov_b32 s2, 0x358637bd
	v_readlane_b32 s12, v254, 55
	v_mul_f32_e32 v145, v202, v132
	v_mul_f32_e32 v0, v0, v145
	v_fma_f32 v112, v112, v144, -v0
	v_rcp_f32_e32 v0, v141
	v_pk_mul_f32 v[146:147], v[146:147], v[144:145]
	v_fma_f32 v132, v112, v112, 0
	v_sub_f32_e32 v96, v146, v147
	v_mul_f32_e32 v137, v202, v0
	v_mov_b32_e32 v146, v80
	v_mov_b32_e32 v147, v32
	v_mul_f32_e32 v0, v1, v137
	v_pk_mul_f32 v[146:147], v[146:147], v[144:145]
	v_fma_f32 v113, v113, v136, -v0
	v_pk_mul_f32 v[0:1], v[64:65], v[136:137]
	v_mov_b32_e32 v32, v81
	v_sub_f32_e32 v80, v146, v147
	v_mov_b32_e32 v147, v16
	v_sub_f32_e32 v97, v0, v1
	v_pk_mul_f32 v[0:1], v[32:33], v[136:137]
	v_mov_b32_e32 v16, v49
	v_sub_f32_e32 v64, v0, v1
	v_pk_mul_f32 v[0:1], v[16:17], v[136:137]
	v_mov_b32_e32 v16, v98
	v_sub_f32_e32 v49, v0, v1
	v_rcp_f32_e32 v1, v142
	v_rcp_f32_e32 v0, v138
	v_mov_b32_e32 v17, v66
	v_mov_b32_e32 v66, v99
	v_mul_f32_e32 v1, v202, v1
	v_pk_mul_f32 v[16:17], v[16:17], v[0:1]
	v_mul_f32_e32 v2, v2, v1
	v_sub_f32_e32 v81, v16, v17
	v_mov_b32_e32 v16, v82
	v_mov_b32_e32 v17, v34
	v_pk_mul_f32 v[16:17], v[16:17], v[0:1]
	v_fma_f32 v32, v114, v0, -v2
	v_sub_f32_e32 v65, v16, v17
	v_mov_b32_e32 v16, v50
	v_mov_b32_e32 v17, v18
	v_pk_mul_f32 v[0:1], v[16:17], v[0:1]
	v_mov_b32_e32 v34, v83
	v_sub_f32_e32 v50, v0, v1
	v_rcp_f32_e32 v1, v143
	v_rcp_f32_e32 v0, v139
	v_mov_b32_e32 v18, v51
	v_rcp_f32_e32 v16, v128
	v_mul_f32_e32 v1, v202, v1
	v_mul_f32_e32 v2, v3, v1
	v_fma_f32 v33, v115, v0, -v2
	v_pk_mul_f32 v[2:3], v[66:67], v[0:1]
	v_mov_b32_e32 v136, v84
	v_sub_f32_e32 v66, v2, v3
	v_pk_mul_f32 v[2:3], v[34:35], v[0:1]
	v_pk_mul_f32 v[0:1], v[18:19], v[0:1]
	v_sub_f32_e32 v35, v2, v3
	v_sub_f32_e32 v34, v0, v1
	ds_read_b128 v[0:3], v134 offset:288
	v_mov_b32_e32 v137, v36
	v_mov_b32_e32 v82, v100
	v_mov_b32_e32 v83, v68
	v_mov_b32_e32 v68, v101
	s_waitcnt lgkmcnt(0)
	v_rcp_f32_e32 v0, v0
	v_rcp_f32_e32 v1, v1
	v_mov_b32_e32 v36, v85
	v_mov_b32_e32 v84, v104
	v_mul_f32_e32 v17, v202, v0
	v_mul_f32_e32 v0, v4, v17
	v_fma_f32 v18, v116, v16, -v0
	v_rcp_f32_e32 v0, v129
	v_pk_mul_f32 v[136:137], v[136:137], v[16:17]
	v_mul_f32_e32 v1, v202, v1
	v_sub_f32_e32 v67, v136, v137
	v_mov_b32_e32 v136, v52
	v_mov_b32_e32 v137, v20
	v_pk_mul_f32 v[82:83], v[82:83], v[16:17]
	v_pk_mul_f32 v[16:17], v[136:137], v[16:17]
	v_mul_f32_e32 v4, v5, v1
	v_sub_f32_e32 v51, v16, v17
	v_fma_f32 v16, v117, v0, -v4
	v_pk_mul_f32 v[4:5], v[68:69], v[0:1]
	v_mov_b32_e32 v20, v53
	v_sub_f32_e32 v68, v4, v5
	v_pk_mul_f32 v[4:5], v[36:37], v[0:1]
	v_pk_mul_f32 v[0:1], v[20:21], v[0:1]
	v_sub_f32_e32 v52, v4, v5
	v_sub_f32_e32 v36, v0, v1
	v_rcp_f32_e32 v1, v2
	v_rcp_f32_e32 v0, v130
	v_mov_b32_e32 v4, v102
	v_mov_b32_e32 v5, v70
	v_mul_f32_e32 v1, v202, v1
	v_pk_mul_f32 v[4:5], v[4:5], v[0:1]
	v_mul_f32_e32 v2, v6, v1
	v_sub_f32_e32 v69, v4, v5
	v_mov_b32_e32 v4, v86
	v_mov_b32_e32 v5, v38
	v_pk_mul_f32 v[4:5], v[4:5], v[0:1]
	v_fma_f32 v17, v118, v0, -v2
	v_sub_f32_e32 v53, v4, v5
	v_mov_b32_e32 v4, v54
	v_mov_b32_e32 v5, v22
	v_pk_mul_f32 v[0:1], v[4:5], v[0:1]
	v_mov_b32_e32 v70, v103
	v_sub_f32_e32 v37, v0, v1
	v_rcp_f32_e32 v1, v3
	v_rcp_f32_e32 v0, v131
	v_mov_b32_e32 v38, v87
	v_mov_b32_e32 v22, v55
	v_mul_f32_e32 v1, v202, v1
	v_mul_f32_e32 v2, v7, v1
	v_fma_f32 v19, v119, v0, -v2
	v_pk_mul_f32 v[2:3], v[70:71], v[0:1]
	ds_read_b128 v[4:7], v134 offset:320
	v_sub_f32_e32 v70, v2, v3
	v_pk_mul_f32 v[2:3], v[38:39], v[0:1]
	v_pk_mul_f32 v[0:1], v[22:23], v[0:1]
	v_sub_f32_e32 v54, v2, v3
	v_sub_f32_e32 v38, v0, v1
	ds_read_b128 v[0:3], v134 offset:192
	v_mov_b32_e32 v85, v72
	v_mov_b32_e32 v72, v105
	v_sub_f32_e32 v82, v82, v83
	v_mov_b32_e32 v146, v48
	s_waitcnt lgkmcnt(0)
	v_rcp_f32_e32 v22, v0
	v_rcp_f32_e32 v0, v4
	v_fmac_f32_e32 v132, v96, v96
	v_pk_mul_f32 v[144:145], v[146:147], v[144:145]
	v_fmac_f32_e32 v132, v80, v80
	v_mul_f32_e32 v23, v202, v0
	v_mul_f32_e32 v0, v8, v23
	v_fma_f32 v20, v120, v22, -v0
	v_rcp_f32_e32 v0, v1
	v_rcp_f32_e32 v1, v5
	v_pk_mul_f32 v[84:85], v[84:85], v[22:23]
	v_sub_f32_e32 v48, v144, v145
	v_sub_f32_e32 v71, v84, v85
	v_mov_b32_e32 v84, v88
	v_mov_b32_e32 v85, v40
	v_pk_mul_f32 v[84:85], v[84:85], v[22:23]
	v_mul_f32_e32 v1, v202, v1
	v_sub_f32_e32 v55, v84, v85
	v_mov_b32_e32 v84, v56
	v_mov_b32_e32 v85, v24
	v_pk_mul_f32 v[22:23], v[84:85], v[22:23]
	v_mul_f32_e32 v4, v9, v1
	v_sub_f32_e32 v39, v22, v23
	v_fma_f32 v22, v121, v0, -v4
	v_pk_mul_f32 v[4:5], v[72:73], v[0:1]
	v_mov_b32_e32 v40, v89
	v_mov_b32_e32 v24, v57
	v_sub_f32_e32 v72, v4, v5
	v_pk_mul_f32 v[4:5], v[40:41], v[0:1]
	v_pk_mul_f32 v[0:1], v[24:25], v[0:1]
	v_sub_f32_e32 v56, v4, v5
	v_sub_f32_e32 v40, v0, v1
	v_rcp_f32_e32 v1, v6
	v_rcp_f32_e32 v0, v2
	v_mov_b32_e32 v4, v106
	v_mov_b32_e32 v5, v74
	v_mul_f32_e32 v1, v202, v1
	v_pk_mul_f32 v[4:5], v[4:5], v[0:1]
	v_mul_f32_e32 v2, v10, v1
	v_sub_f32_e32 v73, v4, v5
	v_mov_b32_e32 v4, v90
	v_mov_b32_e32 v5, v42
	v_pk_mul_f32 v[4:5], v[4:5], v[0:1]
	v_fma_f32 v23, v122, v0, -v2
	v_sub_f32_e32 v57, v4, v5
	v_mov_b32_e32 v4, v58
	v_mov_b32_e32 v5, v26
	v_pk_mul_f32 v[0:1], v[4:5], v[0:1]
	v_mov_b32_e32 v74, v107
	v_sub_f32_e32 v41, v0, v1
	v_rcp_f32_e32 v1, v7
	v_rcp_f32_e32 v0, v3
	v_mov_b32_e32 v42, v91
	v_mov_b32_e32 v26, v59
	v_mul_f32_e32 v1, v202, v1
	v_mul_f32_e32 v2, v11, v1
	v_fma_f32 v83, v123, v0, -v2
	v_pk_mul_f32 v[2:3], v[74:75], v[0:1]
	ds_read_b128 v[4:7], v134 offset:352
	v_sub_f32_e32 v58, v2, v3
	v_pk_mul_f32 v[2:3], v[42:43], v[0:1]
	v_pk_mul_f32 v[0:1], v[26:27], v[0:1]
	v_sub_f32_e32 v43, v2, v3
	v_sub_f32_e32 v42, v0, v1
	ds_read_b128 v[0:3], v134 offset:224
	v_mov_b32_e32 v24, v108
	v_mov_b32_e32 v25, v76
	v_mov_b32_e32 v76, v109
	v_fmac_f32_e32 v132, v48, v48
	s_waitcnt lgkmcnt(0)
; __device__ __forceinline__ int crow(int r, int hi) { return (r & 3) + 8 * (r >> 2) + 4 * hi; }
; template <int CTRL> __device__ __forceinline__ float dpp_mov(float x) { return __int_as_float(__builtin_amdgcn_update_dpp(0, __float_as_int(x), CTRL, 0xf, 0xf, true)); }
; __device__ __forceinline__ void attn_fused(const Params& p, int layer, float lam, float lam_init, int q0, int tok0, int h, int seq, char* lds) {
;     ...
;   for (int r = 0; r < 16; ++r) { const float ra = __builtin_amdgcn_rcpf(li0[crow(r, hi)]), rb = lam * __builtin_amdgcn_rcpf(li1[crow(r, hi)]); float s = 0.f;
; #pragma unroll
;     for (int d = 0; d < 4; ++d) { const float v = oa[d][r] * ra - ob[d][r] * rb; oa[d][r] = v; s = fmaf(v, v, s); }
;     ss[r] = s; }
; #pragma unroll
;   for (int r = 0; r < 16; ++r) { float s = ss[r]; s += dpp_mov<0xB1>(s); s += dpp_mov<0x4E>(s); s += dpp_mov<0x141>(s); s += dpp_mov<0x140>(s);
;     { auto rr = __builtin_amdgcn_permlane16_swap(__float_as_uint(s), __float_as_uint(s), false, false); s = __uint_as_float(rr[0]) + __uint_as_float(rr[1]); }
;     ss[r] = rsqrtf(s * (1.f / 128.f) + EPS) * (1.f - lam_init); }
	v_rcp_f32_e32 v8, v0
	v_rcp_f32_e32 v0, v4
	v_fma_f32 v133, v113, v113, 0
	v_fmac_f32_e32 v133, v97, v97
	v_fmac_f32_e32 v133, v64, v64
	v_mul_f32_e32 v9, v202, v0
	v_mul_f32_e32 v0, v12, v9
	v_fma_f32 v26, v124, v8, -v0
	v_pk_mul_f32 v[24:25], v[24:25], v[8:9]
	v_rcp_f32_e32 v0, v1
	v_rcp_f32_e32 v1, v5
	v_sub_f32_e32 v75, v24, v25
	v_mov_b32_e32 v24, v92
	v_mov_b32_e32 v25, v44
	v_pk_mul_f32 v[24:25], v[24:25], v[8:9]
	v_mul_f32_e32 v1, v202, v1
	v_sub_f32_e32 v74, v24, v25
	v_mov_b32_e32 v24, v60
	v_mov_b32_e32 v25, v28
	v_pk_mul_f32 v[8:9], v[24:25], v[8:9]
	v_mul_f32_e32 v5, v13, v1
	v_sub_f32_e32 v59, v8, v9
	v_pk_mul_f32 v[8:9], v[76:77], v[0:1]
	v_mov_b32_e32 v44, v93
	v_mov_b32_e32 v28, v61
	v_fma_f32 v84, v125, v0, -v5
	v_sub_f32_e32 v76, v8, v9
	v_pk_mul_f32 v[8:9], v[44:45], v[0:1]
	v_pk_mul_f32 v[0:1], v[28:29], v[0:1]
	v_sub_f32_e32 v60, v8, v9
	v_sub_f32_e32 v44, v0, v1
	v_rcp_f32_e32 v1, v6
	v_rcp_f32_e32 v0, v2
	v_mov_b32_e32 v8, v110
	v_mov_b32_e32 v9, v78
	v_mul_f32_e32 v1, v202, v1
	v_pk_mul_f32 v[8:9], v[8:9], v[0:1]
	v_mul_f32_e32 v2, v14, v1
	v_sub_f32_e32 v77, v8, v9
	v_mov_b32_e32 v8, v94
	v_mov_b32_e32 v9, v46
	v_pk_mul_f32 v[8:9], v[8:9], v[0:1]
	v_fma_f32 v87, v126, v0, -v2
	v_sub_f32_e32 v61, v8, v9
	v_mov_b32_e32 v8, v62
	v_mov_b32_e32 v9, v30
	v_pk_mul_f32 v[0:1], v[8:9], v[0:1]
	v_mov_b32_e32 v78, v111
	v_sub_f32_e32 v45, v0, v1
	v_rcp_f32_e32 v1, v7
	v_rcp_f32_e32 v0, v3
	v_mov_b32_e32 v46, v95
	v_mov_b32_e32 v30, v63
	v_mul_f32_e32 v1, v202, v1
	v_mul_f32_e32 v2, v15, v1
	v_fma_f32 v89, v127, v0, -v2
	v_pk_mul_f32 v[2:3], v[78:79], v[0:1]
	v_fmac_f32_e32 v133, v49, v49
	v_sub_f32_e32 v78, v2, v3
	v_pk_mul_f32 v[2:3], v[46:47], v[0:1]
	v_pk_mul_f32 v[0:1], v[30:31], v[0:1]
	v_sub_f32_e32 v47, v2, v3
	v_sub_f32_e32 v46, v0, v1
	v_add_f32_dpp v0, v132, v132 quad_perm:[1,0,3,2] row_mask:0xf bank_mask:0xf bound_ctrl:1
	v_fma_f32 v114, v32, v32, 0
	v_fmac_f32_e32 v114, v81, v81
	v_add_f32_dpp v0, v0, v0 quad_perm:[2,3,0,1] row_mask:0xf bank_mask:0xf bound_ctrl:1
	v_fmac_f32_e32 v114, v65, v65
	v_fmac_f32_e32 v114, v50, v50
	v_add_f32_dpp v0, v0, v0 row_half_mirror row_mask:0xf bank_mask:0xf bound_ctrl:1
	v_fma_f32 v98, v33, v33, 0
	v_fmac_f32_e32 v98, v66, v66
	v_add_f32_dpp v1, v0, v0 row_mirror row_mask:0xf bank_mask:0xf bound_ctrl:1
	v_add_f32_dpp v0, v133, v133 quad_perm:[1,0,3,2] row_mask:0xf bank_mask:0xf bound_ctrl:1
	v_mov_b32_e32 v3, v1
	s_nop 1
	v_permlane16_swap_b32_e32 v1, v3
	v_add_f32_dpp v0, v0, v0 quad_perm:[2,3,0,1] row_mask:0xf bank_mask:0xf bound_ctrl:1
	v_fmac_f32_e32 v98, v35, v35
	v_fmac_f32_e32 v98, v34, v34
	v_add_f32_dpp v0, v0, v0 row_half_mirror row_mask:0xf bank_mask:0xf bound_ctrl:1
	v_fma_f32 v99, v18, v18, 0
	v_fmac_f32_e32 v99, v82, v82
	v_add_f32_dpp v0, v0, v0 row_mirror row_mask:0xf bank_mask:0xf bound_ctrl:1
	v_mov_b32_e32 v2, v0
	s_nop 1
	v_permlane16_swap_b32_e32 v0, v2
	v_pk_add_f32 v[2:3], v[0:1], v[2:3]
	v_mov_b64_e32 v[0:1], s[2:3]
	s_brev_b32 s2, 60
	v_pk_fma_f32 v[2:3], v[2:3], s[2:3], v[0:1] op_sel_hi:[1,0,0]
	v_fmac_f32_e32 v99, v67, v67
	v_mul_f32_e32 v5, 0x4b800000, v3
	v_cmp_gt_f32_e64 s[6:7], s65, v3
	v_cmp_gt_f32_e32 vcc, s65, v2
	v_fmac_f32_e32 v99, v51, v51
	v_cndmask_b32_e64 v3, v3, v5, s[6:7]
	v_rsq_f32_e32 v3, v3
	v_fma_f32 v100, v16, v16, 0
	v_fmac_f32_e32 v100, v68, v68
	v_fmac_f32_e32 v100, v52, v52
	v_mul_f32_e32 v5, 0x45800000, v3
	v_cndmask_b32_e64 v3, v3, v5, s[6:7]
	v_mul_f32_e32 v62, v203, v3
	v_mul_f32_e32 v3, 0x4b800000, v2
	v_cndmask_b32_e32 v2, v2, v3, vcc
	v_rsq_f32_e32 v2, v2
	v_fmac_f32_e32 v100, v36, v36
	v_fma_f32 v21, v17, v17, 0
	v_fmac_f32_e32 v21, v69, v69
	v_mul_f32_e32 v3, 0x45800000, v2
	v_cndmask_b32_e32 v2, v2, v3, vcc
	v_mul_f32_e32 v63, v203, v2
	v_fmac_f32_e32 v21, v53, v53
	v_add_f32_dpp v2, v114, v114 quad_perm:[1,0,3,2] row_mask:0xf bank_mask:0xf bound_ctrl:1
	v_fmac_f32_e32 v21, v37, v37
	v_fma_f32 v102, v19, v19, 0
	v_add_f32_dpp v2, v2, v2 quad_perm:[2,3,0,1] row_mask:0xf bank_mask:0xf bound_ctrl:1
	v_fmac_f32_e32 v102, v70, v70
	v_fmac_f32_e32 v102, v54, v54
	v_add_f32_dpp v2, v2, v2 row_half_mirror row_mask:0xf bank_mask:0xf bound_ctrl:1
	v_fmac_f32_e32 v102, v38, v38
	v_fma_f32 v101, v20, v20, 0
	v_add_f32_dpp v3, v2, v2 row_mirror row_mask:0xf bank_mask:0xf bound_ctrl:1
	v_add_f32_dpp v2, v98, v98 quad_perm:[1,0,3,2] row_mask:0xf bank_mask:0xf bound_ctrl:1
	v_mov_b32_e32 v7, v3
	s_nop 1
	v_permlane16_swap_b32_e32 v3, v7
	v_add_f32_dpp v2, v2, v2 quad_perm:[2,3,0,1] row_mask:0xf bank_mask:0xf bound_ctrl:1
	v_fmac_f32_e32 v101, v71, v71
	v_fmac_f32_e32 v101, v55, v55
	v_add_f32_dpp v2, v2, v2 row_half_mirror row_mask:0xf bank_mask:0xf bound_ctrl:1
	v_fmac_f32_e32 v101, v39, v39
	v_fma_f32 v103, v22, v22, 0
	v_add_f32_dpp v2, v2, v2 row_mirror row_mask:0xf bank_mask:0xf bound_ctrl:1
	v_mov_b32_e32 v6, v2
	s_nop 1
	v_permlane16_swap_b32_e32 v2, v6
	v_pk_add_f32 v[2:3], v[2:3], v[6:7]
	v_fmac_f32_e32 v103, v72, v72
	v_pk_fma_f32 v[2:3], v[2:3], s[2:3], v[0:1] op_sel_hi:[1,0,0]
	v_fmac_f32_e32 v103, v56, v56
	v_mul_f32_e32 v5, 0x4b800000, v3
	v_cmp_gt_f32_e64 s[6:7], s65, v3
	v_cmp_gt_f32_e32 vcc, s65, v2
	v_fmac_f32_e32 v103, v40, v40
	v_cndmask_b32_e64 v3, v3, v5, s[6:7]
	v_rsq_f32_e32 v3, v3
	v_fma_f32 v10, v23, v23, 0
	v_fmac_f32_e32 v10, v73, v73
	v_fmac_f32_e32 v10, v57, v57
	v_mul_f32_e32 v5, 0x45800000, v3
	v_cndmask_b32_e64 v3, v3, v5, s[6:7]
	v_mul_f32_e32 v79, v203, v3
	v_mul_f32_e32 v3, 0x4b800000, v2
	v_cndmask_b32_e32 v2, v2, v3, vcc
	v_rsq_f32_e32 v2, v2
	v_fmac_f32_e32 v10, v41, v41
	v_fma_f32 v11, v83, v83, 0
	v_fmac_f32_e32 v11, v58, v58
	v_mul_f32_e32 v3, 0x45800000, v2
	v_cndmask_b32_e32 v2, v2, v3, vcc
; template <int CTRL> __device__ __forceinline__ float dpp_mov(float x) { return __int_as_float(__builtin_amdgcn_update_dpp(0, __float_as_int(x), CTRL, 0xf, 0xf, true)); }
; __device__ __forceinline__ void attn_fused(const Params& p, int layer, float lam, float lam_init, int q0, int tok0, int h, int seq, char* lds) {
;     ...
; #pragma unroll
;   for (int r = 0; r < 16; ++r) { float s = ss[r]; s += dpp_mov<0xB1>(s); s += dpp_mov<0x4E>(s); s += dpp_mov<0x141>(s); s += dpp_mov<0x140>(s);
;     { auto rr = __builtin_amdgcn_permlane16_swap(__float_as_uint(s), __float_as_uint(s), false, false); s = __uint_as_float(rr[0]) + __uint_as_float(rr[1]); }
;     ss[r] = rsqrtf(s * (1.f / 128.f) + EPS) * (1.f - lam_init); }
	v_mul_f32_e32 v85, v203, v2
	v_fmac_f32_e32 v11, v43, v43
	v_add_f32_dpp v2, v99, v99 quad_perm:[1,0,3,2] row_mask:0xf bank_mask:0xf bound_ctrl:1
	v_fmac_f32_e32 v11, v42, v42
	v_fma_f32 v4, v26, v26, 0
	v_add_f32_dpp v2, v2, v2 quad_perm:[2,3,0,1] row_mask:0xf bank_mask:0xf bound_ctrl:1
	v_fmac_f32_e32 v4, v75, v75
	v_fmac_f32_e32 v4, v74, v74
	v_add_f32_dpp v2, v2, v2 row_half_mirror row_mask:0xf bank_mask:0xf bound_ctrl:1
	v_fmac_f32_e32 v4, v59, v59
	v_fma_f32 v12, v84, v84, 0
	v_add_f32_dpp v3, v2, v2 row_mirror row_mask:0xf bank_mask:0xf bound_ctrl:1
	v_add_f32_dpp v2, v100, v100 quad_perm:[1,0,3,2] row_mask:0xf bank_mask:0xf bound_ctrl:1
	v_mov_b32_e32 v7, v3
	s_nop 1
	v_permlane16_swap_b32_e32 v3, v7
	v_add_f32_dpp v2, v2, v2 quad_perm:[2,3,0,1] row_mask:0xf bank_mask:0xf bound_ctrl:1
	v_fmac_f32_e32 v12, v76, v76
	v_fmac_f32_e32 v12, v60, v60
	v_add_f32_dpp v2, v2, v2 row_half_mirror row_mask:0xf bank_mask:0xf bound_ctrl:1
	v_fmac_f32_e32 v12, v44, v44
	v_fma_f32 v13, v87, v87, 0
	v_add_f32_dpp v2, v2, v2 row_mirror row_mask:0xf bank_mask:0xf bound_ctrl:1
	v_mov_b32_e32 v6, v2
	s_nop 1
	v_permlane16_swap_b32_e32 v2, v6
	v_pk_add_f32 v[2:3], v[2:3], v[6:7]
	v_fmac_f32_e32 v13, v77, v77
	v_pk_fma_f32 v[2:3], v[2:3], s[2:3], v[0:1] op_sel_hi:[1,0,0]
	v_fmac_f32_e32 v13, v61, v61
	v_mul_f32_e32 v5, 0x4b800000, v3
	v_cmp_gt_f32_e64 s[6:7], s65, v3
	v_cmp_gt_f32_e32 vcc, s65, v2
	v_fmac_f32_e32 v13, v45, v45
	v_cndmask_b32_e64 v3, v3, v5, s[6:7]
	v_rsq_f32_e32 v3, v3
	v_fma_f32 v8, v89, v89, 0
	v_fmac_f32_e32 v8, v78, v78
	v_fmac_f32_e32 v8, v47, v47
	v_mul_f32_e32 v5, 0x45800000, v3
	v_cndmask_b32_e64 v3, v3, v5, s[6:7]
	v_mul_f32_e32 v86, v203, v3
	v_mul_f32_e32 v3, 0x4b800000, v2
	v_cndmask_b32_e32 v2, v2, v3, vcc
	v_rsq_f32_e32 v2, v2
	v_fmac_f32_e32 v8, v46, v46
	v_readlane_b32 s13, v254, 56
	s_lshl_b32 s60, s8, 1
	v_mul_f32_e32 v3, 0x45800000, v2
	v_cndmask_b32_e32 v2, v2, v3, vcc
	v_mul_f32_e32 v88, v203, v2
	v_lshlrev_b32_e32 v192, 1, v204
	v_add_f32_dpp v2, v21, v21 quad_perm:[1,0,3,2] row_mask:0xf bank_mask:0xf bound_ctrl:1
	v_mul_f32_e32 v81, v81, v79
	v_mul_f32_e32 v66, v66, v85
	v_add_f32_dpp v2, v2, v2 quad_perm:[2,3,0,1] row_mask:0xf bank_mask:0xf bound_ctrl:1
	v_mul_f32_e32 v64, v64, v63
	v_mul_f32_e32 v35, v35, v85
	v_add_f32_dpp v2, v2, v2 row_half_mirror row_mask:0xf bank_mask:0xf bound_ctrl:1
	v_mov_b32_e32 v237, v215
	v_mov_b32_e32 v238, v226
	v_add_f32_dpp v3, v2, v2 row_mirror row_mask:0xf bank_mask:0xf bound_ctrl:1
	v_add_f32_dpp v2, v102, v102 quad_perm:[1,0,3,2] row_mask:0xf bank_mask:0xf bound_ctrl:1
	v_mov_b32_e32 v7, v3
	s_nop 1
	v_permlane16_swap_b32_e32 v3, v7
	v_add_f32_dpp v2, v2, v2 quad_perm:[2,3,0,1] row_mask:0xf bank_mask:0xf bound_ctrl:1
	v_mov_b32_e32 v226, v221
	v_mov_b32_e32 v221, v220
	v_add_f32_dpp v2, v2, v2 row_half_mirror row_mask:0xf bank_mask:0xf bound_ctrl:1
	v_mov_b32_e32 v220, 0x3e38aa3b
	v_mov_b32_e32 v239, 0x1fef
	v_add_f32_dpp v2, v2, v2 row_mirror row_mask:0xf bank_mask:0xf bound_ctrl:1
	v_mov_b32_e32 v6, v2
	s_nop 1
	v_permlane16_swap_b32_e32 v2, v6
	v_pk_add_f32 v[2:3], v[2:3], v[6:7]
	v_mov_b32_e32 v240, 0xfff
	v_pk_fma_f32 v[2:3], v[2:3], s[2:3], v[0:1] op_sel_hi:[1,0,0]
	v_mov_b32_e32 v241, 0x1fff
	v_mul_f32_e32 v5, 0x4b800000, v3
	v_cmp_gt_f32_e64 s[6:7], s65, v3
	v_cmp_gt_f32_e32 vcc, s65, v2
	v_readlane_b32 s14, v254, 57
	v_cndmask_b32_e64 v3, v3, v5, s[6:7]
	v_rsq_f32_e32 v3, v3
	v_readlane_b32 s15, v254, 58
	v_readlane_b32 s16, v254, 59
	v_readlane_b32 s17, v254, 60
	v_mul_f32_e32 v5, 0x45800000, v3
	v_cndmask_b32_e64 v3, v3, v5, s[6:7]
	v_mul_f32_e32 v90, v203, v3
	v_mul_f32_e32 v3, 0x4b800000, v2
	v_cndmask_b32_e32 v2, v2, v3, vcc
	v_rsq_f32_e32 v2, v2
	v_readlane_b32 s18, v254, 61
	v_readlane_b32 s19, v254, 62
	v_readlane_b32 s20, v254, 63
	v_mul_f32_e32 v3, 0x45800000, v2
	v_cndmask_b32_e32 v2, v2, v3, vcc
	v_mul_f32_e32 v91, v203, v2
	v_readlane_b32 s21, v255, 0
	v_add_f32_dpp v2, v101, v101 quad_perm:[1,0,3,2] row_mask:0xf bank_mask:0xf bound_ctrl:1
	v_readlane_b32 s22, v255, 1
	v_readlane_b32 s23, v255, 2
	v_add_f32_dpp v2, v2, v2 quad_perm:[2,3,0,1] row_mask:0xf bank_mask:0xf bound_ctrl:1
	v_readlane_b32 s24, v255, 3
	v_readlane_b32 s25, v255, 4
	v_add_f32_dpp v2, v2, v2 row_half_mirror row_mask:0xf bank_mask:0xf bound_ctrl:1
	v_readlane_b32 s26, v255, 5
	v_readlane_b32 s27, v255, 6
	v_add_f32_dpp v3, v2, v2 row_mirror row_mask:0xf bank_mask:0xf bound_ctrl:1
	v_add_f32_dpp v2, v103, v103 quad_perm:[1,0,3,2] row_mask:0xf bank_mask:0xf bound_ctrl:1
	v_mov_b32_e32 v7, v3
	s_nop 1
	v_permlane16_swap_b32_e32 v3, v7
	v_add_f32_dpp v2, v2, v2 quad_perm:[2,3,0,1] row_mask:0xf bank_mask:0xf bound_ctrl:1
	s_nop 1
	v_add_f32_dpp v2, v2, v2 row_half_mirror row_mask:0xf bank_mask:0xf bound_ctrl:1
	s_nop 1
	v_add_f32_dpp v2, v2, v2 row_mirror row_mask:0xf bank_mask:0xf bound_ctrl:1
	v_mov_b32_e32 v6, v2
	s_nop 1
	v_permlane16_swap_b32_e32 v2, v6
	v_pk_add_f32 v[2:3], v[2:3], v[6:7]
	s_nop 0
	v_pk_fma_f32 v[2:3], v[2:3], s[2:3], v[0:1] op_sel_hi:[1,0,0]
	s_nop 0
	v_mul_f32_e32 v5, 0x4b800000, v3
	v_cmp_gt_f32_e64 s[6:7], s65, v3
	v_cmp_gt_f32_e32 vcc, s65, v2
	s_nop 0
	v_cndmask_b32_e64 v3, v3, v5, s[6:7]
	v_rsq_f32_e32 v3, v3
	s_nop 0
	v_mul_f32_e32 v5, 0x45800000, v3
	v_cndmask_b32_e64 v3, v3, v5, s[6:7]
	v_mul_f32_e32 v92, v203, v3
	v_mul_f32_e32 v3, 0x4b800000, v2
	v_cndmask_b32_e32 v2, v2, v3, vcc
	v_rsq_f32_e32 v2, v2
	s_nop 0
	v_mul_f32_e32 v3, 0x45800000, v2
	v_cndmask_b32_e32 v2, v2, v3, vcc
	v_mul_f32_e32 v93, v203, v2
	v_mul_f32_e32 v22, v22, v93
	v_add_f32_dpp v2, v10, v10 quad_perm:[1,0,3,2] row_mask:0xf bank_mask:0xf bound_ctrl:1
	s_nop 1
;   __device__ __forceinline__ bf16_t* MIX() const { return (bf16_t*)(ws + 776 * MB); }
; template <int CTRL> __device__ __forceinline__ float dpp_mov(float x) { return __int_as_float(__builtin_amdgcn_update_dpp(0, __float_as_int(x), CTRL, 0xf, 0xf, true)); }
; __device__ __forceinline__ void attn_fused(const Params& p, int layer, float lam, float lam_init, int q0, int tok0, int h, int seq, char* lds) {
;     ...
; #pragma unroll
;   for (int r = 0; r < 16; ++r) { float s = ss[r]; s += dpp_mov<0xB1>(s); s += dpp_mov<0x4E>(s); s += dpp_mov<0x141>(s); s += dpp_mov<0x140>(s);
;     { auto rr = __builtin_amdgcn_permlane16_swap(__float_as_uint(s), __float_as_uint(s), false, false); s = __uint_as_float(rr[0]) + __uint_as_float(rr[1]); }
;     ss[r] = rsqrtf(s * (1.f / 128.f) + EPS) * (1.f - lam_init); }
;   bf16_t* mp = p.MIX() + (size_t)(q0 + wid * 32 + 4 * hi) * DM + h * 128 + r32;
; #pragma unroll
;   for (int d = 0; d < 4; ++d) { const float sl = p.subln[layer * 128 + d * 32 + r32];
	v_add_f32_dpp v2, v2, v2 quad_perm:[2,3,0,1] row_mask:0xf bank_mask:0xf bound_ctrl:1
	s_nop 1
	v_add_f32_dpp v2, v2, v2 row_half_mirror row_mask:0xf bank_mask:0xf bound_ctrl:1
	s_nop 1
	v_add_f32_dpp v3, v2, v2 row_mirror row_mask:0xf bank_mask:0xf bound_ctrl:1
	v_add_f32_dpp v2, v11, v11 quad_perm:[1,0,3,2] row_mask:0xf bank_mask:0xf bound_ctrl:1
	v_mov_b32_e32 v7, v3
	s_nop 1
	v_permlane16_swap_b32_e32 v3, v7
	v_add_f32_dpp v2, v2, v2 quad_perm:[2,3,0,1] row_mask:0xf bank_mask:0xf bound_ctrl:1
	s_nop 1
	v_add_f32_dpp v2, v2, v2 row_half_mirror row_mask:0xf bank_mask:0xf bound_ctrl:1
	s_nop 1
	v_add_f32_dpp v2, v2, v2 row_mirror row_mask:0xf bank_mask:0xf bound_ctrl:1
	v_mov_b32_e32 v6, v2
	s_nop 1
	v_permlane16_swap_b32_e32 v2, v6
	v_pk_add_f32 v[2:3], v[2:3], v[6:7]
	s_nop 0
	v_pk_fma_f32 v[2:3], v[2:3], s[2:3], v[0:1] op_sel_hi:[1,0,0]
	s_nop 0
	v_mul_f32_e32 v5, 0x4b800000, v3
	v_cmp_gt_f32_e64 s[6:7], s65, v3
	v_cmp_gt_f32_e32 vcc, s65, v2
	s_nop 0
	v_cndmask_b32_e64 v3, v3, v5, s[6:7]
	v_rsq_f32_e32 v3, v3
	s_nop 0
	v_mul_f32_e32 v5, 0x45800000, v3
	v_cndmask_b32_e64 v3, v3, v5, s[6:7]
	v_mul_f32_e32 v94, v203, v3
	v_mul_f32_e32 v3, 0x4b800000, v2
	v_cndmask_b32_e32 v2, v2, v3, vcc
	v_rsq_f32_e32 v2, v2
	s_nop 0
	v_mul_f32_e32 v3, 0x45800000, v2
	v_cndmask_b32_e32 v2, v2, v3, vcc
	v_mul_f32_e32 v95, v203, v2
	v_mul_f32_e32 v58, v58, v95
	v_add_f32_dpp v2, v4, v4 quad_perm:[1,0,3,2] row_mask:0xf bank_mask:0xf bound_ctrl:1
	s_nop 1
	v_add_f32_dpp v2, v2, v2 quad_perm:[2,3,0,1] row_mask:0xf bank_mask:0xf bound_ctrl:1
	s_nop 1
	v_add_f32_dpp v2, v2, v2 row_half_mirror row_mask:0xf bank_mask:0xf bound_ctrl:1
	s_nop 1
	v_add_f32_dpp v3, v2, v2 row_mirror row_mask:0xf bank_mask:0xf bound_ctrl:1
	v_add_f32_dpp v2, v12, v12 quad_perm:[1,0,3,2] row_mask:0xf bank_mask:0xf bound_ctrl:1
	v_mov_b32_e32 v5, v3
	s_nop 1
	v_permlane16_swap_b32_e32 v3, v5
	v_add_f32_dpp v2, v2, v2 quad_perm:[2,3,0,1] row_mask:0xf bank_mask:0xf bound_ctrl:1
	s_nop 1
	v_add_f32_dpp v2, v2, v2 row_half_mirror row_mask:0xf bank_mask:0xf bound_ctrl:1
	s_nop 1
	v_add_f32_dpp v2, v2, v2 row_mirror row_mask:0xf bank_mask:0xf bound_ctrl:1
	v_mov_b32_e32 v4, v2
	s_nop 1
	v_permlane16_swap_b32_e32 v2, v4
	v_pk_add_f32 v[2:3], v[2:3], v[4:5]
	s_nop 0
	v_pk_fma_f32 v[2:3], v[2:3], s[2:3], v[0:1] op_sel_hi:[1,0,0]
	s_nop 0
	v_mul_f32_e32 v4, 0x4b800000, v3
	v_cmp_gt_f32_e64 s[6:7], s65, v3
	v_cmp_gt_f32_e32 vcc, s65, v2
	s_nop 0
	v_cndmask_b32_e64 v3, v3, v4, s[6:7]
	v_rsq_f32_e32 v3, v3
	s_nop 0
	v_mul_f32_e32 v4, 0x45800000, v3
	v_cndmask_b32_e64 v3, v3, v4, s[6:7]
	v_mul_f32_e32 v98, v203, v3
	v_mul_f32_e32 v3, 0x4b800000, v2
	v_cndmask_b32_e32 v2, v2, v3, vcc
	v_rsq_f32_e32 v2, v2
	v_mul_f32_e32 v26, v26, v98
	v_mul_f32_e32 v3, 0x45800000, v2
	v_cndmask_b32_e32 v2, v2, v3, vcc
	v_mul_f32_e32 v99, v203, v2
	s_nop 0
	v_add_f32_dpp v2, v13, v13 quad_perm:[1,0,3,2] row_mask:0xf bank_mask:0xf bound_ctrl:1
	s_nop 1
	v_add_f32_dpp v2, v2, v2 quad_perm:[2,3,0,1] row_mask:0xf bank_mask:0xf bound_ctrl:1
	s_nop 1
	v_add_f32_dpp v2, v2, v2 row_half_mirror row_mask:0xf bank_mask:0xf bound_ctrl:1
	s_nop 1
	v_add_f32_dpp v3, v2, v2 row_mirror row_mask:0xf bank_mask:0xf bound_ctrl:1
	v_add_f32_dpp v2, v8, v8 quad_perm:[1,0,3,2] row_mask:0xf bank_mask:0xf bound_ctrl:1
	v_mov_b32_e32 v5, v3
	s_nop 1
	v_permlane16_swap_b32_e32 v3, v5
	v_add_f32_dpp v2, v2, v2 quad_perm:[2,3,0,1] row_mask:0xf bank_mask:0xf bound_ctrl:1
	s_nop 1
	v_add_f32_dpp v2, v2, v2 row_half_mirror row_mask:0xf bank_mask:0xf bound_ctrl:1
	s_nop 1
	v_add_f32_dpp v2, v2, v2 row_mirror row_mask:0xf bank_mask:0xf bound_ctrl:1
	v_mov_b32_e32 v4, v2
	s_nop 1
	v_permlane16_swap_b32_e32 v2, v4
	v_pk_add_f32 v[2:3], v[2:3], v[4:5]
	v_mul_f32_e32 v4, v112, v62
	v_pk_fma_f32 v[0:1], v[2:3], s[2:3], v[0:1] op_sel_hi:[1,0,0]
	s_nop 0
	v_mul_f32_e32 v2, 0x4b800000, v1
	v_cmp_gt_f32_e64 s[6:7], s65, v1
	v_cmp_gt_f32_e32 vcc, s65, v0
	s_nop 0
	v_cndmask_b32_e64 v1, v1, v2, s[6:7]
	v_rsq_f32_e32 v1, v1
	s_nop 0
	v_mul_f32_e32 v2, 0x45800000, v1
	v_cndmask_b32_e64 v1, v1, v2, s[6:7]
	v_or_b32_e32 v2, s9, v204
	v_ashrrev_i32_e32 v3, 31, v2
	v_lshl_add_u64 v[2:3], v[2:3], 2, s[12:13]
	global_load_dword v102, v[2:3], off
	global_load_dword v148, v[2:3], off offset:128
	global_load_dword v149, v[2:3], off offset:256
	global_load_dword v150, v[2:3], off offset:384
	v_mul_f32_e32 v100, v203, v1
	v_mul_f32_e32 v1, 0x4b800000, v0
	v_cndmask_b32_e32 v0, v0, v1, vcc
	v_rsq_f32_e32 v0, v0
	s_waitcnt vmcnt(0)
;   __device__ __forceinline__ bf16_t* MIX() const { return (bf16_t*)(ws + 776 * MB); }
; __device__ __forceinline__ void attn_fused(const Params& p, int layer, float lam, float lam_init, int q0, int tok0, int h, int seq, char* lds) {
;     ...
;   bf16_t* mp = p.MIX() + (size_t)(q0 + wid * 32 + 4 * hi) * DM + h * 128 + r32;
; #pragma unroll
;   for (int d = 0; d < 4; ++d) { const float sl = p.subln[layer * 128 + d * 32 + r32];
; #pragma unroll
;     for (int r = 0; r < 16; ++r) { const float y = oa[d][r] * ss[r] * sl;
;       mp[(size_t)((r & 3) + 8 * (r >> 2)) * DM + d * 32] = (bf16_t)(cvtpk(y, 0.f) & 0xffffu); } }
	v_mul_f32_e32 v4, v4, v102
	v_mul_f32_e32 v1, 0x45800000, v0
	v_cndmask_b32_e32 v0, v0, v1, vcc
	v_mul_f32_e32 v101, v203, v0
	v_lshl_add_u32 v0, v205, 2, s1
	v_ashrrev_i32_e32 v1, 31, v0
	v_lshlrev_b64 v[0:1], 12, v[0:1]
	v_lshl_add_u64 v[0:1], s[44:45], 0, v[0:1]
	v_lshl_add_u64 v[0:1], v[0:1], 0, s[60:61]
	v_lshl_add_u64 v[0:1], v[0:1], 0, v[192:193]
	v_cvt_pk_bf16_f32 v4, v4, v193
	global_store_short v[0:1], v4, off
	v_mul_f32_e32 v4, v113, v63
	v_mul_f32_e32 v4, v4, v102
	v_cvt_pk_bf16_f32 v8, v4, v193
	v_add_co_u32_e32 v4, vcc, s3, v0
	s_movk_i32 s1, 0x2000
	s_nop 0
	v_addc_co_u32_e32 v5, vcc, 0, v1, vcc
	v_add_co_u32_e32 v6, vcc, s1, v0
	s_movk_i32 s1, 0x3000
	s_nop 0
	v_addc_co_u32_e32 v7, vcc, 0, v1, vcc
	global_store_short v[6:7], v8, off offset:-4096
	v_mul_f32_e32 v8, v32, v79
	v_mul_f32_e32 v8, v8, v102
	v_cvt_pk_bf16_f32 v8, v8, v193
	global_store_short v[6:7], v8, off
	v_mul_f32_e32 v8, v33, v85
	v_mul_f32_e32 v8, v8, v102
	v_cvt_pk_bf16_f32 v10, v8, v193
	v_add_co_u32_e32 v8, vcc, s1, v0
	s_mov_b32 s1, 0x9000
	s_nop 0
	v_addc_co_u32_e32 v9, vcc, 0, v1, vcc
	global_store_short v[8:9], v10, off
	v_mul_f32_e32 v10, v18, v86
	v_mul_f32_e32 v10, v10, v102
	v_cvt_pk_bf16_f32 v14, v10, v193
	v_add_co_u32_e32 v10, vcc, s88, v0
	v_mul_f32_e32 v22, v22, v102
	s_nop 0
	v_addc_co_u32_e32 v11, vcc, 0, v1, vcc
	v_add_co_u32_e32 v12, vcc, s1, v0
	s_mov_b32 s1, 0xa000
	s_nop 0
	v_addc_co_u32_e32 v13, vcc, 0, v1, vcc
	global_store_short v[12:13], v14, off offset:-4096
	v_mul_f32_e32 v14, v16, v88
	v_mul_f32_e32 v14, v14, v102
	v_cvt_pk_bf16_f32 v14, v14, v193
	global_store_short v[12:13], v14, off
	v_mul_f32_e32 v14, v17, v90
	v_mul_f32_e32 v14, v14, v102
	v_cvt_pk_bf16_f32 v18, v14, v193
	v_add_co_u32_e32 v14, vcc, s1, v0
	s_mov_b32 s1, 0xb000
	s_nop 0
	v_addc_co_u32_e32 v15, vcc, 0, v1, vcc
	v_add_co_u32_e32 v16, vcc, s1, v0
	s_mov_b32 s1, 0x11000
	s_nop 0
	v_addc_co_u32_e32 v17, vcc, 0, v1, vcc
	global_store_short v[16:17], v18, off offset:-4096
	v_mul_f32_e32 v18, v19, v91
	v_mul_f32_e32 v18, v18, v102
	v_cvt_pk_bf16_f32 v18, v18, v193
	global_store_short v[16:17], v18, off
	v_mul_f32_e32 v18, v20, v92
	v_mul_f32_e32 v18, v18, v102
	v_cvt_pk_bf16_f32 v24, v18, v193
	v_add_co_u32_e32 v18, vcc, s81, v0
	v_mul_f32_e32 v26, v26, v102
	s_nop 0
	v_addc_co_u32_e32 v19, vcc, 0, v1, vcc
	v_add_co_u32_e32 v20, vcc, s1, v0
	s_mov_b32 s1, 0x12000
	s_nop 0
	v_addc_co_u32_e32 v21, vcc, 0, v1, vcc
	global_store_short v[20:21], v24, off offset:-4096
	v_cvt_pk_bf16_f32 v22, v22, v193
	global_store_short v[20:21], v22, off
	v_mul_f32_e32 v22, v23, v94
	v_mul_f32_e32 v22, v22, v102
	v_cvt_pk_bf16_f32 v27, v22, v193
	v_add_co_u32_e32 v22, vcc, s1, v0
	s_mov_b32 s1, 0x13000
	s_nop 0
	v_addc_co_u32_e32 v23, vcc, 0, v1, vcc
	v_add_co_u32_e32 v24, vcc, s1, v0
	s_mov_b32 s1, 0x18000
	s_nop 0
	v_addc_co_u32_e32 v25, vcc, 0, v1, vcc
	global_store_short v[24:25], v27, off offset:-4096
	v_mul_f32_e32 v27, v83, v95
	v_mul_f32_e32 v27, v27, v102
	v_cvt_pk_bf16_f32 v27, v27, v193
	global_store_short v[24:25], v27, off
	v_cvt_pk_bf16_f32 v30, v26, v193
	v_add_co_u32_e32 v26, vcc, s1, v0
	s_mov_b32 s1, 0x19000
	s_nop 0
	v_addc_co_u32_e32 v27, vcc, 0, v1, vcc
	v_add_co_u32_e32 v28, vcc, s1, v0
	s_mov_b32 s1, 0x1a000
	s_nop 0
	v_addc_co_u32_e32 v29, vcc, 0, v1, vcc
	global_store_short v[28:29], v30, off offset:-4096
	v_mul_f32_e32 v30, v84, v99
	v_mul_f32_e32 v30, v102, v30
	v_cvt_pk_bf16_f32 v30, v30, v193
	global_store_short v[28:29], v30, off
	v_mul_f32_e32 v30, v87, v100
	v_mul_f32_e32 v30, v102, v30
	v_cvt_pk_bf16_f32 v83, v30, v193
	v_add_co_u32_e32 v30, vcc, s1, v0
	s_mov_b32 s1, 0x1b000
	s_nop 0
	v_addc_co_u32_e32 v31, vcc, 0, v1, vcc
	v_add_co_u32_e32 v32, vcc, s1, v0
	v_mul_f32_e32 v84, v96, v62
	s_nop 0
	v_addc_co_u32_e32 v33, vcc, 0, v1, vcc
	global_store_short v[32:33], v83, off offset:-4096
	v_mul_f32_e32 v83, v89, v101
	v_mul_f32_e32 v83, v102, v83
	v_cvt_pk_bf16_f32 v83, v83, v193
	global_store_short v[32:33], v83, off
	s_nop 1
	v_mov_b32_e32 v83, v148
	v_mul_f32_e32 v84, v84, v83
	v_cvt_pk_bf16_f32 v84, v84, v193
	global_store_short v[0:1], v84, off offset:64
	v_mul_f32_e32 v84, v97, v63
	v_mul_f32_e32 v84, v84, v83
	v_mul_f32_e32 v81, v81, v83
	v_mul_f32_e32 v66, v66, v83
	v_cvt_pk_bf16_f32 v84, v84, v193
	global_store_short v[4:5], v84, off offset:64
	v_cvt_pk_bf16_f32 v81, v81, v193
	global_store_short v[6:7], v81, off offset:64
	v_cvt_pk_bf16_f32 v66, v66, v193
	global_store_short v[8:9], v66, off offset:64
	v_mul_f32_e32 v66, v82, v86
	v_mul_f32_e32 v66, v66, v83
	v_cvt_pk_bf16_f32 v66, v66, v193
	global_store_short v[10:11], v66, off offset:64
	v_mul_f32_e32 v66, v68, v88
	v_mul_f32_e32 v66, v66, v83
	v_cvt_pk_bf16_f32 v66, v66, v193
	global_store_short v[12:13], v66, off offset:64
	v_mul_f32_e32 v66, v69, v90
	v_mul_f32_e32 v66, v66, v83
	v_cvt_pk_bf16_f32 v66, v66, v193
	global_store_short v[14:15], v66, off offset:64
	v_mul_f32_e32 v66, v70, v91
	v_mul_f32_e32 v66, v66, v83
	v_cvt_pk_bf16_f32 v66, v66, v193
	global_store_short v[16:17], v66, off offset:64
	v_mul_f32_e32 v66, v71, v92
	v_mul_f32_e32 v66, v66, v83
	v_cvt_pk_bf16_f32 v66, v66, v193
	global_store_short v[18:19], v66, off offset:64
	v_mul_f32_e32 v66, v72, v93
	v_mul_f32_e32 v66, v66, v83
	v_cvt_pk_bf16_f32 v66, v66, v193
	global_store_short v[20:21], v66, off offset:64
	v_mul_f32_e32 v66, v73, v94
; __device__ __forceinline__ void attn_fused(const Params& p, int layer, float lam, float lam_init, int q0, int tok0, int h, int seq, char* lds) {
;     ...
;   for (int d = 0; d < 4; ++d) { const float sl = p.subln[layer * 128 + d * 32 + r32];
; #pragma unroll
;     for (int r = 0; r < 16; ++r) { const float y = oa[d][r] * ss[r] * sl;
;       mp[(size_t)((r & 3) + 8 * (r >> 2)) * DM + d * 32] = (bf16_t)(cvtpk(y, 0.f) & 0xffffu); } }
; __device__ __forceinline__ void attn_phase(const Params& p, int layer, char* lds) {
;     ...
;   for (int it = blockIdx.x; it < 1024; it += gridDim.x) {
	v_mul_f32_e32 v66, v66, v83
	v_mul_f32_e32 v58, v58, v83
	v_cvt_pk_bf16_f32 v66, v66, v193
	global_store_short v[22:23], v66, off offset:64
	v_cvt_pk_bf16_f32 v58, v58, v193
	global_store_short v[24:25], v58, off offset:64
	v_mul_f32_e32 v58, v75, v98
	v_mul_f32_e32 v58, v58, v83
	v_cvt_pk_bf16_f32 v58, v58, v193
	global_store_short v[26:27], v58, off offset:64
	v_mul_f32_e32 v58, v76, v99
	v_mul_f32_e32 v58, v58, v83
	v_cvt_pk_bf16_f32 v58, v58, v193
	global_store_short v[28:29], v58, off offset:64
	v_mul_f32_e32 v58, v77, v100
	v_mul_f32_e32 v58, v58, v83
	v_cvt_pk_bf16_f32 v58, v58, v193
	global_store_short v[30:31], v58, off offset:64
	v_mul_f32_e32 v58, v78, v101
	v_mul_f32_e32 v58, v58, v83
	v_cvt_pk_bf16_f32 v58, v58, v193
	global_store_short v[32:33], v58, off offset:64
	s_nop 1
	v_mov_b32_e32 v58, v149
	v_mul_f32_e32 v66, v80, v62
	v_mul_f32_e32 v66, v66, v58
	v_mul_f32_e32 v64, v64, v58
	v_cvt_pk_bf16_f32 v66, v66, v193
	global_store_short v[0:1], v66, off offset:128
	v_cvt_pk_bf16_f32 v64, v64, v193
	global_store_short v[4:5], v64, off offset:128
	v_mul_f32_e32 v64, v65, v79
	v_mul_f32_e32 v64, v64, v58
	v_mul_f32_e32 v35, v35, v58
	v_cvt_pk_bf16_f32 v64, v64, v193
	global_store_short v[6:7], v64, off offset:128
	v_cvt_pk_bf16_f32 v35, v35, v193
	global_store_short v[8:9], v35, off offset:128
	v_mul_f32_e32 v35, v67, v86
	v_mul_f32_e32 v35, v35, v58
	v_cvt_pk_bf16_f32 v35, v35, v193
	global_store_short v[10:11], v35, off offset:128
	v_mul_f32_e32 v35, v52, v88
	v_mul_f32_e32 v35, v35, v58
	v_cvt_pk_bf16_f32 v35, v35, v193
	global_store_short v[12:13], v35, off offset:128
	v_mul_f32_e32 v35, v53, v90
	v_mul_f32_e32 v35, v35, v58
	v_cvt_pk_bf16_f32 v35, v35, v193
	global_store_short v[14:15], v35, off offset:128
	v_mul_f32_e32 v35, v54, v91
	v_mul_f32_e32 v35, v35, v58
	v_cvt_pk_bf16_f32 v35, v35, v193
	global_store_short v[16:17], v35, off offset:128
	v_mul_f32_e32 v35, v55, v92
	v_mul_f32_e32 v35, v35, v58
	v_cvt_pk_bf16_f32 v35, v35, v193
	global_store_short v[18:19], v35, off offset:128
	v_mul_f32_e32 v35, v56, v93
	v_mul_f32_e32 v35, v35, v58
	v_cvt_pk_bf16_f32 v35, v35, v193
	global_store_short v[20:21], v35, off offset:128
	v_mul_f32_e32 v35, v57, v94
	v_mul_f32_e32 v35, v35, v58
	v_cvt_pk_bf16_f32 v35, v35, v193
	global_store_short v[22:23], v35, off offset:128
	v_mul_f32_e32 v35, v43, v95
	v_mul_f32_e32 v35, v35, v58
	v_cvt_pk_bf16_f32 v35, v35, v193
	global_store_short v[24:25], v35, off offset:128
	v_mul_f32_e32 v35, v74, v98
	v_mul_f32_e32 v35, v35, v58
	v_cvt_pk_bf16_f32 v35, v35, v193
	global_store_short v[26:27], v35, off offset:128
	v_mul_f32_e32 v35, v60, v99
	v_mul_f32_e32 v35, v35, v58
	v_cvt_pk_bf16_f32 v35, v35, v193
	global_store_short v[28:29], v35, off offset:128
	v_mul_f32_e32 v35, v61, v100
	v_mul_f32_e32 v35, v35, v58
	v_cvt_pk_bf16_f32 v35, v35, v193
	global_store_short v[30:31], v35, off offset:128
	v_mul_f32_e32 v35, v47, v101
	v_mul_f32_e32 v35, v35, v58
	v_cvt_pk_bf16_f32 v35, v35, v193
	s_nop 1
	v_mov_b32_e32 v2, v150
	v_mul_f32_e32 v3, v48, v62
	global_store_short v[32:33], v35, off offset:128
	v_mul_f32_e32 v3, v3, v2
	v_cvt_pk_bf16_f32 v3, v3, v193
	global_store_short v[0:1], v3, off offset:192
	v_mul_f32_e32 v0, v49, v63
	v_mul_f32_e32 v0, v0, v2
	v_cvt_pk_bf16_f32 v0, v0, v193
	global_store_short v[4:5], v0, off offset:192
	v_mul_f32_e32 v0, v50, v79
	v_mul_f32_e32 v0, v0, v2
	v_cvt_pk_bf16_f32 v0, v0, v193
	global_store_short v[6:7], v0, off offset:192
	v_mul_f32_e32 v0, v34, v85
	v_mul_f32_e32 v0, v0, v2
	v_cvt_pk_bf16_f32 v0, v0, v193
	global_store_short v[8:9], v0, off offset:192
	v_mul_f32_e32 v0, v51, v86
	v_mul_f32_e32 v0, v0, v2
	v_cvt_pk_bf16_f32 v0, v0, v193
	global_store_short v[10:11], v0, off offset:192
	v_mul_f32_e32 v0, v36, v88
	v_mul_f32_e32 v0, v0, v2
	v_cvt_pk_bf16_f32 v0, v0, v193
	global_store_short v[12:13], v0, off offset:192
	v_mul_f32_e32 v0, v37, v90
	v_mul_f32_e32 v0, v0, v2
	v_cvt_pk_bf16_f32 v0, v0, v193
	global_store_short v[14:15], v0, off offset:192
	v_mul_f32_e32 v0, v38, v91
	v_mul_f32_e32 v0, v0, v2
	v_cvt_pk_bf16_f32 v0, v0, v193
	global_store_short v[16:17], v0, off offset:192
	v_mul_f32_e32 v0, v39, v92
	v_mul_f32_e32 v0, v0, v2
	v_cvt_pk_bf16_f32 v0, v0, v193
	global_store_short v[18:19], v0, off offset:192
	v_mul_f32_e32 v0, v40, v93
	v_mul_f32_e32 v0, v0, v2
	v_cvt_pk_bf16_f32 v0, v0, v193
	global_store_short v[20:21], v0, off offset:192
	v_mul_f32_e32 v0, v41, v94
	v_mul_f32_e32 v0, v0, v2
	v_cvt_pk_bf16_f32 v0, v0, v193
	global_store_short v[22:23], v0, off offset:192
	v_mul_f32_e32 v0, v42, v95
	v_mul_f32_e32 v0, v0, v2
	v_cvt_pk_bf16_f32 v0, v0, v193
	global_store_short v[24:25], v0, off offset:192
	v_mul_f32_e32 v0, v59, v98
	v_mul_f32_e32 v0, v0, v2
	v_cvt_pk_bf16_f32 v0, v0, v193
	global_store_short v[26:27], v0, off offset:192
	v_mul_f32_e32 v0, v44, v99
	v_mul_f32_e32 v0, v0, v2
	v_cvt_pk_bf16_f32 v0, v0, v193
	global_store_short v[28:29], v0, off offset:192
	v_mul_f32_e32 v0, v45, v100
	v_mul_f32_e32 v0, v0, v2
	v_cvt_pk_bf16_f32 v0, v0, v193
	global_store_short v[30:31], v0, off offset:192
	v_mul_f32_e32 v0, v46, v101
	v_mul_f32_e32 v0, v0, v2
	v_cvt_pk_bf16_f32 v0, v0, v193
	global_store_short v[32:33], v0, off offset:192
	s_load_dword s1, s[94:95], 0x0
	s_waitcnt lgkmcnt(0)
	s_add_i32 s72, s1, s72
	s_cmpk_gt_i32 s72, 0x3ff
	s_cbranch_scc1 .LBB0_146

;   __device__ __forceinline__ bf16_t* Z() const { return (bf16_t*)(ws + 456 * MB); }
; #define opaque_tid() opaque_tid_w(p.wave)
; __device__ __forceinline__ void gate_pair(const Params& p, int layer, int it, char* lds) {
;   const int tid = opaque_tid(), half = tid >> 8, ltid = tid & 255, lane = tid & 63, r32 = lane & 31, hi = lane >> 5;
;   const int item = it * 2 + half, ci = item >> 3, g = item & 7, t0 = ci * 128;
;   bf16_t* vnT = (bf16_t*)(lds + half * 34816);
;   bf16_t* gul = (bf16_t*)(lds + 69632 + half * 33792);
;   {
; #pragma unroll
;     for (int i = 0; i < 8; ++i) { const int row = i * 16 + (ltid >> 4), cc = ltid & 15;
;       const u32x4 w = *(const u32x4*)(p.Z() + (size_t)(t0 + row) * LDZ + 3072 + g * 128 + cc * 8);
;       u32x2* d = (u32x2*)(gul + row * 132 + cc * 8); d[0] = (u32x2){w[0], w[1]}; d[1] = (u32x2){w[2], w[3]}; }
;     const int cc = ltid & 15, c8 = cc * 8;
;     u32x4 gvw[8];
; #pragma unroll
;     for (int i = 0; i < 8; ++i) gvw[i] = *(const u32x4*)(p.Z() + (size_t)(t0 + i * 16 + (ltid >> 4)) * LDZ + 4096 + g * 128 + c8);
;     const f32x4 lga = *(const f32x4*)(p.gln_g + layer * 1024 + g * 128 + c8), lgb = *(const f32x4*)(p.gln_g + layer * 1024 + g * 128 + c8 + 4);
;     const f32x4 lba = *(const f32x4*)(p.gln_b + layer * 1024 + g * 128 + c8), lbb = *(const f32x4*)(p.gln_b + layer * 1024 + g * 128 + c8 + 4);
.LBB0_148:
	v_mbcnt_lo_u32_b32 v36, -1, 0
	v_mbcnt_hi_u32_b32 v36, -1, v36
	s_movk_i32 s1, 0xff80
	v_add_u32_e32 v38, s10, v36
	v_ashrrev_i32_e32 v37, 8, v38
	v_lshl_add_u32 v0, s5, 1, v37
	v_lshlrev_b32_e32 v28, 4, v0
	v_bfe_u32 v44, v38, 4, 4
	v_lshlrev_b32_e32 v0, 7, v0
	v_and_b32_e32 v117, 0x380, v0
	v_lshlrev_b32_e32 v60, 3, v36
	v_and_or_b32 v104, v28, s1, v44
	v_mov_b64_e32 v[52:53], s[98:99]
	v_and_b32_e32 v61, 0x78, v60
	v_mad_i64_i32 v[0:1], s[8:9], v104, s11, v[52:53]
	v_lshlrev_b32_e32 v192, 1, v117
	v_lshlrev_b32_e32 v88, 1, v61
	v_mov_b32_e32 v89, v193
	v_lshl_add_u64 v[0:1], v[0:1], 0, v[192:193]
	v_or_b32_e32 v102, 16, v104
	v_lshl_add_u64 v[32:33], v[0:1], 0, v[88:89]
	v_mad_i64_i32 v[2:3], s[8:9], v102, s11, v[52:53]
	v_add_co_u32_e32 v0, vcc, s67, v32
	v_lshl_add_u64 v[2:3], v[2:3], 0, v[192:193]
	v_or_b32_e32 v100, 32, v104
	v_addc_co_u32_e32 v1, vcc, 0, v33, vcc
	v_lshl_add_u64 v[34:35], v[2:3], 0, v[88:89]
	v_mad_i64_i32 v[8:9], s[8:9], v100, s11, v[52:53]
	v_add_co_u32_e32 v4, vcc, s67, v34
	v_lshl_add_u64 v[8:9], v[8:9], 0, v[192:193]
	v_or_b32_e32 v98, 48, v104
	v_addc_co_u32_e32 v5, vcc, 0, v35, vcc
	v_lshl_add_u64 v[48:49], v[8:9], 0, v[88:89]
	v_mad_i64_i32 v[10:11], s[8:9], v98, s11, v[52:53]
	v_add_co_u32_e32 v8, vcc, s67, v48
	v_lshl_add_u64 v[10:11], v[10:11], 0, v[192:193]
	v_or_b32_e32 v96, 64, v104
	v_addc_co_u32_e32 v9, vcc, 0, v49, vcc
	v_lshl_add_u64 v[50:51], v[10:11], 0, v[88:89]
	v_mad_i64_i32 v[16:17], s[8:9], v96, s11, v[52:53]
	v_add_co_u32_e32 v12, vcc, s67, v50
	v_lshl_add_u64 v[16:17], v[16:17], 0, v[192:193]
	v_or_b32_e32 v94, 0x50, v104
	v_addc_co_u32_e32 v13, vcc, 0, v51, vcc
	v_lshl_add_u64 v[54:55], v[16:17], 0, v[88:89]
	v_mad_i64_i32 v[18:19], s[8:9], v94, s11, v[52:53]
	v_add_co_u32_e32 v16, vcc, s67, v54
	v_lshl_add_u64 v[18:19], v[18:19], 0, v[192:193]
	v_or_b32_e32 v92, 0x60, v104
	v_addc_co_u32_e32 v17, vcc, 0, v55, vcc
	v_lshl_add_u64 v[56:57], v[18:19], 0, v[88:89]
	v_mad_i64_i32 v[24:25], s[8:9], v92, s11, v[52:53]
	s_movk_i32 s1, 0x70
	v_add_co_u32_e32 v20, vcc, s67, v56
	v_lshl_add_u64 v[24:25], v[24:25], 0, v[192:193]
	v_or3_b32 v90, v44, v28, s1
	v_addc_co_u32_e32 v21, vcc, 0, v57, vcc
	v_lshl_add_u64 v[58:59], v[24:25], 0, v[88:89]
	v_mad_i64_i32 v[28:29], s[8:9], v90, s11, v[52:53]
	v_add_co_u32_e32 v24, vcc, s67, v58
	v_lshl_add_u64 v[28:29], v[28:29], 0, v[192:193]
	s_nop 0
	v_addc_co_u32_e32 v25, vcc, 0, v59, vcc
	v_lshl_add_u64 v[28:29], v[28:29], 0, v[88:89]
	global_load_dwordx4 v[0:3], v[0:1], off offset:2048
	s_nop 0
	global_load_dwordx4 v[4:7], v[4:5], off offset:2048
	v_add_co_u32_e32 v28, vcc, s67, v28
	global_load_dwordx4 v[8:11], v[8:9], off offset:2048
	s_nop 0
	global_load_dwordx4 v[12:15], v[12:13], off offset:2048
	v_addc_co_u32_e32 v29, vcc, 0, v29, vcc
	global_load_dwordx4 v[16:19], v[16:17], off offset:2048
	s_nop 0
	global_load_dwordx4 v[20:23], v[20:21], off offset:2048
	v_add_co_u32_e32 v32, vcc, s2, v32
	global_load_dwordx4 v[24:27], v[24:25], off offset:2048
	s_nop 0
	v_addc_co_u32_e32 v33, vcc, 0, v33, vcc
	global_load_dwordx4 v[28:31], v[28:29], off offset:2048
	s_mov_b32 s1, 0x8400
	global_load_dwordx4 v[40:43], v[32:33], off
	v_mov_b32_e32 v32, 0x11000
	v_mad_i32_i24 v118, v37, s1, v32
	v_or_b32_e32 v32, v118, v88
	s_movk_i32 s1, 0x108
	v_mad_u32_u24 v115, v44, s1, v32
	v_add_u32_e32 v114, 0x1080, v115
	v_lshlrev_b32_e32 v106, 2, v117
	v_mov_b32_e32 v107, v193
	v_add_u32_e32 v113, 0x2100, v115
	v_add_u32_e32 v112, 0x3180, v115
	v_add_u32_e32 v111, 0x4200, v115
	v_add_u32_e32 v110, 0x5280, v115
	v_add_u32_e32 v109, 0x6300, v115
	v_add_u32_e32 v108, 0x7380, v115
	v_lshrrev_b32_e32 v62, 4, v38
	v_bfe_u32 v60, v60, 5, 2
	s_mov_b32 s1, 0x8800
	v_and_b32_e32 v64, 48, v88
	v_and_b32_e32 v39, 31, v36
	v_bfe_u32 v116, v36, 5, 1
	v_lshlrev_b32_e32 v140, 3, v116
	v_ashrrev_i32_e32 v105, 31, v104
	v_ashrrev_i32_e32 v91, 31, v90
	v_ashrrev_i32_e32 v103, 31, v102
	v_ashrrev_i32_e32 v101, 31, v100
	v_ashrrev_i32_e32 v99, 31, v98
	v_ashrrev_i32_e32 v97, 31, v96
	v_ashrrev_i32_e32 v95, 31, v94
	v_ashrrev_i32_e32 v93, 31, v92
	s_waitcnt vmcnt(8)
	ds_write2_b64 v115, v[0:1], v[2:3] offset1:1
	v_add_co_u32_e32 v0, vcc, s2, v34
	s_waitcnt vmcnt(7)
	ds_write2_b64 v114, v[4:5], v[6:7] offset1:1
	v_addc_co_u32_e32 v1, vcc, 0, v35, vcc
	global_load_dwordx4 v[44:47], v[0:1], off
	v_lshl_add_u64 v[0:1], s[6:7], 0, v[106:107]
	v_lshlrev_b32_e32 v4, 2, v61
	v_mov_b32_e32 v5, v193
	s_waitcnt vmcnt(7)
	ds_write2_b64 v113, v[8:9], v[10:11] offset1:1
	s_waitcnt vmcnt(6)
	ds_write2_b64 v112, v[12:13], v[14:15] offset1:1
	s_waitcnt vmcnt(5)
	ds_write2_b64 v111, v[16:17], v[18:19] offset1:1
	s_waitcnt vmcnt(4)
	ds_write2_b64 v110, v[20:21], v[22:23] offset1:1
	s_waitcnt vmcnt(3)
	ds_write2_b64 v109, v[24:25], v[26:27] offset1:1
	s_waitcnt vmcnt(2)
	ds_write2_b64 v108, v[28:29], v[30:31] offset1:1
	v_lshl_add_u64 v[6:7], v[0:1], 0, v[4:5]
	global_load_dwordx4 v[0:3], v[6:7], off offset:16
	global_load_dwordx4 v[8:11], v[6:7], off
	v_lshl_add_u64 v[6:7], s[16:17], 0, v[106:107]
	v_lshl_add_u64 v[12:13], v[6:7], 0, v[4:5]
	global_load_dwordx4 v[4:7], v[12:13], off offset:16
	s_nop 0
	global_load_dwordx4 v[12:15], v[12:13], off
	v_add_co_u32_e32 v16, vcc, s2, v48
	s_nop 1
	v_addc_co_u32_e32 v17, vcc, 0, v49, vcc
	v_add_co_u32_e32 v18, vcc, s2, v50
	s_nop 1
	v_addc_co_u32_e32 v19, vcc, 0, v51, vcc
	global_load_dwordx4 v[48:51], v[16:17], off
	global_load_dwordx4 v[32:35], v[18:19], off
	v_add_co_u32_e32 v16, vcc, s2, v54
	s_waitcnt vmcnt(7)
; __device__ __forceinline__ float bflo(unsigned w) { return __uint_as_float(w << 16); }
; __device__ __forceinline__ float bfhi(unsigned w) { return __uint_as_float(w & 0xffff0000u); }
; template <int CTRL> __device__ __forceinline__ float dpp_mov(float x) { return __int_as_float(__builtin_amdgcn_update_dpp(0, __float_as_int(x), CTRL, 0xf, 0xf, true)); }
; __device__ __forceinline__ int v_st(int k, int c) { const int kk = (k & ~0xC) | ((k & 4) << 1) | ((k & 8) >> 1); return ((kk >> 3) * 4 + (c >> 5)) * 512 + ((kk & 7) * 32 + (c & 31)) * 2; }
; __device__ __forceinline__ void gate_pair(const Params& p, int layer, int it, char* lds) {
;     ...
;     for (int i = 0; i < 8; ++i) { const int q = i * 16 + (ltid >> 4);
;       float x[8];
; #pragma unroll
;       for (int e = 0; e < 4; ++e) { x[2 * e] = bflo(gvw[i][e]); x[2 * e + 1] = bfhi(gvw[i][e]); }
;       float s = ((x[0] + x[1]) + (x[2] + x[3])) + ((x[4] + x[5]) + (x[6] + x[7]));
;       s += dpp_mov<0xB1>(s); s += dpp_mov<0x4E>(s); s += dpp_mov<0x141>(s); s += dpp_mov<0x140>(s);
;       const float mu = s * (1.f / 128.f);
;       float s2 = 0.f;
; #pragma unroll
;       for (int e = 0; e < 8; ++e) { x[e] -= mu; s2 = fmaf(x[e], x[e], s2); }
;       s2 += dpp_mov<0xB1>(s2); s2 += dpp_mov<0x4E>(s2); s2 += dpp_mov<0x141>(s2); s2 += dpp_mov<0x140>(s2);
;       const float rstd = rsqrtf(s2 * (1.f / 128.f) + EPS);
;       const u32x4 w = {cvtpk(x[0] * rstd * lga[0] + lba[0], x[1] * rstd * lga[1] + lba[1]), cvtpk(x[2] * rstd * lga[2] + lba[2], x[3] * rstd * lga[3] + lba[3]),
;                        cvtpk(x[4] * rstd * lgb[0] + lbb[0], x[5] * rstd * lgb[1] + lbb[1]), cvtpk(x[6] * rstd * lgb[2] + lbb[2], x[7] * rstd * lgb[3] + lbb[3])};
;       *(u32x4*)((char*)vnT + (q >> 6) * 16384 + v_st(q & 63, c8)) = w; }
	v_lshlrev_b32_e32 v54, 16, v40
	v_addc_co_u32_e32 v17, vcc, 0, v55, vcc
	v_add_co_u32_e32 v18, vcc, s2, v56
	v_lshlrev_b32_e32 v55, 16, v42
	s_nop 0
	v_addc_co_u32_e32 v19, vcc, 0, v57, vcc
	global_load_dwordx4 v[28:31], v[16:17], off
	global_load_dwordx4 v[24:27], v[18:19], off
	v_add_co_u32_e32 v16, vcc, s2, v58
	v_or_b32_e32 v18, 0x70, v104
	s_nop 0
	v_addc_co_u32_e32 v17, vcc, 0, v59, vcc
	v_mad_i64_i32 v[18:19], s[8:9], v18, s11, v[52:53]
	v_lshrrev_b32_e32 v52, 5, v38
	v_and_b32_e32 v57, 0xffff0000, v42
	v_and_b32_e32 v56, 0xffff0000, v40
	v_lshlrev_b32_e32 v59, 16, v43
	v_lshlrev_b32_e32 v58, 16, v41
	v_and_b32_e32 v43, 0xffff0000, v43
	v_and_b32_e32 v42, 0xffff0000, v41
	v_and_b32_e32 v61, 4, v52
	v_pk_add_f32 v[40:41], v[54:55], v[56:57]
	v_pk_add_f32 v[52:53], v[58:59], v[42:43]
	v_lshl_add_u64 v[18:19], v[18:19], 0, v[192:193]
	v_pk_add_f32 v[40:41], v[40:41], v[52:53]
	v_lshl_add_u64 v[18:19], v[18:19], 0, v[88:89]
	v_add_f32_e32 v40, v40, v41
	v_add_co_u32_e32 v18, vcc, s2, v18
	s_nop 0
	v_add_f32_dpp v40, v40, v40 quad_perm:[1,0,3,2] row_mask:0xf bank_mask:0xf bound_ctrl:1
	v_addc_co_u32_e32 v19, vcc, 0, v19, vcc
	s_nop 0
	v_add_f32_dpp v40, v40, v40 quad_perm:[2,3,0,1] row_mask:0xf bank_mask:0xf bound_ctrl:1
	global_load_dwordx4 v[20:23], v[16:17], off
	s_nop 0
	global_load_dwordx4 v[16:19], v[18:19], off
	v_add_f32_dpp v40, v40, v40 row_half_mirror row_mask:0xf bank_mask:0xf bound_ctrl:1
	s_nop 1
	v_add_f32_dpp v40, v40, v40 row_mirror row_mask:0xf bank_mask:0xf bound_ctrl:1
	v_fmac_f32_e32 v54, 0xbc000000, v40
	v_fma_f32 v41, v54, v54, 0
	v_fmac_f32_e32 v56, 0xbc000000, v40
	v_fmac_f32_e32 v41, v56, v56
	v_fmac_f32_e32 v58, 0xbc000000, v40
	v_fmac_f32_e32 v41, v58, v58
	v_fmac_f32_e32 v42, 0xbc000000, v40
	v_fmac_f32_e32 v41, v42, v42
	v_fmac_f32_e32 v55, 0xbc000000, v40
	v_fmac_f32_e32 v41, v55, v55
	v_fmac_f32_e32 v57, 0xbc000000, v40
	v_fmac_f32_e32 v41, v57, v57
	v_fmac_f32_e32 v59, 0xbc000000, v40
	v_fmac_f32_e32 v41, v59, v59
	v_fmac_f32_e32 v43, 0xbc000000, v40
	v_fmac_f32_e32 v41, v43, v43
	s_nop 1
	v_add_f32_dpp v40, v41, v41 quad_perm:[1,0,3,2] row_mask:0xf bank_mask:0xf bound_ctrl:1
	s_nop 1
	v_add_f32_dpp v40, v40, v40 quad_perm:[2,3,0,1] row_mask:0xf bank_mask:0xf bound_ctrl:1
	s_nop 1
	v_add_f32_dpp v40, v40, v40 row_half_mirror row_mask:0xf bank_mask:0xf bound_ctrl:1
	s_nop 1
	v_add_f32_dpp v40, v40, v40 row_mirror row_mask:0xf bank_mask:0xf bound_ctrl:1
	v_fmamk_f32 v40, v40, 0x3c000000, v212
	v_mul_f32_e32 v41, 0x4b800000, v40
	v_cmp_gt_f32_e32 vcc, s65, v40
	s_nop 1
	v_cndmask_b32_e32 v40, v40, v41, vcc
	v_rsq_f32_e32 v40, v40
	v_and_or_b32 v41, v62, 3, v61
	v_lshlrev_b32_e32 v63, 6, v41
	s_waitcnt vmcnt(10)
	v_lshlrev_b32_e32 v61, 16, v47
	v_mul_f32_e32 v41, 0x45800000, v40
	v_cndmask_b32_e32 v40, v40, v41, vcc
	v_mul_f32_e32 v41, v54, v40
	v_mul_f32_e32 v52, v56, v40
	s_waitcnt vmcnt(6)
	v_fma_f32 v41, v8, v41, v12
	v_fma_f32 v52, v9, v52, v13
	v_cvt_pk_bf16_f32 v52, v41, v52
	v_mul_f32_e32 v41, v58, v40
	v_fma_f32 v41, v10, v41, v14
	v_mul_f32_e32 v42, v42, v40
	v_fma_f32 v42, v11, v42, v15
	v_cvt_pk_bf16_f32 v53, v41, v42
	v_mul_f32_e32 v41, v55, v40
	v_fma_f32 v41, v0, v41, v4
	v_mul_f32_e32 v42, v57, v40
	v_fma_f32 v42, v1, v42, v5
	v_cvt_pk_bf16_f32 v54, v41, v42
	v_mul_f32_e32 v41, v59, v40
	v_mul_f32_e32 v40, v43, v40
	v_fma_f32 v40, v3, v40, v7
	v_fma_f32 v41, v2, v41, v6
	v_cvt_pk_bf16_f32 v55, v41, v40
	v_and_or_b32 v40, v62, 4, v60
	v_lshlrev_b32_e32 v57, 16, v46
	v_lshlrev_b32_e32 v56, 16, v44
	v_and_b32_e32 v59, 0xffff0000, v46
	v_and_b32_e32 v58, 0xffff0000, v44
	v_lshlrev_b32_e32 v60, 16, v45
	v_and_b32_e32 v47, 0xffff0000, v47
	v_and_b32_e32 v46, 0xffff0000, v45
	v_lshlrev_b32_e32 v62, 9, v40
	v_pk_add_f32 v[40:41], v[56:57], v[58:59]
	v_pk_add_f32 v[42:43], v[60:61], v[46:47]
	s_nop 0
	v_pk_add_f32 v[40:41], v[40:41], v[42:43]
	s_nop 0
	v_add_f32_e32 v40, v40, v41
	s_nop 1
	v_add_f32_dpp v40, v40, v40 quad_perm:[1,0,3,2] row_mask:0xf bank_mask:0xf bound_ctrl:1
	s_nop 1
	v_add_f32_dpp v40, v40, v40 quad_perm:[2,3,0,1] row_mask:0xf bank_mask:0xf bound_ctrl:1
	s_nop 1
	v_add_f32_dpp v40, v40, v40 row_half_mirror row_mask:0xf bank_mask:0xf bound_ctrl:1
	s_nop 1
	v_add_f32_dpp v40, v40, v40 row_mirror row_mask:0xf bank_mask:0xf bound_ctrl:1
	v_fmac_f32_e32 v56, 0xbc000000, v40
	v_fma_f32 v41, v56, v56, 0
	v_fmac_f32_e32 v58, 0xbc000000, v40
	v_fmac_f32_e32 v41, v58, v58
	v_fmac_f32_e32 v60, 0xbc000000, v40
	v_fmac_f32_e32 v41, v60, v60
	v_fmac_f32_e32 v46, 0xbc000000, v40
	v_fmac_f32_e32 v41, v46, v46
	v_fmac_f32_e32 v57, 0xbc000000, v40
	v_fmac_f32_e32 v41, v57, v57
	v_fmac_f32_e32 v59, 0xbc000000, v40
	v_fmac_f32_e32 v41, v59, v59
	v_fmac_f32_e32 v61, 0xbc000000, v40
	v_fmac_f32_e32 v41, v61, v61
	v_fmac_f32_e32 v47, 0xbc000000, v40
	v_fmac_f32_e32 v41, v47, v47
	s_nop 1
	v_add_f32_dpp v40, v41, v41 quad_perm:[1,0,3,2] row_mask:0xf bank_mask:0xf bound_ctrl:1
	s_nop 1
	v_add_f32_dpp v40, v40, v40 quad_perm:[2,3,0,1] row_mask:0xf bank_mask:0xf bound_ctrl:1
	s_nop 1
	v_add_f32_dpp v40, v40, v40 row_half_mirror row_mask:0xf bank_mask:0xf bound_ctrl:1
	s_nop 1
	v_add_f32_dpp v40, v40, v40 row_mirror row_mask:0xf bank_mask:0xf bound_ctrl:1
	v_fmamk_f32 v40, v40, 0x3c000000, v212
	v_mul_f32_e32 v41, 0x4b800000, v40
	v_cmp_gt_f32_e32 vcc, s65, v40
	s_nop 1
	v_cndmask_b32_e32 v40, v40, v41, vcc
	v_rsq_f32_e32 v41, v40
	v_mad_i32_i24 v40, v37, s1, v62
	v_or3_b32 v40, v40, v63, v64
	ds_write_b128 v40, v[52:55]
	v_mul_f32_e32 v42, 0x45800000, v41
	v_cndmask_b32_e32 v41, v41, v42, vcc
	v_mul_f32_e32 v42, v56, v41
	v_mul_f32_e32 v43, v58, v41
	v_fma_f32 v42, v8, v42, v12
	v_fma_f32 v43, v9, v43, v13
	v_cvt_pk_bf16_f32 v42, v42, v43
	v_mul_f32_e32 v43, v60, v41
	v_mul_f32_e32 v44, v46, v41
	v_fma_f32 v43, v10, v43, v14
	v_fma_f32 v44, v11, v44, v15
	v_cvt_pk_bf16_f32 v43, v43, v44
	v_mul_f32_e32 v44, v57, v41
	v_mul_f32_e32 v45, v59, v41
	v_fma_f32 v44, v0, v44, v4
	v_fma_f32 v45, v1, v45, v5
	v_cvt_pk_bf16_f32 v44, v44, v45
	v_mul_f32_e32 v45, v61, v41
	v_mul_f32_e32 v41, v47, v41
	s_waitcnt vmcnt(5)
; __device__ __forceinline__ float bflo(unsigned w) { return __uint_as_float(w << 16); }
; __device__ __forceinline__ float bfhi(unsigned w) { return __uint_as_float(w & 0xffff0000u); }
; template <int CTRL> __device__ __forceinline__ float dpp_mov(float x) { return __int_as_float(__builtin_amdgcn_update_dpp(0, __float_as_int(x), CTRL, 0xf, 0xf, true)); }
; __device__ __forceinline__ int v_st(int k, int c) { const int kk = (k & ~0xC) | ((k & 4) << 1) | ((k & 8) >> 1); return ((kk >> 3) * 4 + (c >> 5)) * 512 + ((kk & 7) * 32 + (c & 31)) * 2; }
; __device__ __forceinline__ void gate_pair(const Params& p, int layer, int it, char* lds) {
;     ...
;     for (int i = 0; i < 8; ++i) { const int q = i * 16 + (ltid >> 4);
;       float x[8];
; #pragma unroll
;       for (int e = 0; e < 4; ++e) { x[2 * e] = bflo(gvw[i][e]); x[2 * e + 1] = bfhi(gvw[i][e]); }
;       float s = ((x[0] + x[1]) + (x[2] + x[3])) + ((x[4] + x[5]) + (x[6] + x[7]));
;       s += dpp_mov<0xB1>(s); s += dpp_mov<0x4E>(s); s += dpp_mov<0x141>(s); s += dpp_mov<0x140>(s);
;       const float mu = s * (1.f / 128.f);
;       float s2 = 0.f;
; #pragma unroll
;       for (int e = 0; e < 8; ++e) { x[e] -= mu; s2 = fmaf(x[e], x[e], s2); }
;       s2 += dpp_mov<0xB1>(s2); s2 += dpp_mov<0x4E>(s2); s2 += dpp_mov<0x141>(s2); s2 += dpp_mov<0x140>(s2);
;       const float rstd = rsqrtf(s2 * (1.f / 128.f) + EPS);
;       const u32x4 w = {cvtpk(x[0] * rstd * lga[0] + lba[0], x[1] * rstd * lga[1] + lba[1]), cvtpk(x[2] * rstd * lga[2] + lba[2], x[3] * rstd * lga[3] + lba[3]),
;                        cvtpk(x[4] * rstd * lgb[0] + lbb[0], x[5] * rstd * lgb[1] + lbb[1]), cvtpk(x[6] * rstd * lgb[2] + lbb[2], x[7] * rstd * lgb[3] + lbb[3])};
;       *(u32x4*)((char*)vnT + (q >> 6) * 16384 + v_st(q & 63, c8)) = w; }
	v_lshlrev_b32_e32 v47, 16, v50
	v_lshlrev_b32_e32 v46, 16, v48
	v_and_b32_e32 v53, 0xffff0000, v50
	v_and_b32_e32 v52, 0xffff0000, v48
	v_lshlrev_b32_e32 v55, 16, v51
	v_lshlrev_b32_e32 v54, 16, v49
	v_and_b32_e32 v51, 0xffff0000, v51
	v_and_b32_e32 v50, 0xffff0000, v49
	v_pk_add_f32 v[48:49], v[46:47], v[52:53]
	v_pk_add_f32 v[56:57], v[54:55], v[50:51]
	v_fma_f32 v45, v2, v45, v6
	v_pk_add_f32 v[48:49], v[48:49], v[56:57]
	v_fma_f32 v41, v3, v41, v7
	v_add_f32_e32 v48, v48, v49
	v_cvt_pk_bf16_f32 v45, v45, v41
	ds_write_b128 v40, v[42:45] offset:4096
	s_nop 0
	v_add_f32_dpp v48, v48, v48 quad_perm:[1,0,3,2] row_mask:0xf bank_mask:0xf bound_ctrl:1
	s_nop 1
	v_add_f32_dpp v48, v48, v48 quad_perm:[2,3,0,1] row_mask:0xf bank_mask:0xf bound_ctrl:1
	s_nop 1
	v_add_f32_dpp v48, v48, v48 row_half_mirror row_mask:0xf bank_mask:0xf bound_ctrl:1
	s_nop 1
	v_add_f32_dpp v48, v48, v48 row_mirror row_mask:0xf bank_mask:0xf bound_ctrl:1
	v_fmac_f32_e32 v46, 0xbc000000, v48
	v_fma_f32 v49, v46, v46, 0
	v_fmac_f32_e32 v52, 0xbc000000, v48
	v_fmac_f32_e32 v49, v52, v52
	v_fmac_f32_e32 v54, 0xbc000000, v48
	v_fmac_f32_e32 v49, v54, v54
	v_fmac_f32_e32 v50, 0xbc000000, v48
	v_fmac_f32_e32 v49, v50, v50
	v_fmac_f32_e32 v47, 0xbc000000, v48
	v_fmac_f32_e32 v49, v47, v47
	v_fmac_f32_e32 v53, 0xbc000000, v48
	v_fmac_f32_e32 v49, v53, v53
	v_fmac_f32_e32 v55, 0xbc000000, v48
	v_fmac_f32_e32 v49, v55, v55
	v_fmac_f32_e32 v51, 0xbc000000, v48
	v_fmac_f32_e32 v49, v51, v51
	s_nop 1
	v_add_f32_dpp v48, v49, v49 quad_perm:[1,0,3,2] row_mask:0xf bank_mask:0xf bound_ctrl:1
	s_nop 1
	v_add_f32_dpp v48, v48, v48 quad_perm:[2,3,0,1] row_mask:0xf bank_mask:0xf bound_ctrl:1
	s_nop 1
	v_add_f32_dpp v48, v48, v48 row_half_mirror row_mask:0xf bank_mask:0xf bound_ctrl:1
	s_nop 1
	v_add_f32_dpp v48, v48, v48 row_mirror row_mask:0xf bank_mask:0xf bound_ctrl:1
	v_fmamk_f32 v48, v48, 0x3c000000, v212
	v_mul_f32_e32 v49, 0x4b800000, v48
	v_cmp_gt_f32_e32 vcc, s65, v48
	s_nop 1
	v_cndmask_b32_e32 v48, v48, v49, vcc
	v_rsq_f32_e32 v48, v48
	s_waitcnt vmcnt(4)
	v_and_b32_e32 v49, 0xffff0000, v34
	v_mul_f32_e32 v41, 0x45800000, v48
	v_cndmask_b32_e32 v41, v48, v41, vcc
	v_mul_f32_e32 v42, v46, v41
	v_mul_f32_e32 v43, v52, v41
	v_fma_f32 v42, v8, v42, v12
	v_fma_f32 v43, v9, v43, v13
	v_cvt_pk_bf16_f32 v42, v42, v43
	v_mul_f32_e32 v43, v54, v41
	v_mul_f32_e32 v44, v50, v41
	v_fma_f32 v43, v10, v43, v14
	v_fma_f32 v44, v11, v44, v15
	v_cvt_pk_bf16_f32 v43, v43, v44
	v_mul_f32_e32 v44, v47, v41
	v_mul_f32_e32 v45, v53, v41
	v_fma_f32 v44, v0, v44, v4
	v_fma_f32 v45, v1, v45, v5
	v_cvt_pk_bf16_f32 v44, v44, v45
	v_mul_f32_e32 v45, v55, v41
	v_mul_f32_e32 v41, v51, v41
	v_lshlrev_b32_e32 v47, 16, v34
	v_lshlrev_b32_e32 v46, 16, v32
	v_and_b32_e32 v48, 0xffff0000, v32
	v_lshlrev_b32_e32 v51, 16, v35
	v_lshlrev_b32_e32 v50, 16, v33
	v_and_b32_e32 v35, 0xffff0000, v35
	v_and_b32_e32 v34, 0xffff0000, v33
	v_pk_add_f32 v[32:33], v[46:47], v[48:49]
	v_pk_add_f32 v[52:53], v[50:51], v[34:35]
	v_fma_f32 v45, v2, v45, v6
	v_pk_add_f32 v[32:33], v[32:33], v[52:53]
	s_nop 0
	v_add_f32_e32 v32, v32, v33
	s_nop 1
	v_add_f32_dpp v32, v32, v32 quad_perm:[1,0,3,2] row_mask:0xf bank_mask:0xf bound_ctrl:1
	s_nop 1
	v_add_f32_dpp v32, v32, v32 quad_perm:[2,3,0,1] row_mask:0xf bank_mask:0xf bound_ctrl:1
	s_nop 1
	v_add_f32_dpp v32, v32, v32 row_half_mirror row_mask:0xf bank_mask:0xf bound_ctrl:1
	s_nop 1
	v_add_f32_dpp v32, v32, v32 row_mirror row_mask:0xf bank_mask:0xf bound_ctrl:1
	v_fmac_f32_e32 v46, 0xbc000000, v32
	v_fma_f32 v33, v46, v46, 0
	v_fmac_f32_e32 v48, 0xbc000000, v32
	v_fmac_f32_e32 v33, v48, v48
	v_fmac_f32_e32 v50, 0xbc000000, v32
	v_fmac_f32_e32 v33, v50, v50
	v_fmac_f32_e32 v34, 0xbc000000, v32
	v_fmac_f32_e32 v33, v34, v34
	v_fmac_f32_e32 v47, 0xbc000000, v32
	v_fmac_f32_e32 v33, v47, v47
	v_fmac_f32_e32 v49, 0xbc000000, v32
	v_fmac_f32_e32 v33, v49, v49
	v_fmac_f32_e32 v51, 0xbc000000, v32
	v_fmac_f32_e32 v33, v51, v51
	v_fmac_f32_e32 v35, 0xbc000000, v32
	v_fmac_f32_e32 v33, v35, v35
	s_nop 1
	v_add_f32_dpp v32, v33, v33 quad_perm:[1,0,3,2] row_mask:0xf bank_mask:0xf bound_ctrl:1
	s_nop 1
	v_add_f32_dpp v32, v32, v32 quad_perm:[2,3,0,1] row_mask:0xf bank_mask:0xf bound_ctrl:1
	s_nop 1
	v_add_f32_dpp v32, v32, v32 row_half_mirror row_mask:0xf bank_mask:0xf bound_ctrl:1
	s_nop 1
	v_add_f32_dpp v32, v32, v32 row_mirror row_mask:0xf bank_mask:0xf bound_ctrl:1
	v_fmamk_f32 v32, v32, 0x3c000000, v212
	v_mul_f32_e32 v33, 0x4b800000, v32
	v_cmp_gt_f32_e32 vcc, s65, v32
	s_nop 1
	v_cndmask_b32_e32 v32, v32, v33, vcc
	v_rsq_f32_e32 v32, v32
	v_fma_f32 v33, v3, v41, v7
	v_cvt_pk_bf16_f32 v45, v45, v33
	ds_write_b128 v40, v[42:45] offset:8192
	v_mul_f32_e32 v33, 0x45800000, v32
	v_cndmask_b32_e32 v41, v32, v33, vcc
	v_mul_f32_e32 v32, v46, v41
	v_mul_f32_e32 v33, v48, v41
	v_fma_f32 v32, v8, v32, v12
	v_fma_f32 v33, v9, v33, v13
	v_cvt_pk_bf16_f32 v32, v32, v33
	v_mul_f32_e32 v33, v50, v41
	v_mul_f32_e32 v34, v34, v41
	v_fma_f32 v33, v10, v33, v14
	v_fma_f32 v34, v11, v34, v15
	v_cvt_pk_bf16_f32 v33, v33, v34
	v_mul_f32_e32 v34, v47, v41
	v_mul_f32_e32 v42, v49, v41
	v_fma_f32 v34, v0, v34, v4
	v_fma_f32 v42, v1, v42, v5
	v_cvt_pk_bf16_f32 v34, v34, v42
	v_mul_f32_e32 v42, v51, v41
	v_fma_f32 v50, v2, v42, v6
	s_waitcnt vmcnt(3)
; __device__ __forceinline__ float bflo(unsigned w) { return __uint_as_float(w << 16); }
; __device__ __forceinline__ float bfhi(unsigned w) { return __uint_as_float(w & 0xffff0000u); }
; template <int CTRL> __device__ __forceinline__ float dpp_mov(float x) { return __int_as_float(__builtin_amdgcn_update_dpp(0, __float_as_int(x), CTRL, 0xf, 0xf, true)); }
; __device__ __forceinline__ int v_st(int k, int c) { const int kk = (k & ~0xC) | ((k & 4) << 1) | ((k & 8) >> 1); return ((kk >> 3) * 4 + (c >> 5)) * 512 + ((kk & 7) * 32 + (c & 31)) * 2; }
; __device__ __forceinline__ void gate_pair(const Params& p, int layer, int it, char* lds) {
;     ...
;     for (int i = 0; i < 8; ++i) { const int q = i * 16 + (ltid >> 4);
;       float x[8];
; #pragma unroll
;       for (int e = 0; e < 4; ++e) { x[2 * e] = bflo(gvw[i][e]); x[2 * e + 1] = bfhi(gvw[i][e]); }
;       float s = ((x[0] + x[1]) + (x[2] + x[3])) + ((x[4] + x[5]) + (x[6] + x[7]));
;       s += dpp_mov<0xB1>(s); s += dpp_mov<0x4E>(s); s += dpp_mov<0x141>(s); s += dpp_mov<0x140>(s);
;       const float mu = s * (1.f / 128.f);
;       float s2 = 0.f;
; #pragma unroll
;       for (int e = 0; e < 8; ++e) { x[e] -= mu; s2 = fmaf(x[e], x[e], s2); }
;       s2 += dpp_mov<0xB1>(s2); s2 += dpp_mov<0x4E>(s2); s2 += dpp_mov<0x141>(s2); s2 += dpp_mov<0x140>(s2);
;       const float rstd = rsqrtf(s2 * (1.f / 128.f) + EPS);
;       const u32x4 w = {cvtpk(x[0] * rstd * lga[0] + lba[0], x[1] * rstd * lga[1] + lba[1]), cvtpk(x[2] * rstd * lga[2] + lba[2], x[3] * rstd * lga[3] + lba[3]),
;                        cvtpk(x[4] * rstd * lgb[0] + lbb[0], x[5] * rstd * lgb[1] + lbb[1]), cvtpk(x[6] * rstd * lgb[2] + lbb[2], x[7] * rstd * lgb[3] + lbb[3])};
;       *(u32x4*)((char*)vnT + (q >> 6) * 16384 + v_st(q & 63, c8)) = w; }
	v_lshlrev_b32_e32 v43, 16, v30
	v_lshlrev_b32_e32 v42, 16, v28
	v_and_b32_e32 v45, 0xffff0000, v30
	v_and_b32_e32 v44, 0xffff0000, v28
	v_lshlrev_b32_e32 v47, 16, v31
	v_lshlrev_b32_e32 v46, 16, v29
	v_and_b32_e32 v31, 0xffff0000, v31
	v_and_b32_e32 v30, 0xffff0000, v29
	v_pk_add_f32 v[28:29], v[42:43], v[44:45]
	v_pk_add_f32 v[48:49], v[46:47], v[30:31]
	v_mul_f32_e32 v35, v35, v41
	v_pk_add_f32 v[28:29], v[28:29], v[48:49]
	s_nop 0
	v_add_f32_e32 v28, v28, v29
	s_nop 1
	v_add_f32_dpp v28, v28, v28 quad_perm:[1,0,3,2] row_mask:0xf bank_mask:0xf bound_ctrl:1
	s_nop 1
	v_add_f32_dpp v28, v28, v28 quad_perm:[2,3,0,1] row_mask:0xf bank_mask:0xf bound_ctrl:1
	s_nop 1
	v_add_f32_dpp v28, v28, v28 row_half_mirror row_mask:0xf bank_mask:0xf bound_ctrl:1
	s_nop 1
	v_add_f32_dpp v28, v28, v28 row_mirror row_mask:0xf bank_mask:0xf bound_ctrl:1
	v_fmac_f32_e32 v42, 0xbc000000, v28
	v_fma_f32 v29, v42, v42, 0
	v_fmac_f32_e32 v44, 0xbc000000, v28
	v_fmac_f32_e32 v29, v44, v44
	v_fmac_f32_e32 v46, 0xbc000000, v28
	v_fmac_f32_e32 v29, v46, v46
	v_fmac_f32_e32 v30, 0xbc000000, v28
	v_fmac_f32_e32 v29, v30, v30
	v_fmac_f32_e32 v43, 0xbc000000, v28
	v_fmac_f32_e32 v29, v43, v43
	v_fmac_f32_e32 v45, 0xbc000000, v28
	v_fmac_f32_e32 v29, v45, v45
	v_fmac_f32_e32 v47, 0xbc000000, v28
	v_fmac_f32_e32 v29, v47, v47
	v_fmac_f32_e32 v31, 0xbc000000, v28
	v_fmac_f32_e32 v29, v31, v31
	s_nop 1
	v_add_f32_dpp v28, v29, v29 quad_perm:[1,0,3,2] row_mask:0xf bank_mask:0xf bound_ctrl:1
	s_nop 1
	v_add_f32_dpp v28, v28, v28 quad_perm:[2,3,0,1] row_mask:0xf bank_mask:0xf bound_ctrl:1
	s_nop 1
	v_add_f32_dpp v28, v28, v28 row_half_mirror row_mask:0xf bank_mask:0xf bound_ctrl:1
	s_nop 1
	v_add_f32_dpp v28, v28, v28 row_mirror row_mask:0xf bank_mask:0xf bound_ctrl:1
	v_fmamk_f32 v28, v28, 0x3c000000, v212
	v_mul_f32_e32 v29, 0x4b800000, v28
	v_cmp_gt_f32_e32 vcc, s65, v28
	s_nop 1
	v_cndmask_b32_e32 v28, v28, v29, vcc
	v_rsq_f32_e32 v28, v28
	v_fma_f32 v29, v3, v35, v7
	v_cvt_pk_bf16_f32 v35, v50, v29
	ds_write_b128 v40, v[32:35] offset:12288
	v_mul_f32_e32 v29, 0x45800000, v28
	v_cndmask_b32_e32 v32, v28, v29, vcc
	v_mul_f32_e32 v28, v42, v32
	v_mul_f32_e32 v29, v44, v32
	v_fma_f32 v28, v8, v28, v12
	v_fma_f32 v29, v9, v29, v13
	v_cvt_pk_bf16_f32 v28, v28, v29
	v_mul_f32_e32 v29, v46, v32
	v_mul_f32_e32 v30, v30, v32
	v_fma_f32 v29, v10, v29, v14
	v_fma_f32 v30, v11, v30, v15
	v_cvt_pk_bf16_f32 v29, v29, v30
	v_mul_f32_e32 v30, v43, v32
	v_mul_f32_e32 v33, v45, v32
	v_fma_f32 v30, v0, v30, v4
	v_fma_f32 v33, v1, v33, v5
	v_cvt_pk_bf16_f32 v30, v30, v33
	v_mul_f32_e32 v33, v47, v32
	v_fma_f32 v41, v2, v33, v6
	v_mul_f32_e32 v31, v31, v32
	s_waitcnt vmcnt(2)
	v_lshlrev_b32_e32 v33, 16, v26
	v_lshlrev_b32_e32 v32, 16, v24
	v_and_b32_e32 v35, 0xffff0000, v26
	v_and_b32_e32 v34, 0xffff0000, v24
	v_lshlrev_b32_e32 v43, 16, v27
	v_lshlrev_b32_e32 v42, 16, v25
	v_and_b32_e32 v27, 0xffff0000, v27
	v_and_b32_e32 v26, 0xffff0000, v25
	v_pk_add_f32 v[24:25], v[32:33], v[34:35]
	v_pk_add_f32 v[44:45], v[42:43], v[26:27]
	s_nop 0
	v_pk_add_f32 v[24:25], v[24:25], v[44:45]
	s_nop 0
	v_add_f32_e32 v24, v24, v25
	s_nop 1
	v_add_f32_dpp v24, v24, v24 quad_perm:[1,0,3,2] row_mask:0xf bank_mask:0xf bound_ctrl:1
	s_nop 1
	v_add_f32_dpp v24, v24, v24 quad_perm:[2,3,0,1] row_mask:0xf bank_mask:0xf bound_ctrl:1
	s_nop 1
	v_add_f32_dpp v24, v24, v24 row_half_mirror row_mask:0xf bank_mask:0xf bound_ctrl:1
	s_nop 1
	v_add_f32_dpp v24, v24, v24 row_mirror row_mask:0xf bank_mask:0xf bound_ctrl:1
	v_fmac_f32_e32 v32, 0xbc000000, v24
	v_fma_f32 v25, v32, v32, 0
	v_fmac_f32_e32 v34, 0xbc000000, v24
	v_fmac_f32_e32 v25, v34, v34
	v_fmac_f32_e32 v42, 0xbc000000, v24
	v_fmac_f32_e32 v25, v42, v42
	v_fmac_f32_e32 v26, 0xbc000000, v24
	v_fmac_f32_e32 v25, v26, v26
	v_fmac_f32_e32 v33, 0xbc000000, v24
	v_fmac_f32_e32 v25, v33, v33
	v_fmac_f32_e32 v35, 0xbc000000, v24
	v_fmac_f32_e32 v25, v35, v35
	v_fmac_f32_e32 v43, 0xbc000000, v24
	v_fmac_f32_e32 v25, v43, v43
	v_fmac_f32_e32 v27, 0xbc000000, v24
	v_fmac_f32_e32 v25, v27, v27
	s_nop 1
	v_add_f32_dpp v24, v25, v25 quad_perm:[1,0,3,2] row_mask:0xf bank_mask:0xf bound_ctrl:1
	s_nop 1
	v_add_f32_dpp v24, v24, v24 quad_perm:[2,3,0,1] row_mask:0xf bank_mask:0xf bound_ctrl:1
	s_nop 1
	v_add_f32_dpp v24, v24, v24 row_half_mirror row_mask:0xf bank_mask:0xf bound_ctrl:1
	s_nop 1
	v_add_f32_dpp v24, v24, v24 row_mirror row_mask:0xf bank_mask:0xf bound_ctrl:1
	v_fmamk_f32 v24, v24, 0x3c000000, v212
	v_mul_f32_e32 v25, 0x4b800000, v24
	v_cmp_gt_f32_e32 vcc, s65, v24
	s_nop 1
	v_cndmask_b32_e32 v24, v24, v25, vcc
	v_rsq_f32_e32 v24, v24
	v_fma_f32 v25, v3, v31, v7
	v_cvt_pk_bf16_f32 v31, v41, v25
	ds_write_b128 v40, v[28:31] offset:16384
	v_mul_f32_e32 v25, 0x45800000, v24
	v_cndmask_b32_e32 v28, v24, v25, vcc
	v_mul_f32_e32 v24, v32, v28
	v_mul_f32_e32 v25, v34, v28
	v_fma_f32 v24, v8, v24, v12
	v_fma_f32 v25, v9, v25, v13
	v_cvt_pk_bf16_f32 v24, v24, v25
	v_mul_f32_e32 v25, v42, v28
	v_mul_f32_e32 v26, v26, v28
	v_fma_f32 v25, v10, v25, v14
	v_fma_f32 v26, v11, v26, v15
	v_cvt_pk_bf16_f32 v25, v25, v26
	v_mul_f32_e32 v26, v33, v28
	v_mul_f32_e32 v29, v35, v28
	v_fma_f32 v26, v0, v26, v4
	v_fma_f32 v29, v1, v29, v5
	v_cvt_pk_bf16_f32 v26, v26, v29
	v_mul_f32_e32 v29, v43, v28
	v_fma_f32 v41, v2, v29, v6
	v_mul_f32_e32 v27, v27, v28
	s_waitcnt vmcnt(1)
; __device__ __forceinline__ float bflo(unsigned w) { return __uint_as_float(w << 16); }
; __device__ __forceinline__ float bfhi(unsigned w) { return __uint_as_float(w & 0xffff0000u); }
; template <int CTRL> __device__ __forceinline__ float dpp_mov(float x) { return __int_as_float(__builtin_amdgcn_update_dpp(0, __float_as_int(x), CTRL, 0xf, 0xf, true)); }
; __device__ __forceinline__ int v_st(int k, int c) { const int kk = (k & ~0xC) | ((k & 4) << 1) | ((k & 8) >> 1); return ((kk >> 3) * 4 + (c >> 5)) * 512 + ((kk & 7) * 32 + (c & 31)) * 2; }
; __device__ __forceinline__ void gate_pair(const Params& p, int layer, int it, char* lds) {
;     ...
;     for (int i = 0; i < 8; ++i) { const int q = i * 16 + (ltid >> 4);
;       float x[8];
; #pragma unroll
;       for (int e = 0; e < 4; ++e) { x[2 * e] = bflo(gvw[i][e]); x[2 * e + 1] = bfhi(gvw[i][e]); }
;       float s = ((x[0] + x[1]) + (x[2] + x[3])) + ((x[4] + x[5]) + (x[6] + x[7]));
;       s += dpp_mov<0xB1>(s); s += dpp_mov<0x4E>(s); s += dpp_mov<0x141>(s); s += dpp_mov<0x140>(s);
;       const float mu = s * (1.f / 128.f);
;       float s2 = 0.f;
; #pragma unroll
;       for (int e = 0; e < 8; ++e) { x[e] -= mu; s2 = fmaf(x[e], x[e], s2); }
;       s2 += dpp_mov<0xB1>(s2); s2 += dpp_mov<0x4E>(s2); s2 += dpp_mov<0x141>(s2); s2 += dpp_mov<0x140>(s2);
;       const float rstd = rsqrtf(s2 * (1.f / 128.f) + EPS);
;       const u32x4 w = {cvtpk(x[0] * rstd * lga[0] + lba[0], x[1] * rstd * lga[1] + lba[1]), cvtpk(x[2] * rstd * lga[2] + lba[2], x[3] * rstd * lga[3] + lba[3]),
;                        cvtpk(x[4] * rstd * lgb[0] + lbb[0], x[5] * rstd * lgb[1] + lbb[1]), cvtpk(x[6] * rstd * lgb[2] + lbb[2], x[7] * rstd * lgb[3] + lbb[3])};
;       *(u32x4*)((char*)vnT + (q >> 6) * 16384 + v_st(q & 63, c8)) = w; }
;   }
;   __syncthreads();
;   {
;     const int w4 = ltid >> 6, p0 = w4 * 32;
;     const float* swp = p.sw + (((size_t)layer * 8 + g) * 128 + p0 + r32) * 128 + hi * 8;
;     bf16x8 bfr[8];
; #pragma unroll
;     for (int s = 0; s < 8; ++s) { const f32x4 a = *(const f32x4*)(swp + s * 16), b = *(const f32x4*)(swp + s * 16 + 4);
	v_lshlrev_b32_e32 v29, 16, v22
	v_lshlrev_b32_e32 v28, 16, v20
	v_and_b32_e32 v31, 0xffff0000, v22
	v_and_b32_e32 v30, 0xffff0000, v20
	v_lshlrev_b32_e32 v33, 16, v23
	v_lshlrev_b32_e32 v32, 16, v21
	v_and_b32_e32 v23, 0xffff0000, v23
	v_and_b32_e32 v22, 0xffff0000, v21
	v_pk_add_f32 v[20:21], v[28:29], v[30:31]
	v_pk_add_f32 v[34:35], v[32:33], v[22:23]
	s_nop 0
	v_pk_add_f32 v[20:21], v[20:21], v[34:35]
	s_nop 0
	v_add_f32_e32 v20, v20, v21
	s_nop 1
	v_add_f32_dpp v20, v20, v20 quad_perm:[1,0,3,2] row_mask:0xf bank_mask:0xf bound_ctrl:1
	s_nop 1
	v_add_f32_dpp v20, v20, v20 quad_perm:[2,3,0,1] row_mask:0xf bank_mask:0xf bound_ctrl:1
	s_nop 1
	v_add_f32_dpp v20, v20, v20 row_half_mirror row_mask:0xf bank_mask:0xf bound_ctrl:1
	s_nop 1
	v_add_f32_dpp v20, v20, v20 row_mirror row_mask:0xf bank_mask:0xf bound_ctrl:1
	v_fmac_f32_e32 v28, 0xbc000000, v20
	v_fma_f32 v21, v28, v28, 0
	v_fmac_f32_e32 v30, 0xbc000000, v20
	v_fmac_f32_e32 v21, v30, v30
	v_fmac_f32_e32 v32, 0xbc000000, v20
	v_fmac_f32_e32 v21, v32, v32
	v_fmac_f32_e32 v22, 0xbc000000, v20
	v_fmac_f32_e32 v21, v22, v22
	v_fmac_f32_e32 v29, 0xbc000000, v20
	v_fmac_f32_e32 v21, v29, v29
	v_fmac_f32_e32 v31, 0xbc000000, v20
	v_fmac_f32_e32 v21, v31, v31
	v_fmac_f32_e32 v33, 0xbc000000, v20
	v_fmac_f32_e32 v21, v33, v33
	v_fmac_f32_e32 v23, 0xbc000000, v20
	v_fmac_f32_e32 v21, v23, v23
	s_nop 1
	v_add_f32_dpp v20, v21, v21 quad_perm:[1,0,3,2] row_mask:0xf bank_mask:0xf bound_ctrl:1
	s_nop 1
	v_add_f32_dpp v20, v20, v20 quad_perm:[2,3,0,1] row_mask:0xf bank_mask:0xf bound_ctrl:1
	s_nop 1
	v_add_f32_dpp v20, v20, v20 row_half_mirror row_mask:0xf bank_mask:0xf bound_ctrl:1
	s_nop 1
	v_add_f32_dpp v20, v20, v20 row_mirror row_mask:0xf bank_mask:0xf bound_ctrl:1
	v_fmamk_f32 v20, v20, 0x3c000000, v212
	v_mul_f32_e32 v21, 0x4b800000, v20
	v_cmp_gt_f32_e32 vcc, s65, v20
	s_nop 1
	v_cndmask_b32_e32 v20, v20, v21, vcc
	v_rsq_f32_e32 v20, v20
	v_fma_f32 v21, v3, v27, v7
	v_cvt_pk_bf16_f32 v27, v41, v21
	ds_write_b128 v40, v[24:27] offset:20480
	v_mul_f32_e32 v21, 0x45800000, v20
	v_cndmask_b32_e32 v24, v20, v21, vcc
	v_mul_f32_e32 v20, v28, v24
	v_mul_f32_e32 v21, v30, v24
	v_fma_f32 v20, v8, v20, v12
	v_fma_f32 v21, v9, v21, v13
	v_cvt_pk_bf16_f32 v20, v20, v21
	v_mul_f32_e32 v21, v32, v24
	v_mul_f32_e32 v22, v22, v24
	v_fma_f32 v21, v10, v21, v14
	v_fma_f32 v22, v11, v22, v15
	v_cvt_pk_bf16_f32 v21, v21, v22
	v_mul_f32_e32 v22, v29, v24
	v_mul_f32_e32 v25, v31, v24
	v_fma_f32 v22, v0, v22, v4
	v_fma_f32 v25, v1, v25, v5
	v_cvt_pk_bf16_f32 v22, v22, v25
	v_mul_f32_e32 v25, v33, v24
	v_fma_f32 v32, v2, v25, v6
	v_mul_f32_e32 v23, v23, v24
	s_waitcnt vmcnt(0)
	v_lshlrev_b32_e32 v25, 16, v18
	v_lshlrev_b32_e32 v24, 16, v16
	v_and_b32_e32 v27, 0xffff0000, v18
	v_and_b32_e32 v26, 0xffff0000, v16
	v_lshlrev_b32_e32 v29, 16, v19
	v_lshlrev_b32_e32 v28, 16, v17
	v_and_b32_e32 v19, 0xffff0000, v19
	v_and_b32_e32 v18, 0xffff0000, v17
	v_pk_add_f32 v[16:17], v[24:25], v[26:27]
	v_pk_add_f32 v[30:31], v[28:29], v[18:19]
	s_nop 0
	v_pk_add_f32 v[16:17], v[16:17], v[30:31]
	s_nop 0
	v_add_f32_e32 v16, v16, v17
	s_nop 1
	v_add_f32_dpp v16, v16, v16 quad_perm:[1,0,3,2] row_mask:0xf bank_mask:0xf bound_ctrl:1
	s_nop 1
	v_add_f32_dpp v16, v16, v16 quad_perm:[2,3,0,1] row_mask:0xf bank_mask:0xf bound_ctrl:1
	s_nop 1
	v_add_f32_dpp v16, v16, v16 row_half_mirror row_mask:0xf bank_mask:0xf bound_ctrl:1
	s_nop 1
	v_add_f32_dpp v16, v16, v16 row_mirror row_mask:0xf bank_mask:0xf bound_ctrl:1
	v_fmac_f32_e32 v24, 0xbc000000, v16
	v_fma_f32 v17, v24, v24, 0
	v_fmac_f32_e32 v26, 0xbc000000, v16
	v_fmac_f32_e32 v17, v26, v26
	v_fmac_f32_e32 v28, 0xbc000000, v16
	v_fmac_f32_e32 v17, v28, v28
	v_fmac_f32_e32 v18, 0xbc000000, v16
	v_fmac_f32_e32 v17, v18, v18
	v_fmac_f32_e32 v25, 0xbc000000, v16
	v_fmac_f32_e32 v17, v25, v25
	v_fmac_f32_e32 v27, 0xbc000000, v16
	v_fmac_f32_e32 v17, v27, v27
	v_fmac_f32_e32 v29, 0xbc000000, v16
	v_fmac_f32_e32 v17, v29, v29
	v_fmac_f32_e32 v19, 0xbc000000, v16
	v_fmac_f32_e32 v17, v19, v19
	s_nop 1
	v_add_f32_dpp v16, v17, v17 quad_perm:[1,0,3,2] row_mask:0xf bank_mask:0xf bound_ctrl:1
	s_nop 1
	v_add_f32_dpp v16, v16, v16 quad_perm:[2,3,0,1] row_mask:0xf bank_mask:0xf bound_ctrl:1
	s_nop 1
	v_add_f32_dpp v16, v16, v16 row_half_mirror row_mask:0xf bank_mask:0xf bound_ctrl:1
	s_nop 1
	v_add_f32_dpp v16, v16, v16 row_mirror row_mask:0xf bank_mask:0xf bound_ctrl:1
	v_fmamk_f32 v16, v16, 0x3c000000, v212
	v_mul_f32_e32 v17, 0x4b800000, v16
	v_cmp_gt_f32_e32 vcc, s65, v16
	s_nop 1
	v_cndmask_b32_e32 v16, v16, v17, vcc
	v_rsq_f32_e32 v16, v16
	v_fma_f32 v17, v3, v23, v7
	v_cvt_pk_bf16_f32 v23, v32, v17
	ds_write_b128 v40, v[20:23] offset:24576
	v_mul_f32_e32 v17, 0x45800000, v16
	v_cndmask_b32_e32 v16, v16, v17, vcc
	v_mul_f32_e32 v17, v24, v16
	v_fma_f32 v8, v8, v17, v12
	v_mul_f32_e32 v12, v26, v16
	v_fma_f32 v9, v9, v12, v13
	v_cvt_pk_bf16_f32 v8, v8, v9
	v_mul_f32_e32 v9, v28, v16
	v_fma_f32 v9, v10, v9, v14
	v_mul_f32_e32 v10, v18, v16
	v_fmac_f32_e32 v15, v11, v10
	v_mul_f32_e32 v10, v25, v16
	v_fma_f32 v0, v0, v10, v4
	v_mul_f32_e32 v4, v27, v16
	v_cvt_pk_bf16_f32 v9, v9, v15
	v_fma_f32 v1, v1, v4, v5
	v_cvt_pk_bf16_f32 v10, v0, v1
	v_mul_f32_e32 v0, v29, v16
	v_fma_f32 v0, v2, v0, v6
	v_mul_f32_e32 v1, v19, v16
	v_fmac_f32_e32 v7, v3, v1
	v_cvt_pk_bf16_f32 v11, v0, v7
	v_lshrrev_b32_e32 v0, 1, v38
	v_and_or_b32 v119, v0, s87, v39
	v_or3_b32 v0, v119, s14, v117
	v_mov_b32_e32 v1, s15
	v_lshlrev_b64 v[0:1], 9, v[0:1]
	v_lshl_add_u64 v[0:1], s[42:43], 0, v[0:1]
	v_and_b32_e32 v2, 32, v36
	v_mov_b32_e32 v3, v193
	ds_write_b128 v40, v[8:11] offset:28672
	v_lshl_add_u64 v[8:9], v[0:1], 0, v[2:3]
	global_load_dwordx4 v[142:145], v[8:9], off
	global_load_dwordx4 v[146:149], v[8:9], off offset:16
	global_load_dwordx4 v[150:153], v[8:9], off offset:64
	global_load_dwordx4 v[154:157], v[8:9], off offset:80
	global_load_dwordx4 v[158:161], v[8:9], off offset:128
	global_load_dwordx4 v[162:165], v[8:9], off offset:144
	global_load_dwordx4 v[166:169], v[8:9], off offset:192
	global_load_dwordx4 v[170:173], v[8:9], off offset:208
	global_load_dwordx4 v[174:177], v[8:9], off offset:256
	global_load_dwordx4 v[178:181], v[8:9], off offset:272
	global_load_dwordx4 v[182:185], v[8:9], off offset:320
	global_load_dwordx4 v[186:189], v[8:9], off offset:336
	global_load_dwordx4 v[194:197], v[8:9], off offset:384
	global_load_dwordx4 v[198:201], v[8:9], off offset:400
	global_load_dwordx4 v[202:205], v[8:9], off offset:448
	global_load_dwordx4 v[206:209], v[8:9], off offset:464
	s_waitcnt lgkmcnt(0)
	s_barrier
; __device__ __forceinline__ float opaque_zero() { float z; asm volatile("v_mov_b32 %0, 0" : "=v"(z)); return z; }
; __device__ __forceinline__ int v_rd_base(int lane) { return ((lane & 3) << 3) | (((lane >> 2) & 3) << 6) | (((lane >> 4) & 1) << 5) | (((lane >> 5) & 1) << 8); }
; __device__ __forceinline__ void gate_pair(const Params& p, int layer, int it, char* lds) {
;     ...
;     bf16x8 bfr[8];
; #pragma unroll
;     for (int s = 0; s < 8; ++s) { const f32x4 a = *(const f32x4*)(swp + s * 16), b = *(const f32x4*)(swp + s * 16 + 4);
;       u32x4 w = {cvtpk(a[0], a[1]), cvtpk(a[2], a[3]), cvtpk(b[0], b[1]), cvtpk(b[2], b[3])}; bfr[s] = *reinterpret_cast<bf16x8*>(&w); }
;     f32x16 acc[4];
;     { const float z0 = opaque_zero();
; #pragma unroll
;       for (int ct = 0; ct < 4; ++ct)
; #pragma unroll
;         for (int r = 0; r < 16; ++r) acc[ct][r] = z0; }
;     const int vnb = (int)(uintptr_t)vnT + v_rd_base(lane);
;     ...
;     GSTEP(0, 0); GSTEP(0, 1); GSTEP(0, 2); GSTEP(0, 3); GSTEP(1, 0); GSTEP(1, 1); GSTEP(1, 2); GSTEP(1, 3);
	s_waitcnt vmcnt(0)
	v_cvt_pk_bf16_f32 v120, v142, v143
	v_cvt_pk_bf16_f32 v121, v144, v145
	v_cvt_pk_bf16_f32 v122, v146, v147
	v_cvt_pk_bf16_f32 v123, v148, v149
	v_cvt_pk_bf16_f32 v124, v150, v151
	v_cvt_pk_bf16_f32 v125, v152, v153
	v_cvt_pk_bf16_f32 v126, v154, v155
	v_cvt_pk_bf16_f32 v127, v156, v157
	v_cvt_pk_bf16_f32 v84, v158, v159
	v_cvt_pk_bf16_f32 v85, v160, v161
	v_cvt_pk_bf16_f32 v86, v162, v163
	v_cvt_pk_bf16_f32 v87, v164, v165
	v_cvt_pk_bf16_f32 v80, v166, v167
	v_cvt_pk_bf16_f32 v81, v168, v169
	v_cvt_pk_bf16_f32 v82, v170, v171
	v_cvt_pk_bf16_f32 v83, v172, v173
	v_cvt_pk_bf16_f32 v76, v174, v175
	v_cvt_pk_bf16_f32 v77, v176, v177
	v_cvt_pk_bf16_f32 v78, v178, v179
	v_cvt_pk_bf16_f32 v79, v180, v181
	v_cvt_pk_bf16_f32 v72, v182, v183
	v_cvt_pk_bf16_f32 v73, v184, v185
	v_cvt_pk_bf16_f32 v74, v186, v187
	v_cvt_pk_bf16_f32 v75, v188, v189
	v_cvt_pk_bf16_f32 v68, v194, v195
	v_cvt_pk_bf16_f32 v69, v196, v197
	v_cvt_pk_bf16_f32 v70, v198, v199
	v_cvt_pk_bf16_f32 v71, v200, v201
	v_and_b32_e32 v16, 63, v36
	v_lshlrev_b32_e32 v16, 3, v16
	v_lshlrev_b32_e32 v19, 4, v36
	v_lshlrev_b32_e32 v20, 1, v36
	v_and_b32_e32 v18, 24, v16
	v_and_b32_e32 v19, 0xc0, v19
	v_and_b32_e32 v20, 32, v20
	v_mul_i32_i24_e32 v17, 0x8800, v37
	v_or3_b32 v18, v18, v19, v20
	v_and_b32_e32 v16, 0x100, v16
	v_cvt_pk_bf16_f32 v64, v202, v203
	v_cvt_pk_bf16_f32 v65, v204, v205
	v_cvt_pk_bf16_f32 v66, v206, v207
	v_cvt_pk_bf16_f32 v67, v208, v209
	v_mov_b32 v0, 0
	v_or3_b32 v141, v18, v16, v17
	ds_read_b64_tr_b16 v[16:17], v141 offset:0
	ds_read_b64_tr_b16 v[18:19], v141 offset:0x800
	ds_read_b64_tr_b16 v[20:21], v141 offset:0x200
	ds_read_b64_tr_b16 v[22:23], v141 offset:0xa00
	ds_read_b64_tr_b16 v[128:129], v141 offset:0x400
	ds_read_b64_tr_b16 v[130:131], v141 offset:0xc00
	ds_read_b64_tr_b16 v[132:133], v141 offset:0x600
	ds_read_b64_tr_b16 v[134:135], v141 offset:0xe00
	s_waitcnt lgkmcnt(0)
	v_mov_b32_e32 v1, v0
	v_mov_b32_e32 v2, v0
	v_mov_b32_e32 v3, v0
	v_mov_b32_e32 v4, v0
	v_mov_b32_e32 v5, v0
	v_mov_b32_e32 v6, v0
	v_mov_b32_e32 v7, v0
	v_mov_b32_e32 v8, v0
	v_mov_b32_e32 v9, v0
	v_mov_b32_e32 v10, v0
	v_mov_b32_e32 v11, v0
	v_mov_b32_e32 v12, v0
	v_mov_b32_e32 v13, v0
	v_mov_b32_e32 v14, v0
	v_mov_b32_e32 v15, v0
	s_nop 1
	v_mfma_f32_32x32x16_bf16 v[48:63], v[16:19], v[120:123], v[0:15]
	v_mfma_f32_32x32x16_bf16 v[32:47], v[20:23], v[120:123], v[0:15]
	v_mfma_f32_32x32x16_bf16 v[16:31], v[128:131], v[120:123], v[0:15]
	v_mfma_f32_32x32x16_bf16 v[0:15], v[132:135], v[120:123], v[0:15]
	ds_read_b64_tr_b16 v[120:121], v141 offset:0x1000
	ds_read_b64_tr_b16 v[122:123], v141 offset:0x1800
	ds_read_b64_tr_b16 v[128:129], v141 offset:0x1200
	ds_read_b64_tr_b16 v[130:131], v141 offset:0x1a00
	ds_read_b64_tr_b16 v[132:133], v141 offset:0x1400
	ds_read_b64_tr_b16 v[134:135], v141 offset:0x1c00
	ds_read_b64_tr_b16 v[136:137], v141 offset:0x1600
	ds_read_b64_tr_b16 v[138:139], v141 offset:0x1e00
	s_waitcnt lgkmcnt(0)
	s_nop 0
	v_mfma_f32_32x32x16_bf16 v[48:63], v[120:123], v[124:127], v[48:63]
	ds_read_b64_tr_b16 v[120:121], v141 offset:0x2000
	ds_read_b64_tr_b16 v[122:123], v141 offset:0x2800
	v_mfma_f32_32x32x16_bf16 v[32:47], v[128:131], v[124:127], v[32:47]
	v_mfma_f32_32x32x16_bf16 v[16:31], v[132:135], v[124:127], v[16:31]
	v_mfma_f32_32x32x16_bf16 v[0:15], v[136:139], v[124:127], v[0:15]
	ds_read_b64_tr_b16 v[124:125], v141 offset:0x2200
	ds_read_b64_tr_b16 v[126:127], v141 offset:0x2a00
	ds_read_b64_tr_b16 v[128:129], v141 offset:0x2400
	ds_read_b64_tr_b16 v[130:131], v141 offset:0x2c00
	ds_read_b64_tr_b16 v[132:133], v141 offset:0x2600
	ds_read_b64_tr_b16 v[134:135], v141 offset:0x2e00
	s_waitcnt lgkmcnt(0)
	v_mfma_f32_32x32x16_bf16 v[48:63], v[120:123], v[84:87], v[48:63]
	v_mfma_f32_32x32x16_bf16 v[32:47], v[124:127], v[84:87], v[32:47]
	v_mfma_f32_32x32x16_bf16 v[16:31], v[128:131], v[84:87], v[16:31]
	v_mfma_f32_32x32x16_bf16 v[0:15], v[132:135], v[84:87], v[0:15]
	ds_read_b64_tr_b16 v[84:85], v141 offset:0x3000
	ds_read_b64_tr_b16 v[86:87], v141 offset:0x3800
	ds_read_b64_tr_b16 v[120:121], v141 offset:0x3200
	ds_read_b64_tr_b16 v[122:123], v141 offset:0x3a00
	ds_read_b64_tr_b16 v[124:125], v141 offset:0x3400
	ds_read_b64_tr_b16 v[126:127], v141 offset:0x3c00
	ds_read_b64_tr_b16 v[128:129], v141 offset:0x3600
	ds_read_b64_tr_b16 v[130:131], v141 offset:0x3e00
	s_waitcnt lgkmcnt(0)
	s_nop 0
	v_mfma_f32_32x32x16_bf16 v[48:63], v[84:87], v[80:83], v[48:63]
	v_mfma_f32_32x32x16_bf16 v[32:47], v[120:123], v[80:83], v[32:47]
	v_mfma_f32_32x32x16_bf16 v[16:31], v[124:127], v[80:83], v[16:31]
	v_mfma_f32_32x32x16_bf16 v[0:15], v[128:131], v[80:83], v[0:15]
	v_add_u32_e32 v128, 0x4000, v141
	ds_read_b64_tr_b16 v[80:81], v128 offset:0
	ds_read_b64_tr_b16 v[82:83], v128 offset:0x800
	ds_read_b64_tr_b16 v[84:85], v128 offset:0x200
	ds_read_b64_tr_b16 v[86:87], v128 offset:0xa00
	ds_read_b64_tr_b16 v[120:121], v128 offset:0x400
	ds_read_b64_tr_b16 v[122:123], v128 offset:0xc00
	ds_read_b64_tr_b16 v[124:125], v128 offset:0x600
	ds_read_b64_tr_b16 v[126:127], v128 offset:0xe00
	s_waitcnt lgkmcnt(0)
	s_nop 0
	v_mfma_f32_32x32x16_bf16 v[48:63], v[80:83], v[76:79], v[48:63]
	v_mfma_f32_32x32x16_bf16 v[32:47], v[84:87], v[76:79], v[32:47]
	v_mfma_f32_32x32x16_bf16 v[16:31], v[120:123], v[76:79], v[16:31]
	v_mfma_f32_32x32x16_bf16 v[0:15], v[124:127], v[76:79], v[0:15]
	ds_read_b64_tr_b16 v[76:77], v128 offset:0x1000
	ds_read_b64_tr_b16 v[78:79], v128 offset:0x1800
	ds_read_b64_tr_b16 v[80:81], v128 offset:0x1200
	ds_read_b64_tr_b16 v[82:83], v128 offset:0x1a00
	ds_read_b64_tr_b16 v[84:85], v128 offset:0x1400
	ds_read_b64_tr_b16 v[86:87], v128 offset:0x1c00
	ds_read_b64_tr_b16 v[120:121], v128 offset:0x1600
	ds_read_b64_tr_b16 v[122:123], v128 offset:0x1e00
	s_waitcnt lgkmcnt(0)
; __device__ __forceinline__ float bflo(unsigned w) { return __uint_as_float(w << 16); }
; __device__ __forceinline__ float bfhi(unsigned w) { return __uint_as_float(w & 0xffff0000u); }
; __device__ __forceinline__ void gate_pair(const Params& p, int layer, int it, char* lds) {
;     ...
;     GSTEP(0, 0); GSTEP(0, 1); GSTEP(0, 2); GSTEP(0, 3); GSTEP(1, 0); GSTEP(1, 1); GSTEP(1, 2); GSTEP(1, 3);
;     ...
;     const float sbv = p.sb[(layer * 8 + g) * 128 + p0 + r32];
;     bf16_t* grow = gul + (p0 + r32) * 132 + 4 * hi;
;     float ss = 0.f;
; #pragma unroll
;     for (int ct = 0; ct < 4; ++ct)
; #pragma unroll
;       for (int rq = 0; rq < 4; ++rq) { const u32x2 gw = *(const u32x2*)(grow + ct * 32 + 8 * rq);
;         const float g0 = bflo(gw[0]), g1 = bfhi(gw[0]), g2 = bflo(gw[1]), g3 = bfhi(gw[1]);
;         float y0 = g0 * (acc[ct][rq * 4 + 0] + sbv), y1 = g1 * (acc[ct][rq * 4 + 1] + sbv), y2 = g2 * (acc[ct][rq * 4 + 2] + sbv), y3 = g3 * (acc[ct][rq * 4 + 3] + sbv);
;         acc[ct][rq * 4 + 0] = y0; acc[ct][rq * 4 + 1] = y1; acc[ct][rq * 4 + 2] = y2; acc[ct][rq * 4 + 3] = y3;
;         ss += y0 * y0 + y1 * y1 + y2 * y2 + y3 * y3; }
	s_nop 0
	v_mfma_f32_32x32x16_bf16 v[48:63], v[76:79], v[72:75], v[48:63]
	v_mfma_f32_32x32x16_bf16 v[32:47], v[80:83], v[72:75], v[32:47]
	v_mfma_f32_32x32x16_bf16 v[16:31], v[84:87], v[72:75], v[16:31]
	v_mfma_f32_32x32x16_bf16 v[0:15], v[120:123], v[72:75], v[0:15]
	ds_read_b64_tr_b16 v[72:73], v128 offset:0x2000
	ds_read_b64_tr_b16 v[74:75], v128 offset:0x2800
	ds_read_b64_tr_b16 v[76:77], v128 offset:0x2200
	ds_read_b64_tr_b16 v[78:79], v128 offset:0x2a00
	ds_read_b64_tr_b16 v[80:81], v128 offset:0x2400
	ds_read_b64_tr_b16 v[82:83], v128 offset:0x2c00
	ds_read_b64_tr_b16 v[84:85], v128 offset:0x2600
	ds_read_b64_tr_b16 v[86:87], v128 offset:0x2e00
	s_waitcnt lgkmcnt(0)
	s_nop 0
	v_mfma_f32_32x32x16_bf16 v[48:63], v[72:75], v[68:71], v[48:63]
	v_mfma_f32_32x32x16_bf16 v[32:47], v[76:79], v[68:71], v[32:47]
	v_mfma_f32_32x32x16_bf16 v[16:31], v[80:83], v[68:71], v[16:31]
	v_mfma_f32_32x32x16_bf16 v[0:15], v[84:87], v[68:71], v[0:15]
	ds_read_b64_tr_b16 v[68:69], v128 offset:0x3000
	ds_read_b64_tr_b16 v[70:71], v128 offset:0x3800
	ds_read_b64_tr_b16 v[72:73], v128 offset:0x3200
	ds_read_b64_tr_b16 v[74:75], v128 offset:0x3a00
	ds_read_b64_tr_b16 v[76:77], v128 offset:0x3400
	ds_read_b64_tr_b16 v[78:79], v128 offset:0x3c00
	ds_read_b64_tr_b16 v[80:81], v128 offset:0x3600
	ds_read_b64_tr_b16 v[82:83], v128 offset:0x3e00
	s_waitcnt lgkmcnt(0)
	s_nop 0
	v_mfma_f32_32x32x16_bf16 v[48:63], v[68:71], v[64:67], v[48:63]
	v_mfma_f32_32x32x16_bf16 v[32:47], v[72:75], v[64:67], v[32:47]
	v_mfma_f32_32x32x16_bf16 v[16:31], v[76:79], v[64:67], v[16:31]
	v_mfma_f32_32x32x16_bf16 v[0:15], v[80:83], v[64:67], v[0:15]
	v_or3_b32 v64, v119, s4, v117
	v_ashrrev_i32_e32 v65, 31, v64
	v_lshl_add_u64 v[64:65], v[64:65], 2, s[44:45]
	global_load_dword v64, v[64:65], off
	v_mul_u32_u24_e32 v65, 0x108, v119
	v_add3_u32 v65, v118, v65, v140
	ds_read2_b64 v[66:69], v65 offset1:2
	ds_read2_b64 v[76:79], v65 offset0:4 offset1:6
	s_waitcnt lgkmcnt(1)
	v_lshlrev_b32_e32 v70, 16, v66
	v_and_b32_e32 v66, 0xffff0000, v66
	v_lshlrev_b32_e32 v71, 16, v67
	v_and_b32_e32 v67, 0xffff0000, v67
	s_waitcnt vmcnt(0)
	v_add_f32_e32 v48, v48, v64
	v_mul_f32_e32 v74, v48, v70
	v_add_f32_e32 v48, v49, v64
	v_lshlrev_b32_e32 v49, 16, v68
	v_add_f32_e32 v52, v52, v64
	v_mul_f32_e32 v75, v48, v66
	v_add_f32_e32 v48, v50, v64
	v_and_b32_e32 v50, 0xffff0000, v68
	v_mul_f32_e32 v70, v52, v49
	v_add_f32_e32 v49, v53, v64
	v_mul_f32_e32 v72, v48, v71
	v_add_f32_e32 v48, v51, v64
	v_lshlrev_b32_e32 v51, 16, v69
	v_mul_f32_e32 v71, v49, v50
	v_add_f32_e32 v49, v54, v64
	v_and_b32_e32 v66, 0xffff0000, v69
	v_mul_f32_e32 v68, v49, v51
	v_add_f32_e32 v49, v55, v64
	v_mul_f32_e32 v73, v48, v67
	v_mul_f32_e32 v48, v75, v75
	v_mul_f32_e32 v69, v49, v66
	v_mul_f32_e32 v49, v71, v71
	v_fmac_f32_e32 v48, v74, v74
	v_fmac_f32_e32 v49, v70, v70
	v_fmac_f32_e32 v48, v72, v72
	v_fmac_f32_e32 v49, v68, v68
	v_fmac_f32_e32 v48, v73, v73
	v_fmac_f32_e32 v49, v69, v69
	v_add_f32_e32 v48, v48, v49
	s_waitcnt lgkmcnt(0)
	v_lshlrev_b32_e32 v49, 16, v76
	v_add_f32_e32 v53, v56, v64
	v_and_b32_e32 v50, 0xffff0000, v76
	v_mul_f32_e32 v66, v53, v49
	v_add_f32_e32 v49, v57, v64
	v_lshlrev_b32_e32 v51, 16, v77
	v_mul_f32_e32 v67, v49, v50
	v_add_f32_e32 v49, v58, v64
	v_and_b32_e32 v52, 0xffff0000, v77
	v_mul_f32_e32 v55, v49, v51
	v_add_f32_e32 v49, v59, v64
	v_mul_f32_e32 v56, v49, v52
	v_mul_f32_e32 v49, v67, v67
	v_fmac_f32_e32 v49, v66, v66
	v_fmac_f32_e32 v49, v55, v55
	v_fmac_f32_e32 v49, v56, v56
	v_add_f32_e32 v48, v48, v49
	v_lshlrev_b32_e32 v49, 16, v78
	v_add_f32_e32 v53, v60, v64
	v_and_b32_e32 v50, 0xffff0000, v78
	v_mul_f32_e32 v57, v53, v49
	v_add_f32_e32 v49, v61, v64
	v_lshlrev_b32_e32 v51, 16, v79
	v_mul_f32_e32 v54, v49, v50
	v_add_f32_e32 v49, v62, v64
	v_and_b32_e32 v52, 0xffff0000, v79
	v_mul_f32_e32 v53, v49, v51
	v_add_f32_e32 v49, v63, v64
	v_mul_f32_e32 v52, v49, v52
	v_mul_f32_e32 v49, v54, v54
	v_fmac_f32_e32 v49, v57, v57
	v_fmac_f32_e32 v49, v53, v53
	v_fmac_f32_e32 v49, v52, v52
	v_add_f32_e32 v60, v48, v49
	ds_read2_b64 v[48:51], v65 offset0:8 offset1:10
	v_add_f32_e32 v32, v32, v64
	v_add_f32_e32 v36, v36, v64
	v_add_f32_e32 v16, v16, v64
	v_add_f32_e32 v20, v20, v64
	s_waitcnt lgkmcnt(0)
	v_lshlrev_b32_e32 v58, 16, v48
	v_and_b32_e32 v48, 0xffff0000, v48
	v_lshlrev_b32_e32 v59, 16, v49
	v_and_b32_e32 v61, 0xffff0000, v49
	v_mul_f32_e32 v49, v32, v58
	v_add_f32_e32 v32, v33, v64
	v_lshlrev_b32_e32 v33, 16, v50
	v_mul_f32_e32 v58, v32, v48
	v_add_f32_e32 v32, v34, v64
	v_and_b32_e32 v34, 0xffff0000, v50
	v_mul_f32_e32 v77, v36, v33
	v_add_f32_e32 v33, v37, v64
	v_mul_f32_e32 v48, v32, v59
	v_add_f32_e32 v32, v35, v64
	v_lshlrev_b32_e32 v35, 16, v51
	v_mul_f32_e32 v63, v33, v34
	v_add_f32_e32 v33, v38, v64
	v_mul_f32_e32 v59, v32, v61
	v_mul_f32_e32 v32, v58, v58
	v_and_b32_e32 v50, 0xffff0000, v51
	v_mul_f32_e32 v61, v33, v35
	v_add_f32_e32 v33, v39, v64
	v_fmac_f32_e32 v32, v49, v49
	v_mul_f32_e32 v51, v33, v50
	v_mul_f32_e32 v33, v63, v63
	v_fmac_f32_e32 v32, v48, v48
	v_fmac_f32_e32 v33, v77, v77
	v_fmac_f32_e32 v32, v59, v59
	v_fmac_f32_e32 v33, v61, v61
	v_add_f32_e32 v32, v60, v32
	v_fmac_f32_e32 v33, v51, v51
	v_add_f32_e32 v36, v32, v33
	ds_read2_b64 v[32:35], v65 offset0:12 offset1:14
	v_add_f32_e32 v39, v40, v64
	s_waitcnt lgkmcnt(0)
; __device__ __forceinline__ float bflo(unsigned w) { return __uint_as_float(w << 16); }
; __device__ __forceinline__ float bfhi(unsigned w) { return __uint_as_float(w & 0xffff0000u); }
; __device__ __forceinline__ float xor32_sum(float x) { auto r = __builtin_amdgcn_permlane32_swap(__float_as_uint(x), __float_as_uint(x), false, false); return __uint_as_float(r[0]) + __uint_as_float(r[1]); }
; __device__ __forceinline__ void gate_pair(const Params& p, int layer, int it, char* lds) {
;     ...
;     for (int ct = 0; ct < 4; ++ct)
; #pragma unroll
;       for (int rq = 0; rq < 4; ++rq) { const u32x2 gw = *(const u32x2*)(grow + ct * 32 + 8 * rq);
;         const float g0 = bflo(gw[0]), g1 = bfhi(gw[0]), g2 = bflo(gw[1]), g3 = bfhi(gw[1]);
;         float y0 = g0 * (acc[ct][rq * 4 + 0] + sbv), y1 = g1 * (acc[ct][rq * 4 + 1] + sbv), y2 = g2 * (acc[ct][rq * 4 + 2] + sbv), y3 = g3 * (acc[ct][rq * 4 + 3] + sbv);
;         acc[ct][rq * 4 + 0] = y0; acc[ct][rq * 4 + 1] = y1; acc[ct][rq * 4 + 2] = y2; acc[ct][rq * 4 + 3] = y3;
;         ss += y0 * y0 + y1 * y1 + y2 * y2 + y3 * y3; }
;     ss = xor32_sum(ss);
;     const float rn = rsqrtf(ss * (1.f / 128.f) + EPS);
; #pragma unroll
;     for (int ct = 0; ct < 4; ++ct)
; #pragma unroll
;       for (int rq = 0; rq < 4; ++rq) { const int c0 = ct * 32 + 8 * rq + 4 * hi; const f32x4 gn = *(const f32x4*)(p.gon + layer * 1024 + g * 128 + c0);
;         const u32x2 w = {cvtpk(acc[ct][rq * 4 + 0] * rn * gn[0], acc[ct][rq * 4 + 1] * rn * gn[1]), cvtpk(acc[ct][rq * 4 + 2] * rn * gn[2], acc[ct][rq * 4 + 3] * rn * gn[3])};
	v_lshlrev_b32_e32 v37, 16, v32
	v_and_b32_e32 v32, 0xffff0000, v32
	v_mul_f32_e32 v78, v39, v37
	v_add_f32_e32 v37, v41, v64
	v_lshlrev_b32_e32 v38, 16, v33
	v_mul_f32_e32 v76, v37, v32
	v_add_f32_e32 v32, v42, v64
	v_and_b32_e32 v33, 0xffff0000, v33
	v_mul_f32_e32 v62, v32, v38
	v_add_f32_e32 v32, v43, v64
	v_mul_f32_e32 v60, v32, v33
	v_mul_f32_e32 v32, v76, v76
	v_fmac_f32_e32 v32, v78, v78
	v_fmac_f32_e32 v32, v62, v62
	v_lshlrev_b32_e32 v33, 16, v34
	v_add_f32_e32 v37, v44, v64
	v_fmac_f32_e32 v32, v60, v60
	v_and_b32_e32 v34, 0xffff0000, v34
	v_mul_f32_e32 v50, v37, v33
	v_add_f32_e32 v33, v45, v64
	v_add_f32_e32 v32, v36, v32
	v_lshlrev_b32_e32 v36, 16, v35
	v_mul_f32_e32 v44, v33, v34
	v_add_f32_e32 v33, v46, v64
	v_and_b32_e32 v35, 0xffff0000, v35
	v_mul_f32_e32 v42, v33, v36
	v_add_f32_e32 v33, v47, v64
	v_mul_f32_e32 v40, v33, v35
	v_mul_f32_e32 v33, v44, v44
	v_fmac_f32_e32 v33, v50, v50
	v_fmac_f32_e32 v33, v42, v42
	v_fmac_f32_e32 v33, v40, v40
	v_add_f32_e32 v36, v32, v33
	ds_read2_b64 v[32:35], v65 offset0:16 offset1:18
	s_waitcnt lgkmcnt(0)
	v_lshlrev_b32_e32 v37, 16, v32
	v_and_b32_e32 v32, 0xffff0000, v32
	v_mul_f32_e32 v46, v16, v37
	v_add_f32_e32 v16, v17, v64
	v_lshlrev_b32_e32 v38, 16, v33
	v_mul_f32_e32 v45, v16, v32
	v_add_f32_e32 v16, v18, v64
	v_and_b32_e32 v33, 0xffff0000, v33
	v_mul_f32_e32 v43, v16, v38
	v_add_f32_e32 v16, v19, v64
	v_mul_f32_e32 v41, v16, v33
	v_mul_f32_e32 v16, v45, v45
	v_lshlrev_b32_e32 v17, 16, v34
	v_fmac_f32_e32 v16, v46, v46
	v_and_b32_e32 v18, 0xffff0000, v34
	v_mul_f32_e32 v39, v20, v17
	v_add_f32_e32 v17, v21, v64
	v_fmac_f32_e32 v16, v43, v43
	v_lshlrev_b32_e32 v19, 16, v35
	v_mul_f32_e32 v38, v17, v18
	v_add_f32_e32 v17, v22, v64
	v_fmac_f32_e32 v16, v41, v41
	v_and_b32_e32 v32, 0xffff0000, v35
	v_mul_f32_e32 v37, v17, v19
	v_add_f32_e32 v17, v23, v64
	v_add_f32_e32 v16, v36, v16
	v_mul_f32_e32 v36, v17, v32
	v_mul_f32_e32 v17, v38, v38
	v_fmac_f32_e32 v17, v39, v39
	v_fmac_f32_e32 v17, v37, v37
	v_fmac_f32_e32 v17, v36, v36
	v_add_f32_e32 v47, v16, v17
	ds_read2_b64 v[16:19], v65 offset0:20 offset1:22
	s_waitcnt lgkmcnt(0)
	v_lshlrev_b32_e32 v21, 16, v18
	v_lshlrev_b32_e32 v20, 16, v16
	v_and_b32_e32 v23, 0xffff0000, v18
	v_and_b32_e32 v22, 0xffff0000, v16
	v_lshlrev_b32_e32 v80, 16, v17
	v_and_b32_e32 v18, 0xffff0000, v17
	v_mov_b32_e32 v16, v24
	v_mov_b32_e32 v17, v28
	v_pk_add_f32 v[16:17], v[16:17], v[64:65] op_sel_hi:[1,0]
	v_mov_b32_e32 v28, v25
	v_pk_mul_f32 v[34:35], v[16:17], v[20:21]
	v_pk_add_f32 v[16:17], v[28:29], v[64:65] op_sel_hi:[1,0]
	v_lshlrev_b32_e32 v81, 16, v19
	v_pk_mul_f32 v[32:33], v[16:17], v[22:23]
	v_mov_b32_e32 v16, v26
	v_mov_b32_e32 v17, v30
	v_pk_add_f32 v[16:17], v[16:17], v[64:65] op_sel_hi:[1,0]
	v_mov_b32_e32 v30, v27
	v_and_b32_e32 v19, 0xffff0000, v19
	v_pk_mul_f32 v[28:29], v[16:17], v[80:81]
	v_pk_add_f32 v[16:17], v[30:31], v[64:65] op_sel_hi:[1,0]
	s_nop 0
	v_pk_mul_f32 v[24:25], v[16:17], v[18:19]
	v_pk_mul_f32 v[16:17], v[32:33], v[32:33]
	s_nop 0
	v_pk_fma_f32 v[16:17], v[34:35], v[34:35], v[16:17]
	s_nop 0
	v_pk_fma_f32 v[16:17], v[28:29], v[28:29], v[16:17]
	s_nop 0
	v_pk_fma_f32 v[16:17], v[24:25], v[24:25], v[16:17]
	s_nop 0
	v_add_f32_e32 v16, v47, v16
	v_add_f32_e32 v47, v16, v17
	ds_read2_b64 v[16:19], v65 offset0:24 offset1:26
	s_waitcnt lgkmcnt(0)
	v_lshlrev_b32_e32 v20, 16, v16
	v_and_b32_e32 v26, 0xffff0000, v16
	v_lshlrev_b32_e32 v30, 16, v17
	v_and_b32_e32 v80, 0xffff0000, v17
	v_mov_b32_e32 v16, v0
	v_mov_b32_e32 v17, v4
	v_mov_b32_e32 v4, v1
	v_lshlrev_b32_e32 v21, 16, v18
	v_and_b32_e32 v27, 0xffff0000, v18
	v_pk_add_f32 v[16:17], v[16:17], v[64:65] op_sel_hi:[1,0]
	v_pk_add_f32 v[0:1], v[4:5], v[64:65] op_sel_hi:[1,0]
	v_pk_mul_f32 v[22:23], v[16:17], v[20:21]
	v_pk_mul_f32 v[20:21], v[0:1], v[26:27]
	v_mov_b32_e32 v0, v2
	v_mov_b32_e32 v1, v6
	v_lshlrev_b32_e32 v31, 16, v19
	v_pk_add_f32 v[0:1], v[0:1], v[64:65] op_sel_hi:[1,0]
	v_mov_b32_e32 v6, v3
	v_and_b32_e32 v81, 0xffff0000, v19
	v_pk_mul_f32 v[18:19], v[0:1], v[30:31]
	v_pk_add_f32 v[0:1], v[6:7], v[64:65] op_sel_hi:[1,0]
	s_nop 0
	v_pk_mul_f32 v[16:17], v[0:1], v[80:81]
	v_pk_mul_f32 v[0:1], v[20:21], v[20:21]
	s_nop 0
	v_pk_fma_f32 v[0:1], v[22:23], v[22:23], v[0:1]
	s_nop 0
	v_pk_fma_f32 v[0:1], v[18:19], v[18:19], v[0:1]
	s_nop 0
	v_pk_fma_f32 v[0:1], v[16:17], v[16:17], v[0:1]
	s_nop 0
	v_add_f32_e32 v0, v47, v0
	v_add_f32_e32 v30, v0, v1
	ds_read2_b64 v[0:3], v65 offset0:28 offset1:30
	s_waitcnt lgkmcnt(0)
	v_lshlrev_b32_e32 v5, 16, v2
	v_lshlrev_b32_e32 v4, 16, v0
	v_and_b32_e32 v7, 0xffff0000, v2
	v_and_b32_e32 v6, 0xffff0000, v0
	v_lshlrev_b32_e32 v26, 16, v1
	v_and_b32_e32 v2, 0xffff0000, v1
	v_mov_b32_e32 v0, v8
	v_mov_b32_e32 v1, v12
	v_pk_add_f32 v[0:1], v[0:1], v[64:65] op_sel_hi:[1,0]
	v_mov_b32_e32 v12, v9
	v_pk_mul_f32 v[4:5], v[0:1], v[4:5]
	v_pk_add_f32 v[0:1], v[12:13], v[64:65] op_sel_hi:[1,0]
	v_lshlrev_b32_e32 v27, 16, v3
	v_pk_mul_f32 v[6:7], v[0:1], v[6:7]
	v_mov_b32_e32 v0, v10
	v_mov_b32_e32 v1, v14
	v_pk_add_f32 v[0:1], v[0:1], v[64:65] op_sel_hi:[1,0]
	v_mov_b32_e32 v14, v11
	v_and_b32_e32 v3, 0xffff0000, v3
	v_pk_mul_f32 v[8:9], v[0:1], v[26:27]
	v_pk_add_f32 v[0:1], v[14:15], v[64:65] op_sel_hi:[1,0]
	s_nop 0
	v_pk_mul_f32 v[10:11], v[0:1], v[2:3]
	v_pk_mul_f32 v[0:1], v[6:7], v[6:7]
	v_lshlrev_b32_e32 v2, 4, v116
	v_pk_fma_f32 v[0:1], v[4:5], v[4:5], v[0:1]
	v_mov_b32_e32 v3, v193
	v_pk_fma_f32 v[0:1], v[8:9], v[8:9], v[0:1]
	s_nop 0
	v_pk_fma_f32 v[0:1], v[10:11], v[10:11], v[0:1]
	s_nop 0
	v_add_f32_e32 v0, v30, v0
	v_add_f32_e32 v0, v0, v1
	v_mov_b32_e32 v1, v0
	s_nop 1
	v_permlane32_swap_b32_e32 v0, v1
	v_add_f32_e32 v0, v0, v1
	v_fmamk_f32 v0, v0, 0x3c000000, v212
	v_cmp_gt_f32_e32 vcc, s65, v0
	v_mul_f32_e32 v1, 0x4b800000, v0
	s_nop 0
	v_cndmask_b32_e32 v0, v0, v1, vcc
	v_rsq_f32_e32 v0, v0
	s_nop 0
	v_mul_f32_e32 v1, 0x45800000, v0
	v_cndmask_b32_e32 v14, v0, v1, vcc
	v_lshl_add_u64 v[0:1], s[12:13], 0, v[106:107]
	v_lshl_add_u64 v[12:13], v[0:1], 0, v[2:3]
	global_load_dwordx4 v[0:3], v[12:13], off
	v_mul_f32_e32 v15, v74, v14
	v_mul_f32_e32 v4, v4, v14
	s_waitcnt vmcnt(0)
; __device__ __forceinline__ void gate_pair(const Params& p, int layer, int it, char* lds) {
;     ...
; #pragma unroll
;     for (int ct = 0; ct < 4; ++ct)
; #pragma unroll
;       for (int rq = 0; rq < 4; ++rq) { const int c0 = ct * 32 + 8 * rq + 4 * hi; const f32x4 gn = *(const f32x4*)(p.gon + layer * 1024 + g * 128 + c0);
;         const u32x2 w = {cvtpk(acc[ct][rq * 4 + 0] * rn * gn[0], acc[ct][rq * 4 + 1] * rn * gn[1]), cvtpk(acc[ct][rq * 4 + 2] * rn * gn[2], acc[ct][rq * 4 + 3] * rn * gn[3])};
;         *(u32x2*)(grow + ct * 32 + 8 * rq) = w; }
;   }
;   __syncthreads();
	v_mul_f32_e32 v0, v0, v15
	v_mul_f32_e32 v15, v75, v14
	v_mul_f32_e32 v1, v1, v15
	v_cvt_pk_bf16_f32 v0, v0, v1
	v_mul_f32_e32 v1, v72, v14
	v_mul_f32_e32 v1, v2, v1
	v_mul_f32_e32 v2, v73, v14
	v_mul_f32_e32 v2, v3, v2
	v_cvt_pk_bf16_f32 v1, v1, v2
	ds_write_b64 v65, v[0:1]
	global_load_dwordx4 v[0:3], v[12:13], off offset:32
	v_mul_f32_e32 v15, v70, v14
	s_waitcnt vmcnt(0)
	v_mul_f32_e32 v0, v0, v15
	v_mul_f32_e32 v15, v71, v14
	v_mul_f32_e32 v1, v1, v15
	v_cvt_pk_bf16_f32 v0, v0, v1
	v_mul_f32_e32 v1, v68, v14
	v_mul_f32_e32 v1, v2, v1
	v_mul_f32_e32 v2, v69, v14
	v_mul_f32_e32 v2, v3, v2
	v_cvt_pk_bf16_f32 v1, v1, v2
	ds_write_b64 v65, v[0:1] offset:16
	global_load_dwordx4 v[0:3], v[12:13], off offset:64
	v_mul_f32_e32 v15, v66, v14
	s_waitcnt vmcnt(0)
	v_mul_f32_e32 v0, v0, v15
	v_mul_f32_e32 v15, v67, v14
	v_mul_f32_e32 v1, v1, v15
	v_cvt_pk_bf16_f32 v0, v0, v1
	v_mul_f32_e32 v1, v55, v14
	v_mul_f32_e32 v1, v2, v1
	v_mul_f32_e32 v2, v56, v14
	v_mul_f32_e32 v2, v3, v2
	v_cvt_pk_bf16_f32 v1, v1, v2
	ds_write_b64 v65, v[0:1] offset:32
	global_load_dwordx4 v[0:3], v[12:13], off offset:96
	v_mul_f32_e32 v15, v57, v14
	s_waitcnt vmcnt(0)
	v_mul_f32_e32 v0, v15, v0
	v_mul_f32_e32 v15, v54, v14
	v_mul_f32_e32 v1, v15, v1
	v_cvt_pk_bf16_f32 v0, v0, v1
	v_mul_f32_e32 v1, v53, v14
	v_mul_f32_e32 v1, v1, v2
	v_mul_f32_e32 v2, v52, v14
	v_mul_f32_e32 v2, v2, v3
	v_cvt_pk_bf16_f32 v1, v1, v2
	ds_write_b64 v65, v[0:1] offset:48
	global_load_dwordx4 v[0:3], v[12:13], off offset:128
	v_mul_f32_e32 v15, v49, v14
	s_waitcnt vmcnt(0)
	v_mul_f32_e32 v0, v15, v0
	v_mul_f32_e32 v15, v58, v14
	v_mul_f32_e32 v1, v15, v1
	v_cvt_pk_bf16_f32 v0, v0, v1
	v_mul_f32_e32 v1, v48, v14
	v_mul_f32_e32 v1, v1, v2
	v_mul_f32_e32 v2, v59, v14
	v_mul_f32_e32 v2, v2, v3
	v_cvt_pk_bf16_f32 v1, v1, v2
	ds_write_b64 v65, v[0:1] offset:64
	global_load_dwordx4 v[0:3], v[12:13], off offset:160
	v_mul_f32_e32 v15, v77, v14
	s_waitcnt vmcnt(0)
	v_mul_f32_e32 v0, v15, v0
	v_mul_f32_e32 v15, v63, v14
	v_mul_f32_e32 v1, v15, v1
	v_cvt_pk_bf16_f32 v0, v0, v1
	v_mul_f32_e32 v1, v61, v14
	v_mul_f32_e32 v1, v1, v2
	v_mul_f32_e32 v2, v51, v14
	v_mul_f32_e32 v2, v2, v3
	v_cvt_pk_bf16_f32 v1, v1, v2
	ds_write_b64 v65, v[0:1] offset:80
	global_load_dwordx4 v[0:3], v[12:13], off offset:192
	v_mul_f32_e32 v15, v78, v14
	s_waitcnt vmcnt(0)
	v_mul_f32_e32 v0, v15, v0
	v_mul_f32_e32 v15, v76, v14
	v_mul_f32_e32 v1, v15, v1
	v_cvt_pk_bf16_f32 v0, v0, v1
	v_mul_f32_e32 v1, v62, v14
	v_mul_f32_e32 v1, v1, v2
	v_mul_f32_e32 v2, v60, v14
	v_mul_f32_e32 v2, v2, v3
	v_cvt_pk_bf16_f32 v1, v1, v2
	ds_write_b64 v65, v[0:1] offset:96
	global_load_dwordx4 v[0:3], v[12:13], off offset:224
	v_mul_f32_e32 v15, v50, v14
	s_waitcnt vmcnt(0)
	v_mul_f32_e32 v0, v15, v0
	v_mul_f32_e32 v15, v44, v14
	v_mul_f32_e32 v1, v15, v1
	v_cvt_pk_bf16_f32 v0, v0, v1
	v_mul_f32_e32 v1, v42, v14
	v_mul_f32_e32 v1, v1, v2
	v_mul_f32_e32 v2, v40, v14
	v_mul_f32_e32 v2, v2, v3
	v_cvt_pk_bf16_f32 v1, v1, v2
	ds_write_b64 v65, v[0:1] offset:112
	global_load_dwordx4 v[0:3], v[12:13], off offset:256
	v_mul_f32_e32 v15, v46, v14
	s_waitcnt vmcnt(0)
	v_mul_f32_e32 v0, v15, v0
	v_mul_f32_e32 v15, v45, v14
	v_mul_f32_e32 v1, v15, v1
	v_cvt_pk_bf16_f32 v0, v0, v1
	v_mul_f32_e32 v1, v43, v14
	v_mul_f32_e32 v1, v1, v2
	v_mul_f32_e32 v2, v41, v14
	v_mul_f32_e32 v2, v2, v3
	v_cvt_pk_bf16_f32 v1, v1, v2
	ds_write_b64 v65, v[0:1] offset:128
	global_load_dwordx4 v[0:3], v[12:13], off offset:288
	v_mul_f32_e32 v15, v39, v14
	s_waitcnt vmcnt(0)
	v_mul_f32_e32 v0, v15, v0
	v_mul_f32_e32 v15, v38, v14
	v_mul_f32_e32 v1, v15, v1
	v_cvt_pk_bf16_f32 v0, v0, v1
	v_mul_f32_e32 v1, v37, v14
	v_mul_f32_e32 v1, v1, v2
	v_mul_f32_e32 v2, v36, v14
	v_mul_f32_e32 v2, v2, v3
	v_cvt_pk_bf16_f32 v1, v1, v2
	ds_write_b64 v65, v[0:1] offset:144
	global_load_dwordx4 v[0:3], v[12:13], off offset:320
	v_mul_f32_e32 v15, v34, v14
	s_waitcnt vmcnt(0)
	v_mul_f32_e32 v0, v15, v0
	v_mul_f32_e32 v15, v32, v14
	v_mul_f32_e32 v1, v15, v1
	v_cvt_pk_bf16_f32 v0, v0, v1
	v_mul_f32_e32 v1, v28, v14
	v_mul_f32_e32 v1, v1, v2
	v_mul_f32_e32 v2, v24, v14
	v_mul_f32_e32 v2, v2, v3
	v_cvt_pk_bf16_f32 v1, v1, v2
	ds_write_b64 v65, v[0:1] offset:160
	global_load_dwordx4 v[0:3], v[12:13], off offset:352
	v_mul_f32_e32 v15, v35, v14
	s_waitcnt vmcnt(0)
	v_mul_f32_e32 v0, v15, v0
	v_mul_f32_e32 v15, v33, v14
	v_mul_f32_e32 v1, v15, v1
	v_cvt_pk_bf16_f32 v0, v0, v1
	v_mul_f32_e32 v1, v29, v14
	v_mul_f32_e32 v1, v1, v2
	v_mul_f32_e32 v2, v25, v14
	v_mul_f32_e32 v2, v2, v3
	v_cvt_pk_bf16_f32 v1, v1, v2
	ds_write_b64 v65, v[0:1] offset:176
	global_load_dwordx4 v[0:3], v[12:13], off offset:384
	v_mul_f32_e32 v15, v22, v14
	s_waitcnt vmcnt(0)
	v_mul_f32_e32 v0, v15, v0
	v_mul_f32_e32 v15, v20, v14
	v_mul_f32_e32 v1, v15, v1
	v_cvt_pk_bf16_f32 v0, v0, v1
	v_mul_f32_e32 v1, v18, v14
	v_mul_f32_e32 v1, v1, v2
	v_mul_f32_e32 v2, v16, v14
	v_mul_f32_e32 v2, v2, v3
	v_cvt_pk_bf16_f32 v1, v1, v2
	ds_write_b64 v65, v[0:1] offset:192
	global_load_dwordx4 v[0:3], v[12:13], off offset:416
	v_mul_f32_e32 v15, v23, v14
	s_waitcnt vmcnt(0)
	v_mul_f32_e32 v0, v15, v0
	v_mul_f32_e32 v15, v21, v14
	v_mul_f32_e32 v1, v15, v1
	v_cvt_pk_bf16_f32 v0, v0, v1
	v_mul_f32_e32 v1, v19, v14
	v_mul_f32_e32 v1, v1, v2
	v_mul_f32_e32 v2, v17, v14
	v_mul_f32_e32 v2, v2, v3
	v_cvt_pk_bf16_f32 v1, v1, v2
	ds_write_b64 v65, v[0:1] offset:208
	global_load_dwordx4 v[0:3], v[12:13], off offset:448
	s_waitcnt vmcnt(0)
	v_mul_f32_e32 v0, v4, v0
	v_mul_f32_e32 v4, v6, v14
	v_mul_f32_e32 v1, v4, v1
	v_cvt_pk_bf16_f32 v0, v0, v1
	v_mul_f32_e32 v1, v8, v14
	v_mul_f32_e32 v1, v1, v2
	v_mul_f32_e32 v2, v10, v14
	v_mul_f32_e32 v2, v2, v3
	v_cvt_pk_bf16_f32 v1, v1, v2
	ds_write_b64 v65, v[0:1] offset:224
	global_load_dwordx4 v[0:3], v[12:13], off offset:480
	v_mul_f32_e32 v4, v5, v14
	s_waitcnt vmcnt(0)
	v_mul_f32_e32 v0, v4, v0
	v_mul_f32_e32 v4, v7, v14
	v_mul_f32_e32 v1, v4, v1
	v_cvt_pk_bf16_f32 v0, v0, v1
	v_mul_f32_e32 v1, v9, v14
	v_mul_f32_e32 v1, v1, v2
	v_mul_f32_e32 v2, v11, v14
	v_mul_f32_e32 v2, v2, v3
	v_cvt_pk_bf16_f32 v1, v1, v2
	v_lshlrev_b64 v[4:5], 12, v[104:105]
	ds_write_b64 v65, v[0:1] offset:240
	s_waitcnt lgkmcnt(0)
	s_barrier
;   __device__ __forceinline__ bf16_t* MIX() const { return (bf16_t*)(ws + 776 * MB); }
; __device__ __forceinline__ void gate_pair(const Params& p, int layer, int it, char* lds) {
;     ...
;   {
; #pragma unroll
;     for (int i = 0; i < 8; ++i) { const int row = i * 16 + (ltid >> 4), cc = ltid & 15;
;       const u32x2* sp2 = (const u32x2*)(gul + row * 132 + cc * 8); const u32x2 lo = sp2[0], hh = sp2[1];
;       *(u32x4*)(p.MIX() + (size_t)(t0 + row) * DM + 1024 + g * 128 + cc * 8) = (u32x4){lo[0], lo[1], hh[0], hh[1]}; }
;   }
;   __syncthreads();
	ds_read2_b64 v[0:3], v115 offset1:1
	v_lshl_add_u64 v[4:5], s[98:99], 0, v[4:5]
	v_lshl_add_u64 v[4:5], v[4:5], 0, v[192:193]
	v_lshl_add_u64 v[4:5], v[4:5], 0, v[88:89]
	v_add_co_u32_e32 v4, vcc, s18, v4
	s_nop 1
	v_addc_co_u32_e32 v5, vcc, 0, v5, vcc
	s_waitcnt lgkmcnt(0)
	global_store_dwordx4 v[4:5], v[0:3], off offset:2048
	v_lshlrev_b64 v[4:5], 12, v[102:103]
	ds_read2_b64 v[0:3], v114 offset1:1
	v_lshl_add_u64 v[4:5], s[98:99], 0, v[4:5]
	v_lshl_add_u64 v[4:5], v[4:5], 0, v[192:193]
	v_lshl_add_u64 v[4:5], v[4:5], 0, v[88:89]
	v_add_co_u32_e32 v4, vcc, s18, v4
	s_nop 1
	v_addc_co_u32_e32 v5, vcc, 0, v5, vcc
	s_waitcnt lgkmcnt(0)
	global_store_dwordx4 v[4:5], v[0:3], off offset:2048
	v_lshlrev_b64 v[4:5], 12, v[100:101]
	ds_read2_b64 v[0:3], v113 offset1:1
	v_lshl_add_u64 v[4:5], s[98:99], 0, v[4:5]
	v_lshl_add_u64 v[4:5], v[4:5], 0, v[192:193]
	v_lshl_add_u64 v[4:5], v[4:5], 0, v[88:89]
	v_add_co_u32_e32 v4, vcc, s18, v4
	s_nop 1
	v_addc_co_u32_e32 v5, vcc, 0, v5, vcc
	s_waitcnt lgkmcnt(0)
	global_store_dwordx4 v[4:5], v[0:3], off offset:2048
	v_lshlrev_b64 v[4:5], 12, v[98:99]
	ds_read2_b64 v[0:3], v112 offset1:1
	v_lshl_add_u64 v[4:5], s[98:99], 0, v[4:5]
	v_lshl_add_u64 v[4:5], v[4:5], 0, v[192:193]
	v_lshl_add_u64 v[4:5], v[4:5], 0, v[88:89]
	v_add_co_u32_e32 v4, vcc, s18, v4
	s_nop 1
	v_addc_co_u32_e32 v5, vcc, 0, v5, vcc
	s_waitcnt lgkmcnt(0)
	global_store_dwordx4 v[4:5], v[0:3], off offset:2048
	v_lshlrev_b64 v[4:5], 12, v[96:97]
	ds_read2_b64 v[0:3], v111 offset1:1
	v_lshl_add_u64 v[4:5], s[98:99], 0, v[4:5]
	v_lshl_add_u64 v[4:5], v[4:5], 0, v[192:193]
	v_lshl_add_u64 v[4:5], v[4:5], 0, v[88:89]
	v_add_co_u32_e32 v4, vcc, s18, v4
	s_nop 1
	v_addc_co_u32_e32 v5, vcc, 0, v5, vcc
	s_waitcnt lgkmcnt(0)
	global_store_dwordx4 v[4:5], v[0:3], off offset:2048
	v_lshlrev_b64 v[4:5], 12, v[94:95]
	ds_read2_b64 v[0:3], v110 offset1:1
	v_lshl_add_u64 v[4:5], s[98:99], 0, v[4:5]
	v_lshl_add_u64 v[4:5], v[4:5], 0, v[192:193]
	v_lshl_add_u64 v[4:5], v[4:5], 0, v[88:89]
	v_add_co_u32_e32 v4, vcc, s18, v4
	s_nop 1
	v_addc_co_u32_e32 v5, vcc, 0, v5, vcc
	s_waitcnt lgkmcnt(0)
	global_store_dwordx4 v[4:5], v[0:3], off offset:2048
	v_lshlrev_b64 v[4:5], 12, v[92:93]
	ds_read2_b64 v[0:3], v109 offset1:1
	v_lshl_add_u64 v[4:5], s[98:99], 0, v[4:5]
	v_lshl_add_u64 v[4:5], v[4:5], 0, v[192:193]
	v_lshl_add_u64 v[4:5], v[4:5], 0, v[88:89]
	v_add_co_u32_e32 v4, vcc, s18, v4
	s_nop 1
	v_addc_co_u32_e32 v5, vcc, 0, v5, vcc
	s_waitcnt lgkmcnt(0)
	global_store_dwordx4 v[4:5], v[0:3], off offset:2048
	v_lshlrev_b64 v[4:5], 12, v[90:91]
	ds_read2_b64 v[0:3], v108 offset1:1
	v_lshl_add_u64 v[4:5], s[98:99], 0, v[4:5]
	v_lshl_add_u64 v[4:5], v[4:5], 0, v[192:193]
	v_lshl_add_u64 v[4:5], v[4:5], 0, v[88:89]
	v_add_co_u32_e32 v4, vcc, 0x30800000, v4
	s_nop 1
	v_addc_co_u32_e32 v5, vcc, 0, v5, vcc
	s_waitcnt lgkmcnt(0)
	global_store_dwordx4 v[4:5], v[0:3], off offset:2048
	s_barrier
	s_load_dword s1, s[94:95], 0x0
	s_waitcnt lgkmcnt(0)
	s_add_i32 s5, s1, s5
	s_cmpk_gt_i32 s5, 0x3ff
	s_cbranch_scc0 .LBB0_148

;   __device__ __forceinline__ bf16_t* XB() const { return (bf16_t*)(ws + 328 * MB); }
; __device__ __forceinline__ float bflo(unsigned w) { return __uint_as_float(w << 16); }
; __device__ __forceinline__ float bfhi(unsigned w) { return __uint_as_float(w & 0xffff0000u); }
; __device__ __forceinline__ void peer_phase(const Params& p, int layer, char* lds, bool last) {
;     ...
;     for (int tt = 0; tt < 4; ++tt) {
;       const int tok = wid * 4 + tt; const bf16_t* xr = p.XB() + (size_t)(t0 + tok) * DM + lane * 8; float ss = 0.f;
; #pragma unroll
;       for (int c = 0; c < 4; ++c) { const u32x4 a = *(const u32x4*)(xr + c * 512);
; #pragma unroll
;         for (int e = 0; e < 4; ++e) { const float lo = bflo(a[e]), hh = bfhi(a[e]); ss = fmaf(lo, lo, ss); ss = fmaf(hh, hh, ss); } }
;       ss = wave_sum_fast(ss);
;       if (lane == 0) rsl[tok] = rsqrtf(ss * (1.f / 2048.f) + EPS);
;     }
.LBB0_156:
	v_mbcnt_lo_u32_b32 v70, -1, 0
	v_mbcnt_hi_u32_b32 v70, -1, v70
	s_lshl_b32 s70, s60, 5
	v_add_u32_e32 v71, s40, v70
	v_ashrrev_i32_e32 v68, 4, v71
	v_and_b32_e32 v66, 63, v70
	v_and_b32_e32 v69, -4, v68
	v_lshlrev_b32_e32 v192, 4, v66
	v_cmp_eq_u32_e32 vcc, 0, v66
	v_add_u32_e32 v66, s70, v69
	v_ashrrev_i32_e32 v67, 31, v66
	v_lshl_add_u64 v[64:65], s[20:21], 0, v[192:193]
	v_lshlrev_b64 v[66:67], 12, v[66:67]
	v_lshl_add_u64 v[66:67], v[64:65], 0, v[66:67]
	global_load_dwordx4 v[0:3], v[66:67], off
	global_load_dwordx4 v[4:7], v[66:67], off offset:1024
	global_load_dwordx4 v[8:11], v[66:67], off offset:2048
	global_load_dwordx4 v[12:15], v[66:67], off offset:3072
	s_mov_b64 s[100:101], 0x1000
	v_lshl_add_u64 v[234:235], v[66:67], 0, s[100:101]
	global_load_dwordx4 v[16:19], v[234:235], off
	global_load_dwordx4 v[20:23], v[234:235], off offset:1024
	global_load_dwordx4 v[24:27], v[234:235], off offset:2048
	global_load_dwordx4 v[28:31], v[234:235], off offset:3072
	s_mov_b64 s[100:101], 0x2000
	v_lshl_add_u64 v[234:235], v[66:67], 0, s[100:101]
	global_load_dwordx4 v[32:35], v[234:235], off
	global_load_dwordx4 v[36:39], v[234:235], off offset:1024
	global_load_dwordx4 v[40:43], v[234:235], off offset:2048
	global_load_dwordx4 v[44:47], v[234:235], off offset:3072
	s_mov_b64 s[100:101], 0x3000
	v_lshl_add_u64 v[234:235], v[66:67], 0, s[100:101]
	global_load_dwordx4 v[48:51], v[234:235], off
	global_load_dwordx4 v[52:55], v[234:235], off offset:1024
	global_load_dwordx4 v[56:59], v[234:235], off offset:2048
	global_load_dwordx4 v[60:63], v[234:235], off offset:3072
	s_waitcnt vmcnt(0)
	v_mov_b64_e32 v[72:73], v[0:1]
	v_mov_b64_e32 v[74:75], v[2:3]
	v_lshlrev_b32_e32 v76, 16, v72
	v_and_b32_e32 v77, 0xffff0000, v72
	v_fma_f32 v72, v76, v76, 0
	v_fmac_f32_e32 v72, v77, v77
	v_lshlrev_b32_e32 v76, 16, v73
	v_and_b32_e32 v73, 0xffff0000, v73
	v_fmac_f32_e32 v72, v76, v76
	v_fmac_f32_e32 v72, v73, v73
	v_lshlrev_b32_e32 v73, 16, v74
	v_and_b32_e32 v74, 0xffff0000, v74
	v_fmac_f32_e32 v72, v73, v73
	v_fmac_f32_e32 v72, v74, v74
	v_lshlrev_b32_e32 v73, 16, v75
	v_and_b32_e32 v74, 0xffff0000, v75
	v_fmac_f32_e32 v72, v73, v73
	v_fmac_f32_e32 v72, v74, v74
	v_mov_b64_e32 v[74:75], v[4:5]
	v_mov_b64_e32 v[76:77], v[6:7]
	v_lshlrev_b32_e32 v73, 16, v74
	v_and_b32_e32 v74, 0xffff0000, v74
	v_fmac_f32_e32 v72, v73, v73
	v_fmac_f32_e32 v72, v74, v74
	v_lshlrev_b32_e32 v73, 16, v75
	v_and_b32_e32 v74, 0xffff0000, v75
	v_fmac_f32_e32 v72, v73, v73
	v_fmac_f32_e32 v72, v74, v74
	v_lshlrev_b32_e32 v73, 16, v76
	v_and_b32_e32 v74, 0xffff0000, v76
	v_fmac_f32_e32 v72, v73, v73
	v_fmac_f32_e32 v72, v74, v74
	v_lshlrev_b32_e32 v73, 16, v77
	v_and_b32_e32 v74, 0xffff0000, v77
	v_fmac_f32_e32 v72, v73, v73
	v_fmac_f32_e32 v72, v74, v74
	v_mov_b64_e32 v[74:75], v[8:9]
	v_mov_b64_e32 v[76:77], v[10:11]
	v_lshlrev_b32_e32 v73, 16, v74
	v_and_b32_e32 v74, 0xffff0000, v74
	v_fmac_f32_e32 v72, v73, v73
	v_fmac_f32_e32 v72, v74, v74
	v_lshlrev_b32_e32 v73, 16, v75
	v_and_b32_e32 v74, 0xffff0000, v75
	v_fmac_f32_e32 v72, v73, v73
	v_fmac_f32_e32 v72, v74, v74
	v_lshlrev_b32_e32 v73, 16, v76
	v_and_b32_e32 v74, 0xffff0000, v76
	v_fmac_f32_e32 v72, v73, v73
	v_fmac_f32_e32 v72, v74, v74
	v_lshlrev_b32_e32 v73, 16, v77
	v_and_b32_e32 v74, 0xffff0000, v77
	v_fmac_f32_e32 v72, v73, v73
	v_fmac_f32_e32 v72, v74, v74
	v_mov_b64_e32 v[74:75], v[12:13]
	v_mov_b64_e32 v[76:77], v[14:15]
	v_lshlrev_b32_e32 v66, 16, v74
	v_and_b32_e32 v67, 0xffff0000, v74
	v_fmac_f32_e32 v72, v66, v66
	v_fmac_f32_e32 v72, v67, v67
	v_lshlrev_b32_e32 v66, 16, v75
	v_and_b32_e32 v67, 0xffff0000, v75
	v_fmac_f32_e32 v72, v66, v66
	v_fmac_f32_e32 v72, v67, v67
	v_lshlrev_b32_e32 v66, 16, v76
	v_and_b32_e32 v67, 0xffff0000, v76
	v_fmac_f32_e32 v72, v66, v66
	v_fmac_f32_e32 v72, v67, v67
	v_lshlrev_b32_e32 v66, 16, v77
	v_and_b32_e32 v67, 0xffff0000, v77
	v_fmac_f32_e32 v72, v66, v66
	v_fmac_f32_e32 v72, v67, v67
	s_nop 1
	v_add_f32_dpp v66, v72, v72 quad_perm:[1,0,3,2] row_mask:0xf bank_mask:0xf bound_ctrl:1
	s_nop 1
	v_add_f32_dpp v66, v66, v66 quad_perm:[2,3,0,1] row_mask:0xf bank_mask:0xf bound_ctrl:1
	s_nop 1
	v_add_f32_dpp v66, v66, v66 row_half_mirror row_mask:0xf bank_mask:0xf bound_ctrl:1
	s_nop 1
	v_add_f32_dpp v66, v66, v66 row_mirror row_mask:0xf bank_mask:0xf bound_ctrl:1
	v_mov_b32_e32 v67, v66
	s_nop 1
	v_permlane16_swap_b32_e32 v66, v67
	v_add_f32_e32 v66, v66, v67
	v_mov_b32_e32 v67, v66
	s_nop 1
	v_permlane32_swap_b32_e32 v66, v67
	s_and_saveexec_b64 s[66:67], vcc
	s_cbranch_execz .LBB0_158
	v_add_f32_e32 v66, v66, v67
	v_fmamk_f32 v66, v66, 0x3a000000, v212
	v_mul_f32_e32 v67, 0x4b800000, v66
	v_cmp_gt_f32_e64 s[4:5], s65, v66
	s_nop 1
	v_cndmask_b32_e64 v66, v66, v67, s[4:5]
	v_rsq_f32_e32 v66, v66
	s_nop 0
	v_mul_f32_e32 v67, 0x45800000, v66
	v_cndmask_b32_e64 v66, v66, v67, s[4:5]
	v_lshl_add_u32 v67, v69, 2, v221
	ds_write_b32 v67, v66
;   __device__ __forceinline__ bf16_t* XB() const { return (bf16_t*)(ws + 328 * MB); }
; __device__ __forceinline__ float bflo(unsigned w) { return __uint_as_float(w << 16); }
; __device__ __forceinline__ float bfhi(unsigned w) { return __uint_as_float(w & 0xffff0000u); }
; __device__ __forceinline__ void peer_phase(const Params& p, int layer, char* lds, bool last) {
;     ...
;     for (int tt = 0; tt < 4; ++tt) {
;       const int tok = wid * 4 + tt; const bf16_t* xr = p.XB() + (size_t)(t0 + tok) * DM + lane * 8; float ss = 0.f;
; #pragma unroll
;       for (int c = 0; c < 4; ++c) { const u32x4 a = *(const u32x4*)(xr + c * 512);
; #pragma unroll
;         for (int e = 0; e < 4; ++e) { const float lo = bflo(a[e]), hh = bfhi(a[e]); ss = fmaf(lo, lo, ss); ss = fmaf(hh, hh, ss); } }
;       ss = wave_sum_fast(ss);
;       if (lane == 0) rsl[tok] = rsqrtf(ss * (1.f / 2048.f) + EPS);
;     }
.LBB0_158:
	s_or_b64 exec, exec, s[66:67]
	v_or_b32_e32 v72, 1, v69
	v_add_u32_e32 v66, s70, v72
	v_ashrrev_i32_e32 v67, 31, v66
	v_lshlrev_b64 v[66:67], 12, v[66:67]
	v_lshl_add_u64 v[66:67], v[64:65], 0, v[66:67]
	v_mov_b64_e32 v[74:75], v[16:17]
	v_mov_b64_e32 v[76:77], v[18:19]
	v_lshlrev_b32_e32 v73, 16, v74
	v_and_b32_e32 v74, 0xffff0000, v74
	v_fma_f32 v73, v73, v73, 0
	v_fmac_f32_e32 v73, v74, v74
	v_lshlrev_b32_e32 v74, 16, v75
	v_and_b32_e32 v75, 0xffff0000, v75
	v_fmac_f32_e32 v73, v74, v74
	v_fmac_f32_e32 v73, v75, v75
	v_lshlrev_b32_e32 v74, 16, v76
	v_and_b32_e32 v75, 0xffff0000, v76
	v_fmac_f32_e32 v73, v74, v74
	v_fmac_f32_e32 v73, v75, v75
	v_lshlrev_b32_e32 v74, 16, v77
	v_and_b32_e32 v75, 0xffff0000, v77
	v_fmac_f32_e32 v73, v74, v74
	v_fmac_f32_e32 v73, v75, v75
	v_mov_b64_e32 v[74:75], v[20:21]
	v_mov_b64_e32 v[76:77], v[22:23]
	v_lshlrev_b32_e32 v78, 16, v74
	v_and_b32_e32 v74, 0xffff0000, v74
	v_fmac_f32_e32 v73, v78, v78
	v_fmac_f32_e32 v73, v74, v74
	v_lshlrev_b32_e32 v74, 16, v75
	v_and_b32_e32 v75, 0xffff0000, v75
	v_fmac_f32_e32 v73, v74, v74
	v_fmac_f32_e32 v73, v75, v75
	v_lshlrev_b32_e32 v74, 16, v76
	v_and_b32_e32 v75, 0xffff0000, v76
	v_fmac_f32_e32 v73, v74, v74
	v_fmac_f32_e32 v73, v75, v75
	v_lshlrev_b32_e32 v74, 16, v77
	v_and_b32_e32 v75, 0xffff0000, v77
	v_fmac_f32_e32 v73, v74, v74
	v_fmac_f32_e32 v73, v75, v75
	v_mov_b64_e32 v[74:75], v[24:25]
	v_mov_b64_e32 v[76:77], v[26:27]
	v_lshlrev_b32_e32 v78, 16, v74
	v_and_b32_e32 v74, 0xffff0000, v74
	v_fmac_f32_e32 v73, v78, v78
	v_fmac_f32_e32 v73, v74, v74
	v_lshlrev_b32_e32 v74, 16, v75
	v_and_b32_e32 v75, 0xffff0000, v75
	v_fmac_f32_e32 v73, v74, v74
	v_fmac_f32_e32 v73, v75, v75
	v_lshlrev_b32_e32 v74, 16, v76
	v_and_b32_e32 v75, 0xffff0000, v76
	v_fmac_f32_e32 v73, v74, v74
	v_fmac_f32_e32 v73, v75, v75
	v_lshlrev_b32_e32 v74, 16, v77
	v_and_b32_e32 v75, 0xffff0000, v77
	v_fmac_f32_e32 v73, v74, v74
	v_fmac_f32_e32 v73, v75, v75
	v_mov_b64_e32 v[74:75], v[28:29]
	v_mov_b64_e32 v[76:77], v[30:31]
	v_lshlrev_b32_e32 v66, 16, v74
	v_and_b32_e32 v67, 0xffff0000, v74
	v_fmac_f32_e32 v73, v66, v66
	v_fmac_f32_e32 v73, v67, v67
	v_lshlrev_b32_e32 v66, 16, v75
	v_and_b32_e32 v67, 0xffff0000, v75
	v_fmac_f32_e32 v73, v66, v66
	v_fmac_f32_e32 v73, v67, v67
	v_lshlrev_b32_e32 v66, 16, v76
	v_and_b32_e32 v67, 0xffff0000, v76
	v_fmac_f32_e32 v73, v66, v66
	v_fmac_f32_e32 v73, v67, v67
	v_lshlrev_b32_e32 v66, 16, v77
	v_and_b32_e32 v67, 0xffff0000, v77
	v_fmac_f32_e32 v73, v66, v66
	v_fmac_f32_e32 v73, v67, v67
	s_nop 1
	v_add_f32_dpp v66, v73, v73 quad_perm:[1,0,3,2] row_mask:0xf bank_mask:0xf bound_ctrl:1
	s_nop 1
	v_add_f32_dpp v66, v66, v66 quad_perm:[2,3,0,1] row_mask:0xf bank_mask:0xf bound_ctrl:1
	s_nop 1
	v_add_f32_dpp v66, v66, v66 row_half_mirror row_mask:0xf bank_mask:0xf bound_ctrl:1
	s_nop 1
	v_add_f32_dpp v66, v66, v66 row_mirror row_mask:0xf bank_mask:0xf bound_ctrl:1
	v_mov_b32_e32 v67, v66
	s_nop 1
	v_permlane16_swap_b32_e32 v66, v67
	v_add_f32_e32 v66, v66, v67
	v_mov_b32_e32 v67, v66
	s_nop 1
	v_permlane32_swap_b32_e32 v66, v67
	s_and_saveexec_b64 s[66:67], vcc
	s_cbranch_execz .LBB0_160
	v_add_f32_e32 v66, v66, v67
	v_fmamk_f32 v66, v66, 0x3a000000, v212
	v_mul_f32_e32 v67, 0x4b800000, v66
	v_cmp_gt_f32_e64 s[4:5], s65, v66
	s_nop 1
	v_cndmask_b32_e64 v66, v66, v67, s[4:5]
	v_rsq_f32_e32 v66, v66
	s_nop 0
	v_mul_f32_e32 v67, 0x45800000, v66
	v_cndmask_b32_e64 v66, v66, v67, s[4:5]
	v_lshl_add_u32 v67, v72, 2, v221
	ds_write_b32 v67, v66
.LBB0_160:
	s_or_b64 exec, exec, s[66:67]
	v_or_b32_e32 v69, 2, v69
	v_add_u32_e32 v66, s70, v69
	v_ashrrev_i32_e32 v67, 31, v66
	v_lshlrev_b64 v[66:67], 12, v[66:67]
	v_lshl_add_u64 v[66:67], v[64:65], 0, v[66:67]
	v_mov_b64_e32 v[72:73], v[32:33]
	v_mov_b64_e32 v[74:75], v[34:35]
	v_lshlrev_b32_e32 v76, 16, v72
	v_and_b32_e32 v77, 0xffff0000, v72
	v_fma_f32 v72, v76, v76, 0
	v_fmac_f32_e32 v72, v77, v77
	v_lshlrev_b32_e32 v76, 16, v73
	v_and_b32_e32 v73, 0xffff0000, v73
	v_fmac_f32_e32 v72, v76, v76
	v_fmac_f32_e32 v72, v73, v73
	v_lshlrev_b32_e32 v73, 16, v74
	v_and_b32_e32 v74, 0xffff0000, v74
	v_fmac_f32_e32 v72, v73, v73
	v_fmac_f32_e32 v72, v74, v74
	v_lshlrev_b32_e32 v73, 16, v75
	v_and_b32_e32 v74, 0xffff0000, v75
	v_fmac_f32_e32 v72, v73, v73
	v_fmac_f32_e32 v72, v74, v74
	v_mov_b64_e32 v[74:75], v[36:37]
	v_mov_b64_e32 v[76:77], v[38:39]
	v_lshlrev_b32_e32 v73, 16, v74
	v_and_b32_e32 v74, 0xffff0000, v74
	v_fmac_f32_e32 v72, v73, v73
	v_fmac_f32_e32 v72, v74, v74
	v_lshlrev_b32_e32 v73, 16, v75
	v_and_b32_e32 v74, 0xffff0000, v75
	v_fmac_f32_e32 v72, v73, v73
	v_fmac_f32_e32 v72, v74, v74
	v_lshlrev_b32_e32 v73, 16, v76
	v_and_b32_e32 v74, 0xffff0000, v76
	v_fmac_f32_e32 v72, v73, v73
	v_fmac_f32_e32 v72, v74, v74
	v_lshlrev_b32_e32 v73, 16, v77
	v_and_b32_e32 v74, 0xffff0000, v77
	v_fmac_f32_e32 v72, v73, v73
	v_fmac_f32_e32 v72, v74, v74
	v_mov_b64_e32 v[74:75], v[40:41]
	v_mov_b64_e32 v[76:77], v[42:43]
	v_lshlrev_b32_e32 v73, 16, v74
	v_and_b32_e32 v74, 0xffff0000, v74
	v_fmac_f32_e32 v72, v73, v73
	v_fmac_f32_e32 v72, v74, v74
	v_lshlrev_b32_e32 v73, 16, v75
	v_and_b32_e32 v74, 0xffff0000, v75
	v_fmac_f32_e32 v72, v73, v73
	v_fmac_f32_e32 v72, v74, v74
	v_lshlrev_b32_e32 v73, 16, v76
	v_and_b32_e32 v74, 0xffff0000, v76
	v_fmac_f32_e32 v72, v73, v73
	v_fmac_f32_e32 v72, v74, v74
	v_lshlrev_b32_e32 v73, 16, v77
	v_and_b32_e32 v74, 0xffff0000, v77
	v_fmac_f32_e32 v72, v73, v73
	v_fmac_f32_e32 v72, v74, v74
	v_mov_b64_e32 v[74:75], v[44:45]
	v_mov_b64_e32 v[76:77], v[46:47]
	v_lshlrev_b32_e32 v66, 16, v74
	v_and_b32_e32 v67, 0xffff0000, v74
	v_fmac_f32_e32 v72, v66, v66
	v_fmac_f32_e32 v72, v67, v67
	v_lshlrev_b32_e32 v66, 16, v75
	v_and_b32_e32 v67, 0xffff0000, v75
	v_fmac_f32_e32 v72, v66, v66
	v_fmac_f32_e32 v72, v67, v67
	v_lshlrev_b32_e32 v66, 16, v76
	v_and_b32_e32 v67, 0xffff0000, v76
	v_fmac_f32_e32 v72, v66, v66
	v_fmac_f32_e32 v72, v67, v67
	v_lshlrev_b32_e32 v66, 16, v77
	v_and_b32_e32 v67, 0xffff0000, v77
	v_fmac_f32_e32 v72, v66, v66
	v_fmac_f32_e32 v72, v67, v67
	s_nop 1
	v_add_f32_dpp v66, v72, v72 quad_perm:[1,0,3,2] row_mask:0xf bank_mask:0xf bound_ctrl:1
	s_nop 1
	v_add_f32_dpp v66, v66, v66 quad_perm:[2,3,0,1] row_mask:0xf bank_mask:0xf bound_ctrl:1
	s_nop 1
	v_add_f32_dpp v66, v66, v66 row_half_mirror row_mask:0xf bank_mask:0xf bound_ctrl:1
	s_nop 1
	v_add_f32_dpp v66, v66, v66 row_mirror row_mask:0xf bank_mask:0xf bound_ctrl:1
	v_mov_b32_e32 v67, v66
	s_nop 1
	v_permlane16_swap_b32_e32 v66, v67
	v_add_f32_e32 v66, v66, v67
	v_mov_b32_e32 v67, v66
	s_nop 1
	v_permlane32_swap_b32_e32 v66, v67
	s_and_saveexec_b64 s[66:67], vcc
	s_cbranch_execz .LBB0_162
	v_add_f32_e32 v66, v66, v67
	v_fmamk_f32 v66, v66, 0x3a000000, v212
	v_mul_f32_e32 v67, 0x4b800000, v66
	v_cmp_gt_f32_e64 s[4:5], s65, v66
	s_nop 1
	v_cndmask_b32_e64 v66, v66, v67, s[4:5]
	v_rsq_f32_e32 v66, v66
	s_nop 0
	v_mul_f32_e32 v67, 0x45800000, v66
	v_cndmask_b32_e64 v66, v66, v67, s[4:5]
	v_lshl_add_u32 v67, v69, 2, v221
	ds_write_b32 v67, v66
;   __device__ __forceinline__ bf16_t* XB() const { return (bf16_t*)(ws + 328 * MB); }
;   __device__ __forceinline__ float* S() const { return (float*)(ws + 456 * MB); }
; __device__ __forceinline__ float bflo(unsigned w) { return __uint_as_float(w << 16); }
; __device__ __forceinline__ float bfhi(unsigned w) { return __uint_as_float(w & 0xffff0000u); }
; __device__ __forceinline__ void peer_phase(const Params& p, int layer, char* lds, bool last) {
;     ...
;     for (int tt = 0; tt < 4; ++tt) {
;       const int tok = wid * 4 + tt; const bf16_t* xr = p.XB() + (size_t)(t0 + tok) * DM + lane * 8; float ss = 0.f;
; #pragma unroll
;       for (int c = 0; c < 4; ++c) { const u32x4 a = *(const u32x4*)(xr + c * 512);
; #pragma unroll
;         for (int e = 0; e < 4; ++e) { const float lo = bflo(a[e]), hh = bfhi(a[e]); ss = fmaf(lo, lo, ss); ss = fmaf(hh, hh, ss); } }
;       ss = wave_sum_fast(ss);
;       if (lane == 0) rsl[tok] = rsqrtf(ss * (1.f / 2048.f) + EPS);
;     }
;     {
;       const int tok = tid >> 4, hc = tid & 15;
;       const u32x4* sp = (const u32x4*)((const bf16_t*)p.S() + (size_t)(t0 + tok) * DM + hc * 128);
;       float top[16];
; #pragma unroll
;       for (int i = 0; i < 16; ++i) top[i] = -3.0e38f;
; #pragma unroll 2
;       for (int i8 = 0; i8 < 16; ++i8) { const u32x4 v4 = sp[i8];
.LBB0_162:
	s_or_b64 exec, exec, s[66:67]
	v_or_b32_e32 v66, 3, v68
	v_add_u32_e32 v72, s70, v66
	v_ashrrev_i32_e32 v73, 31, v72
	v_lshlrev_b64 v[72:73], 12, v[72:73]
	v_lshl_add_u64 v[64:65], v[64:65], 0, v[72:73]
	v_mov_b64_e32 v[72:73], v[48:49]
	v_mov_b64_e32 v[74:75], v[50:51]
	v_lshlrev_b32_e32 v67, 16, v72
	v_and_b32_e32 v69, 0xffff0000, v72
	v_fma_f32 v67, v67, v67, 0
	v_fmac_f32_e32 v67, v69, v69
	v_lshlrev_b32_e32 v69, 16, v73
	v_and_b32_e32 v72, 0xffff0000, v73
	v_fmac_f32_e32 v67, v69, v69
	v_fmac_f32_e32 v67, v72, v72
	v_lshlrev_b32_e32 v69, 16, v74
	v_and_b32_e32 v72, 0xffff0000, v74
	v_fmac_f32_e32 v67, v69, v69
	v_fmac_f32_e32 v67, v72, v72
	v_lshlrev_b32_e32 v69, 16, v75
	v_and_b32_e32 v72, 0xffff0000, v75
	v_fmac_f32_e32 v67, v69, v69
	v_fmac_f32_e32 v67, v72, v72
	v_mov_b64_e32 v[72:73], v[52:53]
	v_mov_b64_e32 v[74:75], v[54:55]
	v_lshlrev_b32_e32 v69, 16, v72
	v_and_b32_e32 v72, 0xffff0000, v72
	v_fmac_f32_e32 v67, v69, v69
	v_fmac_f32_e32 v67, v72, v72
	v_lshlrev_b32_e32 v69, 16, v73
	v_and_b32_e32 v72, 0xffff0000, v73
	v_fmac_f32_e32 v67, v69, v69
	v_fmac_f32_e32 v67, v72, v72
	v_lshlrev_b32_e32 v69, 16, v74
	v_and_b32_e32 v72, 0xffff0000, v74
	v_fmac_f32_e32 v67, v69, v69
	v_fmac_f32_e32 v67, v72, v72
	v_lshlrev_b32_e32 v69, 16, v75
	v_and_b32_e32 v72, 0xffff0000, v75
	v_fmac_f32_e32 v67, v69, v69
	v_fmac_f32_e32 v67, v72, v72
	v_mov_b64_e32 v[72:73], v[56:57]
	v_mov_b64_e32 v[74:75], v[58:59]
	v_lshlrev_b32_e32 v69, 16, v72
	v_and_b32_e32 v72, 0xffff0000, v72
	v_fmac_f32_e32 v67, v69, v69
	v_fmac_f32_e32 v67, v72, v72
	v_lshlrev_b32_e32 v69, 16, v73
	v_and_b32_e32 v72, 0xffff0000, v73
	v_fmac_f32_e32 v67, v69, v69
	v_fmac_f32_e32 v67, v72, v72
	v_lshlrev_b32_e32 v69, 16, v74
	v_and_b32_e32 v72, 0xffff0000, v74
	v_fmac_f32_e32 v67, v69, v69
	v_fmac_f32_e32 v67, v72, v72
	v_lshlrev_b32_e32 v69, 16, v75
	v_and_b32_e32 v72, 0xffff0000, v75
	v_fmac_f32_e32 v67, v69, v69
	v_fmac_f32_e32 v67, v72, v72
	v_mov_b64_e32 v[72:73], v[60:61]
	v_mov_b64_e32 v[74:75], v[62:63]
	v_lshlrev_b32_e32 v64, 16, v72
	v_and_b32_e32 v65, 0xffff0000, v72
	v_fmac_f32_e32 v67, v64, v64
	v_fmac_f32_e32 v67, v65, v65
	v_lshlrev_b32_e32 v64, 16, v73
	v_and_b32_e32 v65, 0xffff0000, v73
	v_fmac_f32_e32 v67, v64, v64
	v_fmac_f32_e32 v67, v65, v65
	v_lshlrev_b32_e32 v64, 16, v74
	v_and_b32_e32 v65, 0xffff0000, v74
	v_fmac_f32_e32 v67, v64, v64
	v_fmac_f32_e32 v67, v65, v65
	v_lshlrev_b32_e32 v64, 16, v75
	v_and_b32_e32 v65, 0xffff0000, v75
	v_fmac_f32_e32 v67, v64, v64
	v_fmac_f32_e32 v67, v65, v65
	s_nop 1
	v_add_f32_dpp v64, v67, v67 quad_perm:[1,0,3,2] row_mask:0xf bank_mask:0xf bound_ctrl:1
	s_nop 1
	v_add_f32_dpp v64, v64, v64 quad_perm:[2,3,0,1] row_mask:0xf bank_mask:0xf bound_ctrl:1
	s_nop 1
	v_add_f32_dpp v64, v64, v64 row_half_mirror row_mask:0xf bank_mask:0xf bound_ctrl:1
	s_nop 1
	v_add_f32_dpp v64, v64, v64 row_mirror row_mask:0xf bank_mask:0xf bound_ctrl:1
	v_mov_b32_e32 v65, v64
	s_nop 1
	v_permlane16_swap_b32_e32 v64, v65
	v_add_f32_e32 v64, v64, v65
	v_mov_b32_e32 v65, v64
	s_nop 1
	v_permlane32_swap_b32_e32 v64, v65
	s_and_saveexec_b64 s[4:5], vcc
	s_cbranch_execz .LBB0_164
	v_add_f32_e32 v64, v64, v65
	v_fmamk_f32 v64, v64, 0x3a000000, v212
	v_mul_f32_e32 v65, 0x4b800000, v64
	v_cmp_gt_f32_e32 vcc, s65, v64
	s_nop 1
	v_cndmask_b32_e32 v64, v64, v65, vcc
	v_rsq_f32_e32 v64, v64
	s_nop 0
	v_mul_f32_e32 v65, 0x45800000, v64
	v_cndmask_b32_e32 v64, v64, v65, vcc
	v_lshl_add_u32 v65, v66, 2, v221
	ds_write_b32 v65, v64
.LBB0_164:
	s_or_b64 exec, exec, s[4:5]
	v_add_u32_e32 v64, s70, v68
	v_ashrrev_i32_e32 v65, 31, v64
	v_lshlrev_b64 v[64:65], 12, v[64:65]
	v_and_b32_e32 v72, 15, v70
	v_lshl_or_b32 v64, v72, 8, v64
	s_mov_b32 s1, 15
	v_lshl_add_u64 v[68:69], s[50:51], 0, v[64:65]
	v_mov_b32_e32 v73, 0xff61b1e6
	v_mov_b32_e32 v74, 0xff61b1e6
	v_mov_b32_e32 v75, 0xff61b1e6
	v_mov_b32_e32 v76, 0xff61b1e6
	v_mov_b32_e32 v77, 0xff61b1e6
	v_mov_b32_e32 v78, 0xff61b1e6
	v_mov_b32_e32 v79, 0xff61b1e6
	v_mov_b32_e32 v80, 0xff61b1e6
	v_mov_b32_e32 v81, 0xff61b1e6
	v_mov_b32_e32 v82, 0xff61b1e6
	v_mov_b32_e32 v83, 0xff61b1e6
	v_mov_b32_e32 v84, 0xff61b1e6
	v_mov_b32_e32 v85, 0xff61b1e6
	v_mov_b32_e32 v86, 0xff61b1e6
	v_mov_b32_e32 v87, 0xff61b1e6
	v_mov_b32_e32 v88, 0xff61b1e6
	global_load_dwordx4 v[208:211], v[68:69], off
	global_load_dwordx4 v[216:219], v[68:69], off offset:-16
	v_lshl_add_u64 v[68:69], v[68:69], 0, 32
; __device__ __forceinline__ void peer_phase(const Params& p, int layer, char* lds, bool last) {
;     ...
;       for (int i8 = 0; i8 < 16; ++i8) { const u32x4 v4 = sp[i8];
; #pragma unroll
;         for (int e = 0; e < 4; ++e) { float v = __uint_as_float((v4[e] << 16) | (unsigned)(i8 * 8 + e * 2)); CE16(top, v);
;           v = __uint_as_float((v4[e] & 0xffff0000u) | (unsigned)(i8 * 8 + e * 2 + 1)); CE16(top, v); } }
.LBB0_165:
	s_waitcnt vmcnt(0)
	v_mov_b64_e32 v[64:65], v[208:209]
	v_mov_b64_e32 v[66:67], v[210:211]
	v_mov_b64_e32 v[90:91], v[216:217]
	v_mov_b64_e32 v[92:93], v[218:219]
	global_load_dwordx4 v[208:211], v[68:69], off
	global_load_dwordx4 v[216:219], v[68:69], off offset:-16
	v_lshl_add_u64 v[68:69], v[68:69], 0, 32
	v_lshlrev_b32_e32 v89, 16, v90
	v_add3_u32 v89, s1, v89, -15
	v_med3_f32 v88, v87, v88, v89
	v_med3_f32 v87, v86, v87, v89
	v_med3_f32 v86, v85, v86, v89
	v_med3_f32 v85, v84, v85, v89
	v_med3_f32 v84, v83, v84, v89
	v_med3_f32 v83, v82, v83, v89
	v_med3_f32 v82, v81, v82, v89
	v_med3_f32 v81, v80, v81, v89
	v_med3_f32 v80, v79, v80, v89
	v_med3_f32 v79, v78, v79, v89
	v_med3_f32 v78, v77, v78, v89
	v_med3_f32 v77, v76, v77, v89
	v_med3_f32 v76, v75, v76, v89
	v_med3_f32 v75, v74, v75, v89
	v_med3_f32 v74, v73, v74, v89
	v_max_f32_e32 v89, v89, v89
	v_max_f32_e32 v73, v73, v73
	v_max_f32_e32 v73, v73, v89
	v_and_b32_e32 v89, 0xffff0000, v90
	v_add3_u32 v89, s1, v89, -14
	v_med3_f32 v88, v87, v88, v89
	v_med3_f32 v87, v86, v87, v89
	v_med3_f32 v86, v85, v86, v89
	v_med3_f32 v85, v84, v85, v89
	v_med3_f32 v84, v83, v84, v89
	v_med3_f32 v83, v82, v83, v89
	v_med3_f32 v82, v81, v82, v89
	v_med3_f32 v81, v80, v81, v89
	v_med3_f32 v80, v79, v80, v89
	v_med3_f32 v79, v78, v79, v89
	v_med3_f32 v78, v77, v78, v89
	v_med3_f32 v77, v76, v77, v89
	v_med3_f32 v76, v75, v76, v89
	v_med3_f32 v75, v74, v75, v89
	v_med3_f32 v74, v73, v74, v89
	v_max_f32_e32 v89, v89, v89
	v_max_f32_e32 v73, v73, v89
	v_lshlrev_b32_e32 v89, 16, v91
	v_add3_u32 v89, s1, v89, -13
	v_med3_f32 v88, v87, v88, v89
	v_med3_f32 v87, v86, v87, v89
	v_med3_f32 v86, v85, v86, v89
	v_med3_f32 v85, v84, v85, v89
	v_med3_f32 v84, v83, v84, v89
	v_med3_f32 v83, v82, v83, v89
	v_med3_f32 v82, v81, v82, v89
	v_med3_f32 v81, v80, v81, v89
	v_med3_f32 v80, v79, v80, v89
	v_med3_f32 v79, v78, v79, v89
	v_med3_f32 v78, v77, v78, v89
	v_med3_f32 v77, v76, v77, v89
	v_med3_f32 v76, v75, v76, v89
	v_med3_f32 v75, v74, v75, v89
	v_med3_f32 v74, v73, v74, v89
	v_max_f32_e32 v89, v89, v89
	v_max_f32_e32 v73, v73, v89
	v_and_b32_e32 v89, 0xffff0000, v91
	v_add3_u32 v89, s1, v89, -12
	v_med3_f32 v88, v87, v88, v89
	v_med3_f32 v87, v86, v87, v89
	v_med3_f32 v86, v85, v86, v89
	v_med3_f32 v85, v84, v85, v89
	v_med3_f32 v84, v83, v84, v89
	v_med3_f32 v83, v82, v83, v89
	v_med3_f32 v82, v81, v82, v89
	v_med3_f32 v81, v80, v81, v89
	v_med3_f32 v80, v79, v80, v89
	v_med3_f32 v79, v78, v79, v89
	v_med3_f32 v78, v77, v78, v89
	v_med3_f32 v77, v76, v77, v89
	v_med3_f32 v76, v75, v76, v89
	v_med3_f32 v75, v74, v75, v89
	v_med3_f32 v74, v73, v74, v89
	v_max_f32_e32 v89, v89, v89
	v_max_f32_e32 v73, v73, v89
	v_lshlrev_b32_e32 v89, 16, v92
	v_add3_u32 v89, s1, v89, -11
	v_med3_f32 v88, v87, v88, v89
	v_med3_f32 v87, v86, v87, v89
	v_med3_f32 v86, v85, v86, v89
	v_med3_f32 v85, v84, v85, v89
	v_med3_f32 v84, v83, v84, v89
	v_med3_f32 v83, v82, v83, v89
	v_med3_f32 v82, v81, v82, v89
	v_med3_f32 v81, v80, v81, v89
	v_med3_f32 v80, v79, v80, v89
	v_med3_f32 v79, v78, v79, v89
	v_med3_f32 v78, v77, v78, v89
	v_med3_f32 v77, v76, v77, v89
	v_med3_f32 v76, v75, v76, v89
	v_med3_f32 v75, v74, v75, v89
	v_med3_f32 v74, v73, v74, v89
	v_max_f32_e32 v89, v89, v89
	v_max_f32_e32 v73, v73, v89
	v_and_b32_e32 v89, 0xffff0000, v92
	v_add3_u32 v89, s1, v89, -10
	v_med3_f32 v88, v87, v88, v89
	v_med3_f32 v87, v86, v87, v89
	v_med3_f32 v86, v85, v86, v89
	v_med3_f32 v85, v84, v85, v89
	v_med3_f32 v84, v83, v84, v89
	v_med3_f32 v83, v82, v83, v89
	v_med3_f32 v82, v81, v82, v89
	v_med3_f32 v81, v80, v81, v89
	v_med3_f32 v80, v79, v80, v89
	v_med3_f32 v79, v78, v79, v89
	v_med3_f32 v78, v77, v78, v89
	v_med3_f32 v77, v76, v77, v89
	v_med3_f32 v76, v75, v76, v89
	v_med3_f32 v75, v74, v75, v89
	v_med3_f32 v74, v73, v74, v89
	v_max_f32_e32 v89, v89, v89
	v_max_f32_e32 v73, v73, v89
	v_lshlrev_b32_e32 v89, 16, v93
	v_add3_u32 v89, s1, v89, -9
	v_med3_f32 v88, v87, v88, v89
	v_med3_f32 v87, v86, v87, v89
	v_med3_f32 v86, v85, v86, v89
	v_med3_f32 v85, v84, v85, v89
	v_med3_f32 v84, v83, v84, v89
	v_med3_f32 v83, v82, v83, v89
	v_med3_f32 v82, v81, v82, v89
	v_med3_f32 v81, v80, v81, v89
	v_med3_f32 v80, v79, v80, v89
	v_med3_f32 v79, v78, v79, v89
	v_med3_f32 v78, v77, v78, v89
	v_med3_f32 v77, v76, v77, v89
	v_med3_f32 v76, v75, v76, v89
	v_med3_f32 v75, v74, v75, v89
	v_med3_f32 v74, v73, v74, v89
	v_max_f32_e32 v89, v89, v89
	v_max_f32_e32 v73, v73, v89
	v_and_b32_e32 v89, 0xffff0000, v93
	v_add3_u32 v89, s1, v89, -8
	v_med3_f32 v88, v87, v88, v89
	v_med3_f32 v87, v86, v87, v89
	v_med3_f32 v86, v85, v86, v89
	v_med3_f32 v85, v84, v85, v89
	v_med3_f32 v84, v83, v84, v89
	v_med3_f32 v83, v82, v83, v89
	v_med3_f32 v82, v81, v82, v89
	v_med3_f32 v81, v80, v81, v89
	v_med3_f32 v80, v79, v80, v89
	v_med3_f32 v79, v78, v79, v89
	v_med3_f32 v78, v77, v78, v89
	v_med3_f32 v77, v76, v77, v89
	v_med3_f32 v76, v75, v76, v89
	v_med3_f32 v75, v74, v75, v89
	v_med3_f32 v74, v73, v74, v89
	v_max_f32_e32 v89, v89, v89
	v_max_f32_e32 v73, v73, v89
	v_lshlrev_b32_e32 v89, 16, v64
	v_add3_u32 v89, s1, v89, -7
	v_med3_f32 v88, v87, v88, v89
	v_med3_f32 v87, v86, v87, v89
	v_med3_f32 v86, v85, v86, v89
	v_med3_f32 v85, v84, v85, v89
	v_med3_f32 v84, v83, v84, v89
	v_med3_f32 v83, v82, v83, v89
	v_med3_f32 v82, v81, v82, v89
	v_med3_f32 v81, v80, v81, v89
	v_med3_f32 v80, v79, v80, v89
	v_med3_f32 v79, v78, v79, v89
	v_med3_f32 v78, v77, v78, v89
	v_med3_f32 v77, v76, v77, v89
	v_med3_f32 v76, v75, v76, v89
	v_med3_f32 v75, v74, v75, v89
	v_med3_f32 v74, v73, v74, v89
	v_max_f32_e32 v89, v89, v89
	v_and_b32_e32 v64, 0xffff0000, v64
; __device__ __forceinline__ void peer_phase(const Params& p, int layer, char* lds, bool last) {
;     ...
;       for (int i8 = 0; i8 < 16; ++i8) { const u32x4 v4 = sp[i8];
; #pragma unroll
;         for (int e = 0; e < 4; ++e) { float v = __uint_as_float((v4[e] << 16) | (unsigned)(i8 * 8 + e * 2)); CE16(top, v);
;           v = __uint_as_float((v4[e] & 0xffff0000u) | (unsigned)(i8 * 8 + e * 2 + 1)); CE16(top, v); } }
; #pragma unroll
;       for (int i = 0; i < 16; ++i) L1[i * 512 + tok * 16 + hc] = __float_as_uint(top[i]);
;     }
;     __syncthreads();
;     if (tid < 256) {
	v_max_f32_e32 v73, v73, v89
	v_add3_u32 v64, s1, v64, -6
	v_med3_f32 v88, v87, v88, v64
	v_med3_f32 v87, v86, v87, v64
	v_med3_f32 v86, v85, v86, v64
	v_med3_f32 v85, v84, v85, v64
	v_med3_f32 v84, v83, v84, v64
	v_med3_f32 v83, v82, v83, v64
	v_med3_f32 v82, v81, v82, v64
	v_med3_f32 v81, v80, v81, v64
	v_med3_f32 v80, v79, v80, v64
	v_med3_f32 v79, v78, v79, v64
	v_med3_f32 v78, v77, v78, v64
	v_med3_f32 v77, v76, v77, v64
	v_med3_f32 v76, v75, v76, v64
	v_med3_f32 v75, v74, v75, v64
	v_med3_f32 v74, v73, v74, v64
	v_max_f32_e32 v64, v64, v64
	v_max_f32_e32 v64, v73, v64
	v_lshlrev_b32_e32 v73, 16, v65
	v_add3_u32 v73, s1, v73, -5
	v_med3_f32 v88, v87, v88, v73
	v_med3_f32 v87, v86, v87, v73
	v_med3_f32 v86, v85, v86, v73
	v_med3_f32 v85, v84, v85, v73
	v_med3_f32 v84, v83, v84, v73
	v_med3_f32 v83, v82, v83, v73
	v_med3_f32 v82, v81, v82, v73
	v_med3_f32 v81, v80, v81, v73
	v_med3_f32 v80, v79, v80, v73
	v_med3_f32 v79, v78, v79, v73
	v_med3_f32 v78, v77, v78, v73
	v_med3_f32 v77, v76, v77, v73
	v_med3_f32 v76, v75, v76, v73
	v_med3_f32 v75, v74, v75, v73
	v_med3_f32 v74, v64, v74, v73
	v_max_f32_e32 v73, v73, v73
	v_and_b32_e32 v65, 0xffff0000, v65
	v_max_f32_e32 v64, v64, v73
	v_add3_u32 v65, s1, v65, -4
	v_med3_f32 v73, v87, v88, v65
	v_med3_f32 v87, v86, v87, v65
	v_med3_f32 v86, v85, v86, v65
	v_med3_f32 v85, v84, v85, v65
	v_med3_f32 v84, v83, v84, v65
	v_med3_f32 v83, v82, v83, v65
	v_med3_f32 v82, v81, v82, v65
	v_med3_f32 v81, v80, v81, v65
	v_med3_f32 v80, v79, v80, v65
	v_med3_f32 v79, v78, v79, v65
	v_med3_f32 v78, v77, v78, v65
	v_med3_f32 v77, v76, v77, v65
	v_med3_f32 v76, v75, v76, v65
	v_med3_f32 v75, v74, v75, v65
	v_med3_f32 v74, v64, v74, v65
	v_max_f32_e32 v65, v65, v65
	v_max_f32_e32 v64, v64, v65
	v_lshlrev_b32_e32 v65, 16, v66
	v_add3_u32 v65, s1, v65, -3
	v_med3_f32 v73, v87, v73, v65
	v_med3_f32 v87, v86, v87, v65
	v_med3_f32 v86, v85, v86, v65
	v_med3_f32 v85, v84, v85, v65
	v_med3_f32 v84, v83, v84, v65
	v_med3_f32 v83, v82, v83, v65
	v_med3_f32 v82, v81, v82, v65
	v_med3_f32 v81, v80, v81, v65
	v_med3_f32 v80, v79, v80, v65
	v_med3_f32 v79, v78, v79, v65
	v_med3_f32 v78, v77, v78, v65
	v_med3_f32 v77, v76, v77, v65
	v_med3_f32 v76, v75, v76, v65
	v_med3_f32 v75, v74, v75, v65
	v_med3_f32 v74, v64, v74, v65
	v_max_f32_e32 v65, v65, v65
	v_max_f32_e32 v64, v64, v65
	v_and_b32_e32 v65, 0xffff0000, v66
	v_add3_u32 v65, s1, v65, -2
	v_med3_f32 v66, v87, v73, v65
	v_med3_f32 v73, v86, v87, v65
	v_med3_f32 v86, v85, v86, v65
	v_med3_f32 v85, v84, v85, v65
	v_med3_f32 v84, v83, v84, v65
	v_med3_f32 v83, v82, v83, v65
	v_med3_f32 v82, v81, v82, v65
	v_med3_f32 v81, v80, v81, v65
	v_med3_f32 v80, v79, v80, v65
	v_med3_f32 v79, v78, v79, v65
	v_med3_f32 v78, v77, v78, v65
	v_med3_f32 v77, v76, v77, v65
	v_med3_f32 v76, v75, v76, v65
	v_med3_f32 v75, v74, v75, v65
	v_med3_f32 v74, v64, v74, v65
	v_max_f32_e32 v65, v65, v65
	v_max_f32_e32 v64, v64, v65
	v_lshlrev_b32_e32 v65, 16, v67
	v_add3_u32 v65, s1, v65, -1
	v_med3_f32 v66, v73, v66, v65
	v_med3_f32 v73, v86, v73, v65
	v_med3_f32 v86, v85, v86, v65
	v_med3_f32 v85, v84, v85, v65
	v_med3_f32 v84, v83, v84, v65
	v_med3_f32 v83, v82, v83, v65
	v_med3_f32 v82, v81, v82, v65
	v_med3_f32 v81, v80, v81, v65
	v_med3_f32 v80, v79, v80, v65
	v_med3_f32 v79, v78, v79, v65
	v_med3_f32 v78, v77, v78, v65
	v_med3_f32 v77, v76, v77, v65
	v_med3_f32 v76, v75, v76, v65
	v_med3_f32 v75, v74, v75, v65
	v_med3_f32 v74, v64, v74, v65
	v_max_f32_e32 v65, v65, v65
	v_max_f32_e32 v64, v64, v65
	v_and_b32_e32 v65, 0xffff0000, v67
	v_add_u32_e32 v65, s1, v65
	v_med3_f32 v88, v73, v66, v65
	v_med3_f32 v87, v86, v73, v65
	v_med3_f32 v86, v85, v86, v65
	v_med3_f32 v85, v84, v85, v65
	v_med3_f32 v84, v83, v84, v65
	v_med3_f32 v83, v82, v83, v65
	v_med3_f32 v82, v81, v82, v65
	v_med3_f32 v81, v80, v81, v65
	v_med3_f32 v80, v79, v80, v65
	v_med3_f32 v79, v78, v79, v65
	v_med3_f32 v78, v77, v78, v65
	v_med3_f32 v77, v76, v77, v65
	v_med3_f32 v76, v75, v76, v65
	v_med3_f32 v75, v74, v75, v65
	v_med3_f32 v74, v64, v74, v65
	v_max_f32_e32 v65, v65, v65
	s_add_i32 s1, s1, 16
	v_max_f32_e32 v73, v64, v65
	s_cmpk_eq_i32 s1, 0x8f
	s_cbranch_scc0 .LBB0_165
	s_mov_b32 s1, 0x3ffffff0
	v_and_or_b32 v64, v71, s1, v72
	s_movk_i32 s1, 0x100
	v_lshlrev_b32_e32 v64, 2, v64
	v_cmp_gt_i32_e32 vcc, s1, v71
	ds_write2st64_b32 v64, v73, v74 offset1:8
	ds_write2st64_b32 v64, v75, v76 offset0:16 offset1:24
	ds_write2st64_b32 v64, v77, v78 offset0:32 offset1:40
	ds_write2st64_b32 v64, v79, v80 offset0:48 offset1:56
	ds_write2st64_b32 v64, v81, v82 offset0:64 offset1:72
	ds_write2st64_b32 v64, v83, v84 offset0:80 offset1:88
	ds_write2st64_b32 v64, v85, v86 offset0:96 offset1:104
	ds_write2st64_b32 v64, v87, v88 offset0:112 offset1:120
	s_waitcnt lgkmcnt(0)
	s_barrier
	s_and_saveexec_b64 s[4:5], vcc
	s_cbranch_execz .LBB0_168
; __device__ __forceinline__ void peer_phase(const Params& p, int layer, char* lds, bool last) {
;     ...
;     if (tid < 256) {
;       const int tok = tid >> 3, h = tid & 7;
;       const unsigned* l0 = L1 + tok * 16 + h * 2; const unsigned* l1 = l0 + 1;
;       float a[16], b[16], top[16];
; #pragma unroll
;       for (int i = 0; i < 16; ++i) { a[i] = __uint_as_float(l0[i * 512] & ~127u); b[i] = __uint_as_float(l1[i * 512] & ~127u); top[i] = -3.0e38f; }
; #pragma unroll
;       for (int i = 0; i < 16; ++i)
; #pragma unroll
;         for (int j = 0; j < 16; ++j)
;           if ((i + 1) * (j + 1) <= 16) { float v = __uint_as_float((__float_as_uint(a[i] + b[j]) & ~255u) | (unsigned)(i * 16 + j)); CE16(top, v); }
	v_and_b32_e32 v83, 7, v70
	v_ashrrev_i32_e32 v82, 3, v71
	v_lshlrev_b32_e32 v64, 3, v83
	v_lshl_or_b32 v84, v82, 6, v64
	ds_read2st64_b64 v[64:67], v84 offset1:4
	ds_read2st64_b64 v[90:93], v84 offset0:56 offset1:60
	ds_read2st64_b64 v[94:97], v84 offset0:8 offset1:12
	ds_read2st64_b64 v[86:89], v84 offset0:48 offset1:52
	ds_read2st64_b64 v[98:101], v84 offset0:16 offset1:20
	s_waitcnt lgkmcnt(4)
	v_and_b32_e32 v69, 0xffffff80, v65
	v_and_b32_e32 v65, 0xffffff80, v64
	v_add_f32_e32 v64, v69, v65
	v_and_b32_e32 v116, 0xffffff00, v64
	v_and_b32_e32 v102, 0xffffff80, v67
	v_max_f32_e32 v64, v116, v116
	v_max_f32_e32 v117, 0xff61b1e6, v64
	v_add_f32_e32 v64, v65, v102
	v_and_or_b32 v118, v64, s93, 1
	s_waitcnt lgkmcnt(3)
	v_and_b32_e32 v68, 0xffffff80, v92
	v_max_f32_e32 v64, v118, v118
	s_waitcnt lgkmcnt(2)
	v_and_b32_e32 v92, 0xffffff80, v95
	v_max_f32_e32 v119, v117, v64
	v_add_f32_e32 v64, v65, v92
	v_and_or_b32 v120, v64, s93, 2
	s_waitcnt lgkmcnt(1)
	v_and_b32_e32 v114, 0xffffff80, v88
	v_max_f32_e32 v64, v120, v120
	v_and_b32_e32 v88, 0xffffff80, v97
	ds_read2st64_b64 v[74:77], v84 offset0:32 offset1:36
	v_max_f32_e32 v121, v119, v64
	v_add_f32_e32 v64, v65, v88
	v_and_or_b32 v122, v64, s93, 3
	v_max_f32_e32 v64, v122, v122
	s_waitcnt lgkmcnt(1)
	v_and_b32_e32 v85, 0xffffff80, v99
	ds_read2st64_b64 v[70:73], v84 offset0:24 offset1:28
	ds_read2st64_b64 v[78:81], v84 offset0:40 offset1:44
	v_max_f32_e32 v123, v121, v64
	v_add_f32_e32 v64, v65, v85
	v_and_or_b32 v124, v64, s93, 4
	s_waitcnt lgkmcnt(2)
	v_and_b32_e32 v105, 0xffffff80, v74
	v_max_f32_e32 v64, v124, v124
	v_and_b32_e32 v74, 0xffffff80, v101
	v_max_f32_e32 v125, v123, v64
	v_add_f32_e32 v64, v65, v74
	v_and_or_b32 v126, v64, s93, 5
	s_waitcnt lgkmcnt(0)
	v_and_b32_e32 v107, 0xffffff80, v78
	v_max_f32_e32 v64, v126, v126
	v_and_b32_e32 v78, 0xffffff80, v71
	v_max_f32_e32 v127, v125, v64
	v_add_f32_e32 v64, v65, v78
	v_and_or_b32 v128, v64, s93, 6
	v_and_b32_e32 v109, 0xffffff80, v80
	v_max_f32_e32 v64, v128, v128
	v_and_b32_e32 v80, 0xffffff80, v73
	v_max_f32_e32 v129, v127, v64
	v_add_f32_e32 v64, v65, v80
	v_and_or_b32 v113, v64, s93, 7
	v_max_f32_e32 v64, v113, v113
	v_max_f32_e32 v130, v129, v64
	v_and_b32_e32 v64, 0xffffff80, v75
	v_add_f32_e32 v64, v65, v64
	v_and_or_b32 v111, v64, s93, 8
	v_max_f32_e32 v64, v111, v111
	v_max_f32_e32 v131, v130, v64
	v_and_b32_e32 v64, 0xffffff80, v77
	v_add_f32_e32 v64, v65, v64
	v_and_or_b32 v110, v64, s93, 9
	v_max_f32_e32 v64, v110, v110
	v_max_f32_e32 v132, v131, v64
	v_and_b32_e32 v64, 0xffffff80, v79
	v_add_f32_e32 v64, v65, v64
	v_and_or_b32 v108, v64, s93, 10
	v_max_f32_e32 v64, v108, v108
	v_max_f32_e32 v133, v132, v64
	v_and_b32_e32 v64, 0xffffff80, v81
	v_add_f32_e32 v64, v65, v64
	v_and_or_b32 v99, v64, s93, 11
	v_max_f32_e32 v64, v99, v99
	v_max_f32_e32 v134, v133, v64
	v_and_b32_e32 v64, 0xffffff80, v87
	v_add_f32_e32 v64, v65, v64
	v_and_b32_e32 v115, 0xffffff80, v90
	v_and_or_b32 v90, v64, s93, 12
	v_max_f32_e32 v64, v90, v90
	v_max_f32_e32 v135, v134, v64
	v_and_b32_e32 v64, 0xffffff80, v89
	v_add_f32_e32 v64, v65, v64
	v_and_b32_e32 v106, 0xffffff80, v76
	v_and_or_b32 v76, v64, s93, 13
	v_max_f32_e32 v64, v76, v76
	v_max_f32_e32 v136, v135, v64
	v_and_b32_e32 v64, 0xffffff80, v91
	v_add_f32_e32 v64, v65, v64
	v_and_or_b32 v64, v64, s93, 14
	v_max_f32_e32 v67, v64, v64
	v_max_f32_e32 v137, v136, v67
	v_and_b32_e32 v67, 0xffffff80, v93
	v_add_f32_e32 v65, v65, v67
	v_and_b32_e32 v75, 0xffffff80, v66
	v_and_or_b32 v65, v65, s93, 15
	v_add_f32_e32 v66, v69, v75
	v_max_f32_e32 v67, v65, v65
	v_and_or_b32 v66, v66, s93, 16
	v_max_f32_e32 v138, v137, v67
	v_max_f32_e32 v67, v66, v66
	v_max_f32_e32 v139, v138, v67
	v_add_f32_e32 v67, v75, v102
	v_and_or_b32 v67, v67, s93, 17
	v_and_b32_e32 v103, 0xffffff80, v70
	v_max_f32_e32 v70, v67, v67
	v_max_f32_e32 v140, v139, v70
	v_add_f32_e32 v70, v75, v92
	v_and_or_b32 v70, v70, s93, 18
	v_max_f32_e32 v71, v70, v70
	v_max_f32_e32 v141, v140, v71
	v_add_f32_e32 v71, v75, v88
	v_and_or_b32 v71, v71, s93, 19
	v_and_b32_e32 v104, 0xffffff80, v72
	v_max_f32_e32 v72, v71, v71
	v_max_f32_e32 v142, v141, v72
	v_add_f32_e32 v72, v75, v85
	v_and_or_b32 v72, v72, s93, 20
	v_max_f32_e32 v73, v72, v72
	v_max_f32_e32 v143, v142, v73
	v_add_f32_e32 v73, v75, v74
	v_and_or_b32 v73, v73, s93, 21
	v_max_f32_e32 v74, v73, v73
	v_max_f32_e32 v144, v143, v74
	v_add_f32_e32 v74, v75, v78
	v_and_or_b32 v74, v74, s93, 22
	v_add_f32_e32 v75, v75, v80
	v_max_f32_e32 v77, v74, v74
	v_and_or_b32 v75, v75, s93, 23
	v_max_f32_e32 v145, v144, v77
	v_max_f32_e32 v77, v75, v75
	v_and_b32_e32 v81, 0xffffff80, v94
	v_max_f32_e32 v146, v145, v77
	v_add_f32_e32 v77, v69, v81
	v_and_or_b32 v77, v77, s93, 32
	v_max_f32_e32 v78, v77, v77
	v_max_f32_e32 v147, v146, v78
	v_add_f32_e32 v78, v102, v81
	v_and_or_b32 v78, v78, s93, 33
	v_max_f32_e32 v79, v78, v78
	v_max_f32_e32 v148, v147, v79
	v_add_f32_e32 v79, v81, v92
	v_and_or_b32 v79, v79, s93, 34
	v_max_f32_e32 v80, v79, v79
	v_max_f32_e32 v149, v148, v80
	v_add_f32_e32 v80, v81, v88
	v_and_or_b32 v80, v80, s93, 35
	v_add_f32_e32 v81, v81, v85
	v_and_b32_e32 v112, 0xffffff80, v86
	v_max_f32_e32 v86, v80, v80
	v_and_or_b32 v81, v81, s93, 36
	v_max_f32_e32 v150, v149, v86
	v_max_f32_e32 v85, v81, v81
	v_and_b32_e32 v89, 0xffffff80, v96
	v_max_f32_e32 v151, v150, v85
	v_add_f32_e32 v85, v69, v89
	v_and_or_b32 v85, v85, s93, 48
	v_max_f32_e32 v86, v85, v85
	v_max_f32_e32 v152, v151, v86
	v_add_f32_e32 v86, v102, v89
	v_and_or_b32 v86, v86, s93, 49
	v_max_f32_e32 v87, v86, v86
	v_max_f32_e32 v153, v152, v87
	v_add_f32_e32 v87, v92, v89
	v_and_or_b32 v87, v87, s93, 50
; __device__ __forceinline__ void peer_phase(const Params& p, int layer, char* lds, bool last) {
;     ...
;       for (int i = 0; i < 16; ++i) { a[i] = __uint_as_float(l0[i * 512] & ~127u); b[i] = __uint_as_float(l1[i * 512] & ~127u); top[i] = -3.0e38f; }
; #pragma unroll
;       for (int i = 0; i < 16; ++i)
; #pragma unroll
;         for (int j = 0; j < 16; ++j)
;           if ((i + 1) * (j + 1) <= 16) { float v = __uint_as_float((__float_as_uint(a[i] + b[j]) & ~255u) | (unsigned)(i * 16 + j)); CE16(top, v); }
	v_add_f32_e32 v88, v89, v88
	v_max_f32_e32 v91, v87, v87
	v_and_or_b32 v88, v88, s93, 51
	v_max_f32_e32 v154, v153, v91
	v_max_f32_e32 v89, v88, v88
	v_and_b32_e32 v93, 0xffffff80, v98
	v_max_f32_e32 v155, v154, v89
	v_add_f32_e32 v89, v69, v93
	v_and_or_b32 v89, v89, s93, 64
	v_max_f32_e32 v91, v89, v89
	v_max_f32_e32 v156, v155, v91
	v_add_f32_e32 v91, v102, v93
	v_and_b32_e32 v91, 0xffffff00, v91
	v_add_f32_e32 v92, v92, v93
	v_or_b32_e32 v91, 0x41, v91
	v_and_b32_e32 v92, 0xffffff00, v92
	v_max_f32_e32 v94, v91, v91
	v_or_b32_e32 v92, 0x42, v92
	v_max_f32_e32 v157, v156, v94
	v_max_f32_e32 v93, v92, v92
	v_and_b32_e32 v94, 0xffffff80, v100
	v_max_f32_e32 v158, v157, v93
	v_add_f32_e32 v93, v69, v94
	v_and_b32_e32 v93, 0xffffff00, v93
	v_add_f32_e32 v94, v94, v102
	v_or_b32_e32 v93, 0x50, v93
	v_and_b32_e32 v94, 0xffffff00, v94
	v_max_f32_e32 v95, v93, v93
	v_or_b32_e32 v94, 0x51, v94
	v_max_f32_e32 v159, v158, v95
	v_max_f32_e32 v95, v94, v94
	v_max_f32_e32 v160, v159, v95
	v_add_f32_e32 v95, v69, v103
	v_and_b32_e32 v95, 0xffffff00, v95
	v_or_b32_e32 v95, 0x60, v95
	v_max_f32_e32 v96, v95, v95
	v_max_f32_e32 v161, v160, v96
	v_add_f32_e32 v96, v103, v102
	v_and_b32_e32 v96, 0xffffff00, v96
	v_or_b32_e32 v96, 0x61, v96
	v_max_f32_e32 v97, v96, v96
	v_max_f32_e32 v162, v161, v97
	v_add_f32_e32 v97, v69, v104
	v_and_b32_e32 v97, 0xffffff00, v97
	v_or_b32_e32 v97, 0x70, v97
	v_max_f32_e32 v98, v97, v97
	v_max_f32_e32 v163, v162, v98
	v_add_f32_e32 v98, v104, v102
	v_and_b32_e32 v98, 0xffffff00, v98
	v_or_b32_e32 v98, 0x71, v98
	v_max_f32_e32 v100, v98, v98
	v_max_f32_e32 v164, v163, v100
	v_add_f32_e32 v100, v69, v105
	v_and_b32_e32 v100, 0xffffff00, v100
	v_or_b32_e32 v100, 0x80, v100
	v_max_f32_e32 v101, v100, v100
	v_max_f32_e32 v165, v164, v101
	v_add_f32_e32 v101, v69, v106
	v_and_b32_e32 v101, 0xffffff00, v101
	v_or_b32_e32 v101, 0x90, v101
	v_max_f32_e32 v102, v101, v101
	v_max_f32_e32 v166, v165, v102
	v_add_f32_e32 v102, v69, v107
	v_and_b32_e32 v102, 0xffffff00, v102
	v_or_b32_e32 v103, 0xa0, v102
	v_max_f32_e32 v102, v103, v103
	v_max_f32_e32 v167, v166, v102
	v_add_f32_e32 v102, v69, v109
	v_and_b32_e32 v102, 0xffffff00, v102
	v_or_b32_e32 v104, 0xb0, v102
	v_max_f32_e32 v102, v104, v104
	v_max_f32_e32 v109, v167, v102
	v_add_f32_e32 v102, v69, v112
	v_and_b32_e32 v102, 0xffffff00, v102
	v_or_b32_e32 v105, 0xc0, v102
	v_max_f32_e32 v102, v105, v105
	v_max_f32_e32 v112, v109, v102
	v_add_f32_e32 v102, v69, v114
	v_and_b32_e32 v102, 0xffffff00, v102
	v_or_b32_e32 v106, 0xd0, v102
	v_max_f32_e32 v102, v106, v106
	s_mov_b32 s1, 0xff61b1e6
	v_max_f32_e32 v114, v112, v102
	v_add_f32_e32 v102, v69, v115
	v_med3_f32 v115, v116, s1, s1
	v_med3_f32 v116, v117, v115, v118
	v_med3_f32 v117, v119, v116, v120
	v_med3_f32 v119, v121, v117, v122
	v_med3_f32 v121, v123, v119, v124
	v_med3_f32 v123, v125, v121, v126
	v_med3_f32 v125, v127, v123, v128
	v_med3_f32 v127, v129, v125, v113
	v_med3_f32 v129, v130, v127, v111
	v_med3_f32 v130, v131, v129, v110
	v_med3_f32 v131, v132, v130, v108
	v_med3_f32 v132, v133, v131, v99
	v_med3_f32 v133, v134, v132, v90
	v_med3_f32 v134, v135, v133, v76
	v_med3_f32 v135, v136, v134, v64
	v_med3_f32 v136, v137, v135, v65
	v_med3_f32 v137, v138, v136, v66
	v_med3_f32 v138, v139, v137, v67
	v_med3_f32 v139, v140, v138, v70
	v_med3_f32 v140, v141, v139, v71
	v_med3_f32 v141, v142, v140, v72
	v_med3_f32 v142, v143, v141, v73
	v_med3_f32 v143, v144, v142, v74
	v_med3_f32 v144, v145, v143, v75
	v_med3_f32 v145, v146, v144, v77
	v_med3_f32 v146, v147, v145, v78
	v_med3_f32 v147, v148, v146, v79
	v_med3_f32 v148, v149, v147, v80
	v_med3_f32 v149, v150, v148, v81
	v_med3_f32 v150, v151, v149, v85
	v_med3_f32 v151, v152, v150, v86
	v_med3_f32 v152, v153, v151, v87
	v_med3_f32 v153, v154, v152, v88
	v_med3_f32 v154, v155, v153, v89
	v_med3_f32 v155, v156, v154, v91
	v_med3_f32 v156, v157, v155, v92
	v_med3_f32 v157, v158, v156, v93
	v_med3_f32 v158, v159, v157, v94
	v_med3_f32 v159, v160, v158, v95
	v_med3_f32 v160, v161, v159, v96
	v_med3_f32 v161, v162, v160, v97
	v_med3_f32 v162, v163, v161, v98
	v_med3_f32 v163, v164, v162, v100
	v_med3_f32 v164, v165, v163, v101
	v_med3_f32 v165, v166, v164, v103
	v_and_b32_e32 v102, 0xffffff00, v102
	v_med3_f32 v166, v167, v165, v104
	v_or_b32_e32 v107, 0xe0, v102
	v_med3_f32 v167, v109, v166, v105
	v_max_f32_e32 v102, v107, v107
	v_med3_f32 v112, v112, v167, v106
	v_max_f32_e32 v102, v114, v102
	v_med3_f32 v109, v114, v112, v107
	v_med3_f32 v114, v115, v115, v118
	v_med3_f32 v115, v116, v114, v120
	v_med3_f32 v114, v114, v114, v120
	v_med3_f32 v116, v117, v115, v122
	v_med3_f32 v115, v115, v114, v122
	v_med3_f32 v114, v114, v114, v122
	v_med3_f32 v117, v119, v116, v124
	v_med3_f32 v116, v116, v115, v124
	v_med3_f32 v115, v115, v114, v124
	v_med3_f32 v114, v114, v114, v124
	v_med3_f32 v118, v121, v117, v126
	v_med3_f32 v117, v117, v116, v126
	v_med3_f32 v116, v116, v115, v126
	v_med3_f32 v115, v115, v114, v126
	v_med3_f32 v114, v114, v114, v126
	v_med3_f32 v119, v123, v118, v128
	v_med3_f32 v118, v118, v117, v128
	v_med3_f32 v117, v117, v116, v128
	v_med3_f32 v116, v116, v115, v128
	v_med3_f32 v115, v115, v114, v128
	v_med3_f32 v114, v114, v114, v128
	v_med3_f32 v121, v125, v119, v113
	v_med3_f32 v119, v119, v118, v113
	v_med3_f32 v118, v118, v117, v113
	v_med3_f32 v117, v117, v116, v113
	v_med3_f32 v116, v116, v115, v113
	v_med3_f32 v115, v115, v114, v113
	v_med3_f32 v113, v114, v114, v113
	v_med3_f32 v123, v127, v121, v111
	v_med3_f32 v120, v121, v119, v111
	v_med3_f32 v119, v119, v118, v111
	v_med3_f32 v118, v118, v117, v111
	v_med3_f32 v117, v117, v116, v111
; __device__ __forceinline__ void peer_phase(const Params& p, int layer, char* lds, bool last) {
;     ...
;           if ((i + 1) * (j + 1) <= 16) { float v = __uint_as_float((__float_as_uint(a[i] + b[j]) & ~255u) | (unsigned)(i * 16 + j)); CE16(top, v); }
	v_med3_f32 v116, v116, v115, v111
	v_med3_f32 v114, v115, v113, v111
	v_med3_f32 v111, v113, v113, v111
	v_med3_f32 v125, v129, v123, v110
	v_med3_f32 v121, v123, v120, v110
	v_med3_f32 v120, v120, v119, v110
	v_med3_f32 v119, v119, v118, v110
	v_med3_f32 v118, v118, v117, v110
	v_med3_f32 v117, v117, v116, v110
	v_med3_f32 v115, v116, v114, v110
	v_med3_f32 v113, v114, v111, v110
	v_med3_f32 v110, v111, v111, v110
	v_med3_f32 v127, v130, v125, v108
	v_med3_f32 v123, v125, v121, v108
	v_med3_f32 v121, v121, v120, v108
	v_med3_f32 v120, v120, v119, v108
	v_med3_f32 v119, v119, v118, v108
	v_med3_f32 v118, v118, v117, v108
	v_med3_f32 v116, v117, v115, v108
	v_med3_f32 v114, v115, v113, v108
	v_med3_f32 v111, v113, v110, v108
	v_med3_f32 v108, v110, v110, v108
	v_med3_f32 v129, v131, v127, v99
	v_med3_f32 v125, v127, v123, v99
	v_med3_f32 v122, v123, v121, v99
	v_med3_f32 v121, v121, v120, v99
	v_med3_f32 v120, v120, v119, v99
	v_med3_f32 v119, v119, v118, v99
	v_med3_f32 v117, v118, v116, v99
	v_med3_f32 v115, v116, v114, v99
	v_med3_f32 v113, v114, v111, v99
	v_med3_f32 v110, v111, v108, v99
	v_med3_f32 v99, v108, v108, v99
	v_med3_f32 v130, v132, v129, v90
	v_med3_f32 v127, v129, v125, v90
	v_med3_f32 v123, v125, v122, v90
	v_med3_f32 v122, v122, v121, v90
	v_med3_f32 v121, v121, v120, v90
	v_med3_f32 v120, v120, v119, v90
	v_med3_f32 v118, v119, v117, v90
	v_med3_f32 v116, v117, v115, v90
	v_med3_f32 v114, v115, v113, v90
	v_med3_f32 v111, v113, v110, v90
	v_med3_f32 v108, v110, v99, v90
	v_med3_f32 v90, v99, v99, v90
	v_med3_f32 v131, v133, v130, v76
	v_med3_f32 v129, v130, v127, v76
	v_med3_f32 v125, v127, v123, v76
	v_med3_f32 v123, v123, v122, v76
	v_med3_f32 v122, v122, v121, v76
	v_med3_f32 v121, v121, v120, v76
	v_med3_f32 v119, v120, v118, v76
	v_med3_f32 v117, v118, v116, v76
	v_med3_f32 v115, v116, v114, v76
	v_med3_f32 v113, v114, v111, v76
	v_med3_f32 v110, v111, v108, v76
	v_med3_f32 v99, v108, v90, v76
	v_med3_f32 v76, v90, v90, v76
	v_med3_f32 v132, v134, v131, v64
	v_med3_f32 v130, v131, v129, v64
	v_med3_f32 v127, v129, v125, v64
	v_med3_f32 v124, v125, v123, v64
	v_med3_f32 v123, v123, v122, v64
	v_med3_f32 v122, v122, v121, v64
	v_med3_f32 v120, v121, v119, v64
	v_med3_f32 v118, v119, v117, v64
	v_med3_f32 v116, v117, v115, v64
	v_med3_f32 v114, v115, v113, v64
	v_med3_f32 v111, v113, v110, v64
	v_med3_f32 v108, v110, v99, v64
	v_med3_f32 v90, v99, v76, v64
	v_med3_f32 v64, v76, v76, v64
	v_med3_f32 v133, v135, v132, v65
	v_med3_f32 v131, v132, v130, v65
	v_med3_f32 v129, v130, v127, v65
	v_med3_f32 v125, v127, v124, v65
	v_med3_f32 v124, v124, v123, v65
	v_med3_f32 v123, v123, v122, v65
	v_med3_f32 v121, v122, v120, v65
	v_med3_f32 v119, v120, v118, v65
	v_med3_f32 v117, v118, v116, v65
	v_med3_f32 v115, v116, v114, v65
	v_med3_f32 v113, v114, v111, v65
	v_med3_f32 v110, v111, v108, v65
	v_med3_f32 v99, v108, v90, v65
	v_med3_f32 v64, v90, v64, v65
	v_med3_f32 v134, v136, v133, v66
	v_med3_f32 v132, v133, v131, v66
	v_med3_f32 v130, v131, v129, v66
	v_med3_f32 v127, v129, v125, v66
	v_med3_f32 v125, v125, v124, v66
	v_med3_f32 v124, v124, v123, v66
	v_med3_f32 v122, v123, v121, v66
	v_med3_f32 v120, v121, v119, v66
	v_med3_f32 v118, v119, v117, v66
	v_med3_f32 v116, v117, v115, v66
	v_med3_f32 v114, v115, v113, v66
	v_med3_f32 v111, v113, v110, v66
	v_med3_f32 v108, v110, v99, v66
	v_med3_f32 v64, v99, v64, v66
	v_med3_f32 v135, v137, v134, v67
	v_med3_f32 v133, v134, v132, v67
	v_med3_f32 v131, v132, v130, v67
	v_med3_f32 v129, v130, v127, v67
	v_med3_f32 v126, v127, v125, v67
	v_med3_f32 v125, v125, v124, v67
	v_med3_f32 v123, v124, v122, v67
	v_med3_f32 v121, v122, v120, v67
	v_med3_f32 v119, v120, v118, v67
	v_med3_f32 v117, v118, v116, v67
	v_med3_f32 v115, v116, v114, v67
	v_med3_f32 v113, v114, v111, v67
	v_med3_f32 v110, v111, v108, v67
	v_med3_f32 v64, v108, v64, v67
	v_med3_f32 v136, v138, v135, v70
	v_med3_f32 v134, v135, v133, v70
	v_med3_f32 v132, v133, v131, v70
	v_med3_f32 v130, v131, v129, v70
	v_med3_f32 v127, v129, v126, v70
	v_med3_f32 v126, v126, v125, v70
	v_med3_f32 v124, v125, v123, v70
	v_med3_f32 v122, v123, v121, v70
	v_med3_f32 v120, v121, v119, v70
	v_med3_f32 v118, v119, v117, v70
	v_med3_f32 v116, v117, v115, v70
	v_med3_f32 v114, v115, v113, v70
	v_med3_f32 v111, v113, v110, v70
	v_med3_f32 v64, v110, v64, v70
	v_med3_f32 v137, v139, v136, v71
	v_med3_f32 v135, v136, v134, v71
	v_med3_f32 v133, v134, v132, v71
	v_med3_f32 v131, v132, v130, v71
	v_med3_f32 v129, v130, v127, v71
	v_med3_f32 v127, v127, v126, v71
	v_med3_f32 v125, v126, v124, v71
	v_med3_f32 v123, v124, v122, v71
	v_med3_f32 v121, v122, v120, v71
	v_med3_f32 v119, v120, v118, v71
	v_med3_f32 v117, v118, v116, v71
	v_med3_f32 v115, v116, v114, v71
	v_med3_f32 v113, v114, v111, v71
	v_med3_f32 v64, v111, v64, v71
	v_med3_f32 v138, v140, v137, v72
	v_med3_f32 v136, v137, v135, v72
	v_med3_f32 v134, v135, v133, v72
	v_med3_f32 v132, v133, v131, v72
	v_med3_f32 v130, v131, v129, v72
	v_med3_f32 v128, v129, v127, v72
	v_med3_f32 v126, v127, v125, v72
	v_med3_f32 v124, v125, v123, v72
	v_med3_f32 v122, v123, v121, v72
	v_med3_f32 v120, v121, v119, v72
	v_med3_f32 v118, v119, v117, v72
	v_med3_f32 v116, v117, v115, v72
	v_med3_f32 v114, v115, v113, v72
	v_med3_f32 v64, v113, v64, v72
	v_med3_f32 v139, v141, v138, v73
	v_med3_f32 v137, v138, v136, v73
	v_med3_f32 v135, v136, v134, v73
	v_med3_f32 v133, v134, v132, v73
	v_med3_f32 v131, v132, v130, v73
	v_med3_f32 v129, v130, v128, v73
	v_med3_f32 v127, v128, v126, v73
	v_med3_f32 v125, v126, v124, v73
	v_med3_f32 v123, v124, v122, v73
	v_med3_f32 v121, v122, v120, v73
; __device__ __forceinline__ void peer_phase(const Params& p, int layer, char* lds, bool last) {
;     ...
;           if ((i + 1) * (j + 1) <= 16) { float v = __uint_as_float((__float_as_uint(a[i] + b[j]) & ~255u) | (unsigned)(i * 16 + j)); CE16(top, v); }
	v_med3_f32 v119, v120, v118, v73
	v_med3_f32 v117, v118, v116, v73
	v_med3_f32 v115, v116, v114, v73
	v_med3_f32 v64, v114, v64, v73
	v_med3_f32 v140, v142, v139, v74
	v_med3_f32 v138, v139, v137, v74
	v_med3_f32 v136, v137, v135, v74
	v_med3_f32 v134, v135, v133, v74
	v_med3_f32 v132, v133, v131, v74
	v_med3_f32 v130, v131, v129, v74
	v_med3_f32 v128, v129, v127, v74
	v_med3_f32 v126, v127, v125, v74
	v_med3_f32 v124, v125, v123, v74
	v_med3_f32 v122, v123, v121, v74
	v_med3_f32 v120, v121, v119, v74
	v_med3_f32 v118, v119, v117, v74
	v_med3_f32 v116, v117, v115, v74
	v_med3_f32 v64, v115, v64, v74
	v_med3_f32 v141, v143, v140, v75
	v_med3_f32 v139, v140, v138, v75
	v_med3_f32 v137, v138, v136, v75
	v_med3_f32 v135, v136, v134, v75
	v_med3_f32 v133, v134, v132, v75
	v_med3_f32 v131, v132, v130, v75
	v_med3_f32 v129, v130, v128, v75
	v_med3_f32 v127, v128, v126, v75
	v_med3_f32 v125, v126, v124, v75
	v_med3_f32 v123, v124, v122, v75
	v_med3_f32 v121, v122, v120, v75
	v_med3_f32 v119, v120, v118, v75
	v_med3_f32 v117, v118, v116, v75
	v_med3_f32 v64, v116, v64, v75
	v_med3_f32 v142, v144, v141, v77
	v_med3_f32 v140, v141, v139, v77
	v_med3_f32 v138, v139, v137, v77
	v_med3_f32 v136, v137, v135, v77
	v_med3_f32 v134, v135, v133, v77
	v_med3_f32 v132, v133, v131, v77
	v_med3_f32 v130, v131, v129, v77
	v_med3_f32 v128, v129, v127, v77
	v_med3_f32 v126, v127, v125, v77
	v_med3_f32 v124, v125, v123, v77
	v_med3_f32 v122, v123, v121, v77
	v_med3_f32 v120, v121, v119, v77
	v_med3_f32 v118, v119, v117, v77
	v_med3_f32 v64, v117, v64, v77
	v_med3_f32 v143, v145, v142, v78
	v_med3_f32 v141, v142, v140, v78
	v_med3_f32 v139, v140, v138, v78
	v_med3_f32 v137, v138, v136, v78
	v_med3_f32 v135, v136, v134, v78
	v_med3_f32 v133, v134, v132, v78
	v_med3_f32 v131, v132, v130, v78
	v_med3_f32 v129, v130, v128, v78
	v_med3_f32 v127, v128, v126, v78
	v_med3_f32 v125, v126, v124, v78
	v_med3_f32 v123, v124, v122, v78
	v_med3_f32 v121, v122, v120, v78
	v_med3_f32 v119, v120, v118, v78
	v_med3_f32 v64, v118, v64, v78
	v_med3_f32 v144, v146, v143, v79
	v_med3_f32 v142, v143, v141, v79
	v_med3_f32 v140, v141, v139, v79
	v_med3_f32 v138, v139, v137, v79
	v_med3_f32 v136, v137, v135, v79
	v_med3_f32 v134, v135, v133, v79
	v_med3_f32 v132, v133, v131, v79
	v_med3_f32 v130, v131, v129, v79
	v_med3_f32 v128, v129, v127, v79
	v_med3_f32 v126, v127, v125, v79
	v_med3_f32 v124, v125, v123, v79
	v_med3_f32 v122, v123, v121, v79
	v_med3_f32 v120, v121, v119, v79
	v_med3_f32 v64, v119, v64, v79
	v_med3_f32 v145, v147, v144, v80
	v_med3_f32 v143, v144, v142, v80
	v_med3_f32 v141, v142, v140, v80
	v_med3_f32 v139, v140, v138, v80
	v_med3_f32 v137, v138, v136, v80
	v_med3_f32 v135, v136, v134, v80
	v_med3_f32 v133, v134, v132, v80
	v_med3_f32 v131, v132, v130, v80
	v_med3_f32 v129, v130, v128, v80
	v_med3_f32 v127, v128, v126, v80
	v_med3_f32 v125, v126, v124, v80
	v_med3_f32 v123, v124, v122, v80
	v_med3_f32 v121, v122, v120, v80
	v_med3_f32 v64, v120, v64, v80
	v_med3_f32 v146, v148, v145, v81
	v_med3_f32 v144, v145, v143, v81
	v_med3_f32 v142, v143, v141, v81
	v_med3_f32 v140, v141, v139, v81
	v_med3_f32 v138, v139, v137, v81
	v_med3_f32 v136, v137, v135, v81
	v_med3_f32 v134, v135, v133, v81
	v_med3_f32 v132, v133, v131, v81
	v_med3_f32 v130, v131, v129, v81
	v_med3_f32 v128, v129, v127, v81
	v_med3_f32 v126, v127, v125, v81
	v_med3_f32 v124, v125, v123, v81
	v_med3_f32 v122, v123, v121, v81
	v_med3_f32 v64, v121, v64, v81
	v_med3_f32 v147, v149, v146, v85
	v_med3_f32 v145, v146, v144, v85
	v_med3_f32 v143, v144, v142, v85
	v_med3_f32 v141, v142, v140, v85
	v_med3_f32 v139, v140, v138, v85
	v_med3_f32 v137, v138, v136, v85
	v_med3_f32 v135, v136, v134, v85
	v_med3_f32 v133, v134, v132, v85
	v_med3_f32 v131, v132, v130, v85
	v_med3_f32 v129, v130, v128, v85
	v_med3_f32 v127, v128, v126, v85
	v_med3_f32 v125, v126, v124, v85
	v_med3_f32 v123, v124, v122, v85
	v_med3_f32 v64, v122, v64, v85
	v_med3_f32 v148, v150, v147, v86
	v_med3_f32 v146, v147, v145, v86
	v_med3_f32 v144, v145, v143, v86
	v_med3_f32 v142, v143, v141, v86
	v_med3_f32 v140, v141, v139, v86
	v_med3_f32 v138, v139, v137, v86
	v_med3_f32 v136, v137, v135, v86
	v_med3_f32 v134, v135, v133, v86
	v_med3_f32 v132, v133, v131, v86
	v_med3_f32 v130, v131, v129, v86
	v_med3_f32 v128, v129, v127, v86
	v_med3_f32 v126, v127, v125, v86
	v_med3_f32 v124, v125, v123, v86
	v_med3_f32 v64, v123, v64, v86
	v_med3_f32 v149, v151, v148, v87
	v_med3_f32 v147, v148, v146, v87
	v_med3_f32 v145, v146, v144, v87
	v_med3_f32 v143, v144, v142, v87
	v_med3_f32 v141, v142, v140, v87
	v_med3_f32 v139, v140, v138, v87
	v_med3_f32 v137, v138, v136, v87
	v_med3_f32 v135, v136, v134, v87
	v_med3_f32 v133, v134, v132, v87
	v_med3_f32 v131, v132, v130, v87
	v_med3_f32 v129, v130, v128, v87
	v_med3_f32 v127, v128, v126, v87
	v_med3_f32 v125, v126, v124, v87
	v_med3_f32 v64, v124, v64, v87
	v_med3_f32 v150, v152, v149, v88
	v_med3_f32 v148, v149, v147, v88
	v_med3_f32 v146, v147, v145, v88
	v_med3_f32 v144, v145, v143, v88
	v_med3_f32 v142, v143, v141, v88
	v_med3_f32 v140, v141, v139, v88
	v_med3_f32 v138, v139, v137, v88
	v_med3_f32 v136, v137, v135, v88
	v_med3_f32 v134, v135, v133, v88
	v_med3_f32 v132, v133, v131, v88
	v_med3_f32 v130, v131, v129, v88
	v_med3_f32 v128, v129, v127, v88
	v_med3_f32 v126, v127, v125, v88
	v_med3_f32 v64, v125, v64, v88
	v_med3_f32 v151, v153, v150, v89
	v_med3_f32 v149, v150, v148, v89
	v_med3_f32 v147, v148, v146, v89
	v_med3_f32 v145, v146, v144, v89
	v_med3_f32 v143, v144, v142, v89
	v_med3_f32 v141, v142, v140, v89
	v_med3_f32 v139, v140, v138, v89
	v_med3_f32 v137, v138, v136, v89
	v_med3_f32 v135, v136, v134, v89
; __device__ __forceinline__ void peer_phase(const Params& p, int layer, char* lds, bool last) {
;     ...
;           if ((i + 1) * (j + 1) <= 16) { float v = __uint_as_float((__float_as_uint(a[i] + b[j]) & ~255u) | (unsigned)(i * 16 + j)); CE16(top, v); }
	v_med3_f32 v133, v134, v132, v89
	v_med3_f32 v131, v132, v130, v89
	v_med3_f32 v129, v130, v128, v89
	v_med3_f32 v127, v128, v126, v89
	v_med3_f32 v64, v126, v64, v89
	v_med3_f32 v152, v154, v151, v91
	v_med3_f32 v150, v151, v149, v91
	v_med3_f32 v148, v149, v147, v91
	v_med3_f32 v146, v147, v145, v91
	v_med3_f32 v144, v145, v143, v91
	v_med3_f32 v142, v143, v141, v91
	v_med3_f32 v140, v141, v139, v91
	v_med3_f32 v138, v139, v137, v91
	v_med3_f32 v136, v137, v135, v91
	v_med3_f32 v134, v135, v133, v91
	v_med3_f32 v132, v133, v131, v91
	v_med3_f32 v130, v131, v129, v91
	v_med3_f32 v128, v129, v127, v91
	v_med3_f32 v64, v127, v64, v91
	v_med3_f32 v153, v155, v152, v92
	v_med3_f32 v151, v152, v150, v92
	v_med3_f32 v149, v150, v148, v92
	v_med3_f32 v147, v148, v146, v92
	v_med3_f32 v145, v146, v144, v92
	v_med3_f32 v143, v144, v142, v92
	v_med3_f32 v141, v142, v140, v92
	v_med3_f32 v139, v140, v138, v92
	v_med3_f32 v137, v138, v136, v92
	v_med3_f32 v135, v136, v134, v92
	v_med3_f32 v133, v134, v132, v92
	v_med3_f32 v131, v132, v130, v92
	v_med3_f32 v129, v130, v128, v92
	v_med3_f32 v64, v128, v64, v92
	v_med3_f32 v152, v153, v151, v93
	v_med3_f32 v150, v151, v149, v93
	v_med3_f32 v148, v149, v147, v93
	v_med3_f32 v146, v147, v145, v93
	v_med3_f32 v144, v145, v143, v93
	v_med3_f32 v142, v143, v141, v93
	v_med3_f32 v140, v141, v139, v93
	v_med3_f32 v138, v139, v137, v93
	v_med3_f32 v136, v137, v135, v93
	v_med3_f32 v134, v135, v133, v93
	v_med3_f32 v132, v133, v131, v93
	v_med3_f32 v130, v131, v129, v93
	v_med3_f32 v64, v129, v64, v93
	v_med3_f32 v151, v152, v150, v94
	v_med3_f32 v149, v150, v148, v94
	v_med3_f32 v147, v148, v146, v94
	v_med3_f32 v145, v146, v144, v94
	v_med3_f32 v143, v144, v142, v94
	v_med3_f32 v141, v142, v140, v94
	v_med3_f32 v139, v140, v138, v94
	v_med3_f32 v137, v138, v136, v94
	v_med3_f32 v135, v136, v134, v94
	v_med3_f32 v133, v134, v132, v94
	v_med3_f32 v131, v132, v130, v94
	v_med3_f32 v64, v130, v64, v94
	v_med3_f32 v154, v156, v153, v93
	v_med3_f32 v150, v151, v149, v95
	v_med3_f32 v148, v149, v147, v95
	v_med3_f32 v146, v147, v145, v95
	v_med3_f32 v144, v145, v143, v95
	v_med3_f32 v142, v143, v141, v95
	v_med3_f32 v140, v141, v139, v95
	v_med3_f32 v138, v139, v137, v95
	v_med3_f32 v136, v137, v135, v95
	v_med3_f32 v134, v135, v133, v95
	v_med3_f32 v132, v133, v131, v95
	v_med3_f32 v64, v131, v64, v95
	v_med3_f32 v155, v157, v154, v94
	v_med3_f32 v153, v154, v152, v94
	v_med3_f32 v149, v150, v148, v96
	v_med3_f32 v147, v148, v146, v96
	v_med3_f32 v145, v146, v144, v96
	v_med3_f32 v143, v144, v142, v96
	v_med3_f32 v141, v142, v140, v96
	v_med3_f32 v139, v140, v138, v96
	v_med3_f32 v137, v138, v136, v96
	v_med3_f32 v135, v136, v134, v96
	v_med3_f32 v133, v134, v132, v96
	v_med3_f32 v64, v132, v64, v96
	v_med3_f32 v156, v158, v155, v95
	v_med3_f32 v154, v155, v153, v95
	v_med3_f32 v152, v153, v151, v95
	v_med3_f32 v148, v149, v147, v97
	v_med3_f32 v146, v147, v145, v97
	v_med3_f32 v144, v145, v143, v97
	v_med3_f32 v142, v143, v141, v97
	v_med3_f32 v140, v141, v139, v97
	v_med3_f32 v138, v139, v137, v97
	v_med3_f32 v136, v137, v135, v97
	v_med3_f32 v134, v135, v133, v97
	v_med3_f32 v64, v133, v64, v97
	v_med3_f32 v157, v159, v156, v96
	v_med3_f32 v155, v156, v154, v96
	v_med3_f32 v153, v154, v152, v96
	v_med3_f32 v151, v152, v150, v96
	v_med3_f32 v147, v148, v146, v98
	v_med3_f32 v145, v146, v144, v98
	v_med3_f32 v143, v144, v142, v98
	v_med3_f32 v141, v142, v140, v98
	v_med3_f32 v139, v140, v138, v98
	v_med3_f32 v137, v138, v136, v98
	v_med3_f32 v135, v136, v134, v98
	v_med3_f32 v64, v134, v64, v98
	v_med3_f32 v158, v160, v157, v97
	v_med3_f32 v156, v157, v155, v97
	v_med3_f32 v154, v155, v153, v97
	v_med3_f32 v152, v153, v151, v97
	v_med3_f32 v150, v151, v149, v97
	v_med3_f32 v146, v147, v145, v100
	v_med3_f32 v144, v145, v143, v100
	v_med3_f32 v142, v143, v141, v100
	v_med3_f32 v140, v141, v139, v100
	v_med3_f32 v138, v139, v137, v100
	v_med3_f32 v136, v137, v135, v100
	v_med3_f32 v64, v135, v64, v100
	v_med3_f32 v159, v161, v158, v98
	v_med3_f32 v157, v158, v156, v98
	v_med3_f32 v155, v156, v154, v98
	v_med3_f32 v153, v154, v152, v98
	v_med3_f32 v151, v152, v150, v98
	v_med3_f32 v149, v150, v148, v98
	v_med3_f32 v145, v146, v144, v101
	v_med3_f32 v143, v144, v142, v101
	v_med3_f32 v141, v142, v140, v101
	v_med3_f32 v139, v140, v138, v101
	v_med3_f32 v137, v138, v136, v101
	v_med3_f32 v64, v136, v64, v101
	v_med3_f32 v160, v162, v159, v100
	v_med3_f32 v158, v159, v157, v100
	v_med3_f32 v156, v157, v155, v100
	v_med3_f32 v154, v155, v153, v100
	v_med3_f32 v152, v153, v151, v100
	v_med3_f32 v150, v151, v149, v100
	v_med3_f32 v148, v149, v147, v100
	v_med3_f32 v144, v145, v143, v103
	v_med3_f32 v142, v143, v141, v103
	v_med3_f32 v140, v141, v139, v103
	v_med3_f32 v138, v139, v137, v103
	v_med3_f32 v64, v137, v64, v103
	v_med3_f32 v161, v163, v160, v101
	v_med3_f32 v159, v160, v158, v101
	v_med3_f32 v157, v158, v156, v101
	v_med3_f32 v155, v156, v154, v101
	v_med3_f32 v153, v154, v152, v101
	v_med3_f32 v151, v152, v150, v101
	v_med3_f32 v149, v150, v148, v101
	v_med3_f32 v147, v148, v146, v101
	v_med3_f32 v143, v144, v142, v104
	v_med3_f32 v141, v142, v140, v104
	v_med3_f32 v139, v140, v138, v104
	v_med3_f32 v64, v138, v64, v104
	v_med3_f32 v162, v164, v161, v103
	v_med3_f32 v160, v161, v159, v103
	v_med3_f32 v158, v159, v157, v103
	v_med3_f32 v156, v157, v155, v103
	v_med3_f32 v154, v155, v153, v103
	v_med3_f32 v152, v153, v151, v103
	v_med3_f32 v150, v151, v149, v103
	v_med3_f32 v148, v149, v147, v103
	v_med3_f32 v146, v147, v145, v103
	v_med3_f32 v142, v143, v141, v105
	v_med3_f32 v140, v141, v139, v105
; __device__ __forceinline__ void peer_phase(const Params& p, int layer, char* lds, bool last) {
;     ...
;           if ((i + 1) * (j + 1) <= 16) { float v = __uint_as_float((__float_as_uint(a[i] + b[j]) & ~255u) | (unsigned)(i * 16 + j)); CE16(top, v); }
;       const float rsv = rsl[tok];
;       const float m = rsv * __uint_as_float(__float_as_uint(top[0]) & ~255u);
;       float ex[16], sum = 0.f; int ek[16];
; #pragma unroll
;       for (int k = 0; k < 16; ++k) { const unsigned bits = __float_as_uint(top[k]); const float fv = rsv * __uint_as_float(bits & ~255u);
;         ex[k] = __expf(fv - m); sum += ex[k];
;         const int i = (bits >> 4) & 15, j = bits & 15;
;         ek[k] = (int)((l0[i * 512] & 127u) * 128u + (l1[j * 512] & 127u)); }
	v_med3_f32 v64, v139, v64, v105
	v_med3_f32 v163, v165, v162, v104
	v_med3_f32 v161, v162, v160, v104
	v_med3_f32 v159, v160, v158, v104
	v_med3_f32 v157, v158, v156, v104
	v_med3_f32 v155, v156, v154, v104
	v_med3_f32 v153, v154, v152, v104
	v_med3_f32 v151, v152, v150, v104
	v_med3_f32 v149, v150, v148, v104
	v_med3_f32 v147, v148, v146, v104
	v_med3_f32 v145, v146, v144, v104
	v_med3_f32 v141, v142, v140, v106
	v_med3_f32 v64, v140, v64, v106
	v_med3_f32 v164, v166, v163, v105
	v_med3_f32 v162, v163, v161, v105
	v_med3_f32 v160, v161, v159, v105
	v_med3_f32 v158, v159, v157, v105
	v_med3_f32 v156, v157, v155, v105
	v_med3_f32 v154, v155, v153, v105
	v_med3_f32 v152, v153, v151, v105
	v_med3_f32 v150, v151, v149, v105
	v_med3_f32 v148, v149, v147, v105
	v_med3_f32 v146, v147, v145, v105
	v_med3_f32 v144, v145, v143, v105
	v_med3_f32 v66, v141, v64, v107
	v_pk_add_f32 v[64:65], v[68:69], v[68:69] op_sel:[1,0] op_sel_hi:[0,1]
	v_med3_f32 v165, v167, v164, v106
	v_med3_f32 v163, v164, v162, v106
	v_med3_f32 v161, v162, v160, v106
	v_med3_f32 v159, v160, v158, v106
	v_med3_f32 v157, v158, v156, v106
	v_med3_f32 v155, v156, v154, v106
	v_med3_f32 v153, v154, v152, v106
	v_med3_f32 v151, v152, v150, v106
	v_med3_f32 v149, v150, v148, v106
	v_med3_f32 v147, v148, v146, v106
	v_med3_f32 v145, v146, v144, v106
	v_med3_f32 v143, v144, v142, v106
	v_and_b32_e32 v64, 0xffffff00, v64
	v_med3_f32 v112, v112, v165, v107
	v_med3_f32 v164, v165, v163, v107
	v_med3_f32 v162, v163, v161, v107
	v_med3_f32 v160, v161, v159, v107
	v_med3_f32 v158, v159, v157, v107
	v_med3_f32 v156, v157, v155, v107
	v_med3_f32 v154, v155, v153, v107
	v_med3_f32 v152, v153, v151, v107
	v_med3_f32 v150, v151, v149, v107
	v_med3_f32 v148, v149, v147, v107
	v_med3_f32 v146, v147, v145, v107
	v_med3_f32 v144, v145, v143, v107
	v_med3_f32 v142, v143, v141, v107
	v_or_b32_e32 v64, 0xf0, v64
	v_med3_f32 v68, v142, v66, v64
	v_med3_f32 v65, v144, v142, v64
	v_med3_f32 v67, v146, v144, v64
	v_med3_f32 v69, v148, v146, v64
	v_med3_f32 v70, v150, v148, v64
	v_med3_f32 v71, v152, v150, v64
	v_med3_f32 v72, v154, v152, v64
	v_med3_f32 v73, v156, v154, v64
	v_med3_f32 v74, v158, v156, v64
	v_med3_f32 v75, v160, v158, v64
	v_med3_f32 v76, v162, v160, v64
	v_med3_f32 v77, v164, v162, v64
	v_med3_f32 v78, v112, v164, v64
	v_med3_f32 v79, v109, v112, v64
	v_med3_f32 v80, v102, v109, v64
	v_max_f32_e32 v64, v64, v64
	v_max_f32_e32 v81, v102, v64
	v_lshl_add_u32 v64, v82, 2, v221
	ds_read_b32 v66, v64
	v_lshlrev_b32_e32 v64, 7, v80
	v_and_b32_e32 v64, 0x7800, v64
	v_add_u32_e32 v64, v84, v64
	v_and_b32_e32 v113, 0xffffff00, v80
	ds_read_b32 v111, v64
	v_lshlrev_b32_e32 v64, 11, v80
	v_lshlrev_b32_e32 v80, 5, v79
	v_and_b32_e32 v64, 0x7800, v64
	v_and_b32_e32 v80, 0x1e00, v80
	v_add_u32_e32 v64, v84, v64
	v_lshl_add_u32 v80, v80, 2, v84
	ds_read_b32 v112, v64 offset:4
	ds_read_b32 v107, v80
	v_and_b32_e32 v116, 0xffffff00, v79
	v_lshlrev_b32_e32 v64, 5, v78
	v_lshlrev_b32_e32 v79, 11, v79
	v_and_b32_e32 v64, 0x1e00, v64
	v_and_b32_e32 v79, 0x7800, v79
	v_add_u32_e32 v79, v84, v79
	v_lshl_add_u32 v64, v64, 2, v84
	ds_read_b32 v108, v79 offset:4
	ds_read_b32 v109, v64
	v_and_b32_e32 v79, 0xffffff00, v78
	v_lshlrev_b32_e32 v64, 11, v78
	v_lshlrev_b32_e32 v78, 5, v77
	v_and_b32_e32 v64, 0x7800, v64
	v_and_b32_e32 v78, 0x1e00, v78
	v_add_u32_e32 v64, v84, v64
	v_lshl_add_u32 v78, v78, 2, v84
	ds_read_b32 v110, v64 offset:4
	ds_read_b32 v101, v78
	v_and_b32_e32 v117, 0xffffff00, v77
	v_lshlrev_b32_e32 v64, 5, v76
	v_lshlrev_b32_e32 v77, 11, v77
	v_and_b32_e32 v64, 0x1e00, v64
	v_and_b32_e32 v77, 0x7800, v77
	v_add_u32_e32 v77, v84, v77
	v_lshl_add_u32 v64, v64, 2, v84
	ds_read_b32 v102, v77 offset:4
	ds_read_b32 v105, v64
	v_and_b32_e32 v77, 0xffffff00, v76
	v_lshlrev_b32_e32 v64, 11, v76
	v_lshlrev_b32_e32 v76, 5, v75
	v_and_b32_e32 v64, 0x7800, v64
	v_and_b32_e32 v76, 0x1e00, v76
	v_add_u32_e32 v64, v84, v64
	v_lshl_add_u32 v76, v76, 2, v84
	ds_read_b32 v106, v64 offset:4
	ds_read_b32 v99, v76
	v_and_b32_e32 v118, 0xffffff00, v75
	v_lshlrev_b32_e32 v64, 5, v74
	v_lshlrev_b32_e32 v75, 11, v75
	v_and_b32_e32 v64, 0x1e00, v64
	v_and_b32_e32 v75, 0x7800, v75
	v_add_u32_e32 v75, v84, v75
	v_lshl_add_u32 v64, v64, 2, v84
	ds_read_b32 v100, v75 offset:4
	ds_read_b32 v103, v64
	v_and_b32_e32 v75, 0xffffff00, v74
	v_lshlrev_b32_e32 v64, 11, v74
	v_lshlrev_b32_e32 v74, 5, v73
	v_and_b32_e32 v64, 0x7800, v64
	v_and_b32_e32 v74, 0x1e00, v74
	v_add_u32_e32 v64, v84, v64
	v_lshl_add_u32 v74, v74, 2, v84
	ds_read_b32 v104, v64 offset:4
	ds_read_b32 v93, v74
	v_and_b32_e32 v119, 0xffffff00, v73
	v_lshlrev_b32_e32 v64, 5, v72
	v_lshlrev_b32_e32 v73, 11, v73
	v_and_b32_e32 v64, 0x1e00, v64
	v_and_b32_e32 v73, 0x7800, v73
	v_add_u32_e32 v73, v84, v73
	v_lshl_add_u32 v64, v64, 2, v84
	ds_read_b32 v94, v73 offset:4
	ds_read_b32 v97, v64
	v_and_b32_e32 v73, 0xffffff00, v72
	v_lshlrev_b32_e32 v64, 11, v72
	v_lshlrev_b32_e32 v72, 5, v71
	v_and_b32_e32 v64, 0x7800, v64
	v_and_b32_e32 v72, 0x1e00, v72
	v_add_u32_e32 v64, v84, v64
	v_lshl_add_u32 v72, v72, 2, v84
	ds_read_b32 v98, v64 offset:4
	ds_read_b32 v91, v72
	v_and_b32_e32 v120, 0xffffff00, v71
	v_lshlrev_b32_e32 v64, 5, v70
	v_lshlrev_b32_e32 v71, 11, v71
	v_and_b32_e32 v64, 0x1e00, v64
	v_and_b32_e32 v71, 0x7800, v71
	v_add_u32_e32 v71, v84, v71
	v_lshl_add_u32 v64, v64, 2, v84
	ds_read_b32 v92, v71 offset:4
	ds_read_b32 v95, v64
	v_lshlrev_b32_e32 v64, 11, v70
	v_and_b32_e32 v64, 0x7800, v64
	v_add_u32_e32 v64, v84, v64
	v_and_b32_e32 v71, 0xffffff00, v70
	ds_read_b32 v96, v64 offset:4
	v_and_b32_e32 v121, 0xffffff00, v69
	v_lshlrev_b32_e32 v64, 5, v67
	v_lshlrev_b32_e32 v70, 5, v69
	v_lshlrev_b32_e32 v69, 11, v69
	v_and_b32_e32 v64, 0x1e00, v64
	v_and_b32_e32 v69, 0x7800, v69
	v_add_u32_e32 v69, v84, v69
	v_lshl_add_u32 v64, v64, 2, v84
	ds_read_b32 v88, v69 offset:4
	ds_read_b32 v89, v64
	v_lshlrev_b32_e32 v64, 11, v67
	v_and_b32_e32 v64, 0x7800, v64
	v_add_u32_e32 v64, v84, v64
	ds_read_b32 v90, v64 offset:4
	v_lshlrev_b32_e32 v64, 7, v65
	v_and_b32_e32 v70, 0x1e00, v70
	v_and_b32_e32 v64, 0x7800, v64
	v_lshl_add_u32 v70, v70, 2, v84
	v_add_u32_e32 v64, v84, v64
	ds_read_b32 v87, v70
	ds_read_b32 v85, v64
	v_lshlrev_b32_e32 v64, 11, v65
	v_and_b32_e32 v64, 0x7800, v64
	v_add_u32_e32 v64, v84, v64
	v_and_b32_e32 v69, 0xffffff00, v67
	v_and_b32_e32 v67, 0xffffff00, v65
	ds_read_b32 v86, v64 offset:4
	v_and_b32_e32 v65, 0xffffff00, v81
	v_and_b32_e32 v64, 0xffffff00, v68
	s_waitcnt lgkmcnt(14)
; __device__ __forceinline__ void peer_phase(const Params& p, int layer, char* lds, bool last) {
;     ...
;       const float rsv = rsl[tok];
;       const float m = rsv * __uint_as_float(__float_as_uint(top[0]) & ~255u);
;       float ex[16], sum = 0.f; int ek[16];
; #pragma unroll
;       for (int k = 0; k < 16; ++k) { const unsigned bits = __float_as_uint(top[k]); const float fv = rsv * __uint_as_float(bits & ~255u);
;         ex[k] = __expf(fv - m); sum += ex[k];
;         const int i = (bits >> 4) & 15, j = bits & 15;
;         ek[k] = (int)((l0[i * 512] & 127u) * 128u + (l1[j * 512] & 127u)); }
;       const float inv = 1.f / sum;
; #pragma unroll
;       for (int k = 0; k < 16; ++k) { sele[tok * 128 + h * 16 + k] = ek[k]; seld[tok * 128 + h * 16 + k] = scd[ek[k]]; selg[tok * 128 + h * 16 + k] = ex[k] * inv * scu[ek[k]]; }
	v_pk_mul_f32 v[114:115], v[66:67], v[64:65] op_sel_hi:[0,1]
	v_lshlrev_b32_e32 v65, 7, v81
	v_and_b32_e32 v65, 0x7800, v65
	v_add_u32_e32 v65, v84, v65
	ds_read_b32 v122, v65
	v_lshlrev_b32_e32 v65, 11, v81
	v_and_b32_e32 v65, 0x7800, v65
	v_add_u32_e32 v65, v84, v65
	ds_read_b32 v123, v65 offset:4
	v_fma_f32 v65, v66, v113, -v115
	v_mul_f32_e32 v65, 0x3fb8aa3b, v65
	v_exp_f32_e32 v81, v65
	v_fma_f32 v65, v66, v116, -v115
	v_mul_f32_e32 v65, 0x3fb8aa3b, v65
	v_exp_f32_e32 v78, v65
	v_fma_f32 v65, v66, v79, -v115
	v_mul_f32_e32 v65, 0x3fb8aa3b, v65
	v_exp_f32_e32 v79, v65
	v_fma_f32 v65, v66, v117, -v115
	v_mul_f32_e32 v65, 0x3fb8aa3b, v65
	v_exp_f32_e32 v76, v65
	v_fma_f32 v65, v66, v77, -v115
	v_sub_f32_e32 v64, v115, v115
	v_mul_f32_e32 v65, 0x3fb8aa3b, v65
	v_mul_f32_e32 v64, 0x3fb8aa3b, v64
	v_exp_f32_e32 v77, v65
	v_fma_f32 v65, v66, v118, -v115
	v_exp_f32_e32 v80, v64
	v_mul_f32_e32 v65, 0x3fb8aa3b, v65
	v_exp_f32_e32 v74, v65
	v_fma_f32 v65, v66, v75, -v115
	v_mul_f32_e32 v65, 0x3fb8aa3b, v65
	v_exp_f32_e32 v75, v65
	v_fma_f32 v65, v66, v119, -v115
	v_add_f32_e32 v64, 0, v80
	v_mul_f32_e32 v65, 0x3fb8aa3b, v65
	v_add_f32_e32 v64, v81, v64
	v_exp_f32_e32 v72, v65
	v_fma_f32 v65, v66, v73, -v115
	v_add_f32_e32 v64, v78, v64
	v_mul_f32_e32 v65, 0x3fb8aa3b, v65
	v_add_f32_e32 v64, v79, v64
	v_exp_f32_e32 v73, v65
	v_fma_f32 v65, v66, v120, -v115
	v_add_f32_e32 v64, v76, v64
	v_mul_f32_e32 v65, 0x3fb8aa3b, v65
	v_add_f32_e32 v64, v77, v64
	v_exp_f32_e32 v70, v65
	v_fma_f32 v65, v66, v71, -v115
	v_add_f32_e32 v64, v74, v64
	v_mul_f32_e32 v65, 0x3fb8aa3b, v65
	v_add_f32_e32 v64, v75, v64
	v_exp_f32_e32 v71, v65
	v_add_f32_e32 v64, v72, v64
	v_add_f32_e32 v64, v73, v64
	v_add_f32_e32 v64, v70, v64
	v_add_f32_e32 v65, v71, v64
	v_fma_f32 v64, v66, v121, -v115
	v_mul_f32_e32 v64, 0x3fb8aa3b, v64
	v_exp_f32_e32 v64, v64
	v_and_b32_e32 v108, 0x7f, v108
	v_add_f32_e32 v113, v64, v65
	v_fma_f32 v65, v66, v69, -v115
	v_mul_f32_e32 v65, 0x3fb8aa3b, v65
	v_fma_f32 v66, v66, v67, -v115
	v_exp_f32_e32 v65, v65
	v_mul_f32_e32 v66, 0x3fb8aa3b, v66
	v_sub_f32_e32 v67, v114, v115
	v_exp_f32_e32 v66, v66
	v_mul_f32_e32 v67, 0x3fb8aa3b, v67
	v_exp_f32_e32 v67, v67
	v_add_f32_e32 v69, v65, v113
	v_lshlrev_b32_e32 v113, 7, v68
	v_lshlrev_b32_e32 v68, 11, v68
	v_add_f32_e32 v69, v66, v69
	v_and_b32_e32 v113, 0x7800, v113
	v_and_b32_e32 v68, 0x7800, v68
	v_add_f32_e32 v69, v67, v69
	v_add_u32_e32 v113, v84, v113
	v_add_u32_e32 v68, v84, v68
	ds_read_b32 v120, v113
	ds_read_b32 v84, v68 offset:4
	v_div_scale_f32 v68, s[24:25], v69, v69, 1.0
	v_rcp_f32_e32 v113, v68
	s_nop 0
	v_fma_f32 v114, -v68, v113, 1.0
	v_fmac_f32_e32 v113, v114, v113
	v_div_scale_f32 v114, vcc, 1.0, v69, 1.0
	v_mul_f32_e32 v115, v114, v113
	v_fma_f32 v116, -v68, v115, v114
	v_fmac_f32_e32 v115, v116, v113
	v_fma_f32 v68, -v68, v115, v114
	v_div_fmas_f32 v68, v68, v113, v115
	v_div_fixup_f32 v68, v68, v69, 1.0
	v_lshlrev_b32_e32 v69, 6, v83
	v_lshl_or_b32 v69, v82, 9, v69
	v_lshlrev_b32_e32 v82, 7, v111
	s_waitcnt lgkmcnt(3)
	v_lshlrev_b32_e32 v83, 7, v122
	v_and_b32_e32 v82, 0x3f80, v82
	v_and_b32_e32 v83, 0x3f80, v83
	v_and_b32_e32 v111, 0x7f, v112
	s_waitcnt lgkmcnt(2)
	v_and_b32_e32 v112, 0x7f, v123
	v_or_b32_e32 v113, v82, v111
	v_or_b32_e32 v112, v83, v112
	v_lshlrev_b32_e32 v82, 2, v112
	v_lshlrev_b32_e32 v83, 2, v113
	global_load_dword v116, v82, s[36:37]
	s_nop 0
	global_load_dword v82, v82, s[38:39]
	s_nop 0
	global_load_dword v117, v83, s[36:37]
	s_nop 0
	global_load_dword v83, v83, s[38:39]
	v_pk_mul_f32 v[80:81], v[80:81], v[68:69] op_sel_hi:[1,0]
	v_pk_mul_f32 v[78:79], v[78:79], v[68:69] op_sel_hi:[1,0]
	v_add_u32_e32 v121, 0x10200, v69
	v_pk_mul_f32 v[76:77], v[76:77], v[68:69] op_sel_hi:[1,0]
	v_pk_mul_f32 v[74:75], v[74:75], v[68:69] op_sel_hi:[1,0]
	v_pk_mul_f32 v[72:73], v[72:73], v[68:69] op_sel_hi:[1,0]
	v_pk_mul_f32 v[70:71], v[70:71], v[68:69] op_sel_hi:[1,0]
	v_pk_mul_f32 v[64:65], v[64:65], v[68:69] op_sel_hi:[1,0]
	v_pk_mul_f32 v[66:67], v[66:67], v[68:69] op_sel_hi:[1,0]
	s_waitcnt vmcnt(0)
; __device__ __forceinline__ void peer_phase(const Params& p, int layer, char* lds, bool last) {
;     ...
;       for (int k = 0; k < 16; ++k) { sele[tok * 128 + h * 16 + k] = ek[k]; seld[tok * 128 + h * 16 + k] = scd[ek[k]]; selg[tok * 128 + h * 16 + k] = ex[k] * inv * scu[ek[k]]; }
	v_pk_mul_f32 v[80:81], v[80:81], v[82:83]
	v_lshlrev_b32_e32 v82, 7, v109
	v_lshlrev_b32_e32 v83, 7, v107
	v_and_b32_e32 v82, 0x3f80, v82
	v_and_b32_e32 v83, 0x3f80, v83
	v_and_b32_e32 v107, 0x7f, v110
	v_or_b32_e32 v115, v82, v107
	v_or_b32_e32 v114, v83, v108
	v_lshlrev_b32_e32 v82, 2, v114
	v_lshlrev_b32_e32 v83, 2, v115
	global_load_dword v118, v82, s[36:37]
	s_nop 0
	global_load_dword v82, v82, s[38:39]
	ds_write_b128 v69, v[112:115] offset:49152
	global_load_dword v119, v83, s[36:37]
	s_waitcnt vmcnt(0)
	ds_write_b128 v121, v[116:119]
	global_load_dword v83, v83, s[38:39]
	s_waitcnt vmcnt(0)
	v_pk_mul_f32 v[82:83], v[78:79], v[82:83]
	v_lshlrev_b32_e32 v78, 7, v105
	v_lshlrev_b32_e32 v79, 7, v101
	ds_write_b128 v69, v[80:83] offset:32768
	v_and_b32_e32 v78, 0x3f80, v78
	v_and_b32_e32 v80, 0x3f80, v79
	v_and_b32_e32 v79, 0x7f, v106
	v_and_b32_e32 v81, 0x7f, v102
	v_or_b32_e32 v79, v78, v79
	v_or_b32_e32 v78, v80, v81
	v_lshlrev_b32_e32 v80, 2, v78
	v_lshlrev_b32_e32 v81, 2, v79
	global_load_dword v106, v80, s[36:37]
	s_nop 0
	global_load_dword v80, v80, s[38:39]
	s_nop 0
	global_load_dword v107, v81, s[36:37]
	s_nop 0
	global_load_dword v81, v81, s[38:39]
	v_and_b32_e32 v83, 0x7f, v100
	s_waitcnt vmcnt(0)
	v_pk_mul_f32 v[76:77], v[76:77], v[80:81]
	v_lshlrev_b32_e32 v80, 7, v103
	v_lshlrev_b32_e32 v81, 7, v99
	v_and_b32_e32 v80, 0x3f80, v80
	v_and_b32_e32 v82, 0x3f80, v81
	v_and_b32_e32 v81, 0x7f, v104
	v_or_b32_e32 v81, v80, v81
	v_or_b32_e32 v80, v82, v83
	v_lshlrev_b32_e32 v82, 2, v80
	global_load_dword v108, v82, s[36:37]
	s_nop 0
	global_load_dword v82, v82, s[38:39]
	ds_write_b128 v69, v[78:81] offset:49168
	v_lshlrev_b32_e32 v78, 2, v81
	global_load_dword v109, v78, s[36:37]
	global_load_dword v83, v78, s[38:39]
	v_and_b32_e32 v81, 0x7f, v92
	s_waitcnt vmcnt(1)
	ds_write_b128 v121, v[106:109] offset:16
	s_waitcnt vmcnt(0)
	v_pk_mul_f32 v[78:79], v[74:75], v[82:83]
	v_lshlrev_b32_e32 v74, 7, v97
	v_lshlrev_b32_e32 v75, 7, v93
	ds_write_b128 v69, v[76:79] offset:32784
	v_and_b32_e32 v74, 0x3f80, v74
	v_and_b32_e32 v76, 0x3f80, v75
	v_and_b32_e32 v75, 0x7f, v98
	v_and_b32_e32 v77, 0x7f, v94
	v_or_b32_e32 v75, v74, v75
	v_or_b32_e32 v74, v76, v77
	v_lshlrev_b32_e32 v76, 2, v74
	v_lshlrev_b32_e32 v77, 2, v75
	global_load_dword v78, v76, s[36:37]
	s_nop 0
	global_load_dword v76, v76, s[38:39]
	s_nop 0
	global_load_dword v79, v77, s[36:37]
	s_nop 0
	global_load_dword v77, v77, s[38:39]
	s_waitcnt vmcnt(0)
	v_pk_mul_f32 v[72:73], v[72:73], v[76:77]
	v_lshlrev_b32_e32 v76, 7, v95
	v_lshlrev_b32_e32 v77, 7, v91
	v_and_b32_e32 v76, 0x3f80, v76
	v_and_b32_e32 v80, 0x3f80, v77
	v_and_b32_e32 v77, 0x7f, v96
	v_or_b32_e32 v77, v76, v77
	v_or_b32_e32 v76, v80, v81
	v_lshlrev_b32_e32 v81, 2, v76
	global_load_dword v80, v81, s[36:37]
	global_load_dword v82, v81, s[38:39]
	ds_write_b128 v69, v[74:77] offset:49184
	v_lshlrev_b32_e32 v74, 2, v77
	global_load_dword v81, v74, s[36:37]
	global_load_dword v83, v74, s[38:39]
	s_waitcnt vmcnt(1)
	ds_write_b128 v121, v[78:81] offset:32
	s_waitcnt vmcnt(0)
	v_pk_mul_f32 v[74:75], v[70:71], v[82:83]
	v_lshlrev_b32_e32 v70, 7, v89
	v_lshlrev_b32_e32 v71, 7, v87
	ds_write_b128 v69, v[72:75] offset:32800
	v_and_b32_e32 v70, 0x3f80, v70
	v_and_b32_e32 v71, 0x3f80, v71
	v_and_b32_e32 v72, 0x7f, v90
	v_and_b32_e32 v74, 0x7f, v88
	v_or_b32_e32 v73, v70, v72
	v_or_b32_e32 v72, v71, v74
	v_lshlrev_b32_e32 v70, 2, v72
	v_lshlrev_b32_e32 v71, 2, v73
	global_load_dword v76, v70, s[36:37]
	s_nop 0
	global_load_dword v70, v70, s[38:39]
	s_nop 0
	global_load_dword v77, v71, s[36:37]
	s_nop 0
	global_load_dword v71, v71, s[38:39]
	s_waitcnt lgkmcnt(9)
	v_and_b32_e32 v74, 0x7f, v84
	v_and_b32_e32 v78, 0x7f, v86
	s_waitcnt vmcnt(0)
	v_pk_mul_f32 v[64:65], v[64:65], v[70:71]
	v_lshlrev_b32_e32 v70, 7, v120
	v_lshlrev_b32_e32 v71, 7, v85
	v_and_b32_e32 v70, 0x3f80, v70
	v_and_b32_e32 v71, 0x3f80, v71
	v_or_b32_e32 v75, v70, v74
	v_or_b32_e32 v74, v71, v78
	v_lshlrev_b32_e32 v70, 2, v74
	v_lshlrev_b32_e32 v71, 2, v75
	global_load_dword v78, v70, s[36:37]
	s_nop 0
	global_load_dword v70, v70, s[38:39]
	ds_write_b128 v69, v[72:75] offset:49200
	global_load_dword v79, v71, s[36:37]
	s_waitcnt vmcnt(0)
	ds_write_b128 v121, v[76:79] offset:48
	global_load_dword v71, v71, s[38:39]
	s_waitcnt vmcnt(0)
	v_pk_mul_f32 v[66:67], v[66:67], v[70:71]
	ds_write_b128 v69, v[64:67] offset:32816
